# attention P.V: ds_read_u16 operand gathers issued one MFMA ahead with a single lgkmcnt wait per MFMA (was 4 serialized LDS round trips per MFMA); on top of general prep-GDN fast path
# speedup vs baseline: 1.0931x; 1.0180x over previous
.LBB0_98:
	s_or_b64 exec, exec, s[24:25]
	s_waitcnt vmcnt(0)
	v_bfe_u32 v34, v30, 16, 1
	v_add3_u32 v30, v30, v34, s60
	v_bfe_u32 v34, v31, 16, 1
	v_lshrrev_b32_e32 v30, 16, v30
	v_add3_u32 v31, v31, v34, s60
	v_and_or_b32 v34, v31, s33, v30
	v_bfe_u32 v30, v32, 16, 1
	v_add3_u32 v30, v32, v30, s60
	v_bfe_u32 v31, v33, 16, 1
	v_lshrrev_b32_e32 v30, 16, v30
	v_add3_u32 v31, v33, v31, s60
	v_and_or_b32 v35, v31, s33, v30
	v_bfe_u32 v30, v26, 16, 1
	v_add3_u32 v26, v26, v30, s60
	v_bfe_u32 v30, v27, 16, 1
	v_lshrrev_b32_e32 v26, 16, v26
	v_add3_u32 v27, v27, v30, s60
	v_and_or_b32 v36, v27, s33, v26
	v_bfe_u32 v26, v28, 16, 1
	v_add3_u32 v26, v28, v26, s60
	v_bfe_u32 v27, v29, 16, 1
	v_lshrrev_b32_e32 v26, 16, v26
	v_add3_u32 v27, v29, v27, s60
	v_and_or_b32 v37, v27, s33, v26
	v_bfe_u32 v26, v18, 16, 1
	v_add3_u32 v18, v18, v26, s60
	v_bfe_u32 v26, v19, 16, 1
	v_lshrrev_b32_e32 v18, 16, v18
	v_add3_u32 v19, v19, v26, s60
	v_and_or_b32 v66, v19, s33, v18
	v_bfe_u32 v18, v20, 16, 1
	v_add3_u32 v18, v20, v18, s60
	v_bfe_u32 v19, v21, 16, 1
	v_lshrrev_b32_e32 v18, 16, v18
	v_add3_u32 v19, v21, v19, s60
	v_and_or_b32 v67, v19, s33, v18
	v_bfe_u32 v18, v10, 16, 1
	v_add3_u32 v10, v10, v18, s60
	v_bfe_u32 v18, v11, 16, 1
	v_lshrrev_b32_e32 v10, 16, v10
	v_add3_u32 v11, v11, v18, s60
	v_and_or_b32 v68, v11, s33, v10
	v_bfe_u32 v10, v12, 16, 1
	v_add3_u32 v10, v12, v10, s60
	v_bfe_u32 v11, v13, 16, 1
	v_lshrrev_b32_e32 v10, 16, v10
	v_add3_u32 v11, v13, v11, s60
	v_and_or_b32 v69, v11, s33, v10
	v_bfe_u32 v10, v6, 16, 1
	v_add3_u32 v6, v6, v10, s60
	v_bfe_u32 v10, v7, 16, 1
	v_lshrrev_b32_e32 v6, 16, v6
	v_add3_u32 v7, v7, v10, s60
	v_and_or_b32 v70, v7, s33, v6
	v_bfe_u32 v6, v8, 16, 1
	v_add3_u32 v6, v8, v6, s60
	v_bfe_u32 v7, v9, 16, 1
	v_lshrrev_b32_e32 v6, 16, v6
	v_add3_u32 v7, v9, v7, s60
	v_and_or_b32 v71, v7, s33, v6
	v_bfe_u32 v6, v2, 16, 1
	v_add3_u32 v2, v2, v6, s60
	v_bfe_u32 v6, v3, 16, 1
	v_lshrrev_b32_e32 v2, 16, v2
	v_add3_u32 v3, v3, v6, s60
	v_and_or_b32 v72, v3, s33, v2
	v_bfe_u32 v2, v4, 16, 1
	v_add3_u32 v2, v4, v2, s60
	v_bfe_u32 v3, v5, 16, 1
	v_lshrrev_b32_e32 v2, 16, v2
	v_add3_u32 v3, v5, v3, s60
	v_and_or_b32 v73, v3, s33, v2
	v_bfe_u32 v2, v22, 16, 1
	v_add3_u32 v2, v22, v2, s60
	v_bfe_u32 v3, v23, 16, 1
	v_lshrrev_b32_e32 v2, 16, v2
	v_add3_u32 v3, v23, v3, s60
	v_and_or_b32 v74, v3, s33, v2
	v_bfe_u32 v2, v24, 16, 1
	v_add3_u32 v2, v24, v2, s60
	v_bfe_u32 v3, v25, 16, 1
	v_lshrrev_b32_e32 v2, 16, v2
	v_add3_u32 v3, v25, v3, s60
	v_and_or_b32 v75, v3, s33, v2
	v_bfe_u32 v2, v14, 16, 1
	v_add3_u32 v2, v14, v2, s60
	v_bfe_u32 v3, v15, 16, 1
	v_lshrrev_b32_e32 v2, 16, v2
	v_add3_u32 v3, v15, v3, s60
	v_and_or_b32 v76, v3, s33, v2
	v_bfe_u32 v2, v16, 16, 1
	v_add3_u32 v2, v16, v2, s60
	v_bfe_u32 v3, v17, 16, 1
	v_lshrrev_b32_e32 v2, 16, v2
	v_add3_u32 v3, v17, v3, s60
	v_and_or_b32 v77, v3, s33, v2
	ds_read_b128 v[2:5], v140
	ds_read_b128 v[6:9], v140 offset:64
	s_waitcnt lgkmcnt(1)
	v_mfma_f32_16x16x32_bf16 v[2:5], v[2:5], v[70:73], 0
	ds_read_b128 v[10:13], v140 offset:4416
	v_add_u32_e32 v18, v137, v141
	v_add_u32_e32 v26, v137, v142
	s_waitcnt lgkmcnt(1)
	v_mfma_f32_16x16x32_bf16 v[2:5], v[6:9], v[66:69], v[2:5]
	ds_read_b128 v[6:9], v140 offset:128
	v_add_u32_e32 v38, v137, v143
	v_add_u32_e32 v87, v137, v144
	s_waitcnt lgkmcnt(0)
	v_mfma_f32_16x16x32_bf16 v[2:5], v[6:9], v[34:37], v[2:5]
	ds_read_b128 v[6:9], v140 offset:192
	s_mov_b32 s1, 0xff61b1e6
	s_lshl_b32 s46, s0, 1
	s_waitcnt lgkmcnt(0)
	v_mfma_f32_16x16x32_bf16 v[2:5], v[6:9], v[74:77], v[2:5]
	ds_read_b128 v[6:9], v140 offset:4352
	ds_read_b128 v[14:17], v18 offset:64
	ds_read_b128 v[22:25], v26 offset:64
	s_waitcnt lgkmcnt(2)
	v_mfma_f32_16x16x32_bf16 v[6:9], v[6:9], v[70:73], 0
	ds_read_b128 v[30:33], v38 offset:64
	ds_read_b128 v[174:177], v140 offset:60992
	v_mfma_f32_16x16x32_bf16 v[6:9], v[10:13], v[66:69], v[6:9]
	ds_read_b128 v[10:13], v140 offset:4480
	s_waitcnt lgkmcnt(0)
	v_mfma_f32_16x16x32_bf16 v[6:9], v[10:13], v[34:37], v[6:9]
	ds_read_b128 v[10:13], v140 offset:4544
	s_waitcnt lgkmcnt(0)
	v_mfma_f32_16x16x32_bf16 v[62:65], v[10:13], v[74:77], v[6:9]
	s_nop 4
	ds_read_b128 v[6:9], v140 offset:8704
	ds_read_b128 v[10:13], v140 offset:8768
	s_waitcnt lgkmcnt(1)
	v_mfma_f32_16x16x32_bf16 v[6:9], v[6:9], v[70:73], 0
	s_waitcnt lgkmcnt(0)
	v_mfma_f32_16x16x32_bf16 v[6:9], v[10:13], v[66:69], v[6:9]
	ds_read_b128 v[10:13], v140 offset:8832
	s_waitcnt lgkmcnt(0)
	v_mfma_f32_16x16x32_bf16 v[6:9], v[10:13], v[34:37], v[6:9]
	ds_read_b128 v[10:13], v140 offset:8896
	s_waitcnt lgkmcnt(0)
	v_mfma_f32_16x16x32_bf16 v[6:9], v[10:13], v[74:77], v[6:9]
	ds_read_b128 v[10:13], v18
	s_waitcnt lgkmcnt(0)
	v_mfma_f32_16x16x32_bf16 v[10:13], v[10:13], v[70:73], 0
	v_mfma_f32_16x16x32_bf16 v[10:13], v[14:17], v[66:69], v[10:13]
	ds_read_b128 v[14:17], v18 offset:128
	s_waitcnt lgkmcnt(0)
	v_mfma_f32_16x16x32_bf16 v[10:13], v[14:17], v[34:37], v[10:13]
	ds_read_b128 v[14:17], v18 offset:192
	ds_read_b128 v[18:21], v140 offset:21824
	s_waitcnt lgkmcnt(1)
	v_mfma_f32_16x16x32_bf16 v[58:61], v[14:17], v[74:77], v[10:13]
	s_nop 3
	ds_read_b128 v[10:13], v140 offset:17408
	ds_read_b128 v[14:17], v140 offset:17472
	s_waitcnt lgkmcnt(1)
	v_mfma_f32_16x16x32_bf16 v[10:13], v[10:13], v[70:73], 0
	s_waitcnt lgkmcnt(0)
	v_mfma_f32_16x16x32_bf16 v[10:13], v[14:17], v[66:69], v[10:13]
	ds_read_b128 v[14:17], v140 offset:17536
	s_waitcnt lgkmcnt(0)
	v_mfma_f32_16x16x32_bf16 v[10:13], v[14:17], v[34:37], v[10:13]
	ds_read_b128 v[14:17], v140 offset:17600
	s_waitcnt lgkmcnt(0)
	v_mfma_f32_16x16x32_bf16 v[10:13], v[14:17], v[74:77], v[10:13]
	ds_read_b128 v[14:17], v140 offset:21760
	s_waitcnt lgkmcnt(0)
	v_mfma_f32_16x16x32_bf16 v[14:17], v[14:17], v[70:73], 0
	v_mfma_f32_16x16x32_bf16 v[14:17], v[18:21], v[66:69], v[14:17]
	ds_read_b128 v[18:21], v140 offset:21888
	s_waitcnt lgkmcnt(0)
	v_mfma_f32_16x16x32_bf16 v[14:17], v[18:21], v[34:37], v[14:17]
	ds_read_b128 v[18:21], v140 offset:21952
	s_waitcnt lgkmcnt(0)
	v_mfma_f32_16x16x32_bf16 v[54:57], v[18:21], v[74:77], v[14:17]
	s_nop 4
	ds_read_b128 v[14:17], v140 offset:26112
	ds_read_b128 v[18:21], v140 offset:26176
	s_waitcnt lgkmcnt(1)
	v_mfma_f32_16x16x32_bf16 v[14:17], v[14:17], v[70:73], 0
	s_waitcnt lgkmcnt(0)
	v_mfma_f32_16x16x32_bf16 v[14:17], v[18:21], v[66:69], v[14:17]
	ds_read_b128 v[18:21], v140 offset:26240
	s_waitcnt lgkmcnt(0)
	v_mfma_f32_16x16x32_bf16 v[14:17], v[18:21], v[34:37], v[14:17]
	ds_read_b128 v[18:21], v140 offset:26304
	s_waitcnt lgkmcnt(0)
	v_mfma_f32_16x16x32_bf16 v[14:17], v[18:21], v[74:77], v[14:17]
	ds_read_b128 v[18:21], v26
	s_waitcnt lgkmcnt(0)
	v_mfma_f32_16x16x32_bf16 v[18:21], v[18:21], v[70:73], 0
	v_mfma_f32_16x16x32_bf16 v[18:21], v[22:25], v[66:69], v[18:21]
	ds_read_b128 v[22:25], v26 offset:128
	s_waitcnt lgkmcnt(0)
	v_mfma_f32_16x16x32_bf16 v[18:21], v[22:25], v[34:37], v[18:21]
	ds_read_b128 v[22:25], v26 offset:192
	ds_read_b128 v[26:29], v140 offset:39232
	s_waitcnt lgkmcnt(1)
	v_mfma_f32_16x16x32_bf16 v[50:53], v[22:25], v[74:77], v[18:21]
	s_nop 3
	ds_read_b128 v[18:21], v140 offset:34816
	ds_read_b128 v[22:25], v140 offset:34880
	s_waitcnt lgkmcnt(1)
	v_mfma_f32_16x16x32_bf16 v[18:21], v[18:21], v[70:73], 0
	s_waitcnt lgkmcnt(0)
	v_mfma_f32_16x16x32_bf16 v[18:21], v[22:25], v[66:69], v[18:21]
	ds_read_b128 v[22:25], v140 offset:34944
	s_waitcnt lgkmcnt(0)
	v_mfma_f32_16x16x32_bf16 v[18:21], v[22:25], v[34:37], v[18:21]
	ds_read_b128 v[22:25], v140 offset:35008
	s_waitcnt lgkmcnt(0)
	v_mfma_f32_16x16x32_bf16 v[18:21], v[22:25], v[74:77], v[18:21]
	ds_read_b128 v[22:25], v140 offset:39168
	s_waitcnt lgkmcnt(0)
	v_mfma_f32_16x16x32_bf16 v[22:25], v[22:25], v[70:73], 0
	v_mfma_f32_16x16x32_bf16 v[22:25], v[26:29], v[66:69], v[22:25]
	ds_read_b128 v[26:29], v140 offset:39296
	s_waitcnt lgkmcnt(0)
	v_mfma_f32_16x16x32_bf16 v[22:25], v[26:29], v[34:37], v[22:25]
	ds_read_b128 v[26:29], v140 offset:39360
	s_waitcnt lgkmcnt(0)
	v_mfma_f32_16x16x32_bf16 v[46:49], v[26:29], v[74:77], v[22:25]
	s_nop 4
	ds_read_b128 v[22:25], v140 offset:43520
	ds_read_b128 v[26:29], v140 offset:43584
	s_waitcnt lgkmcnt(1)
	v_mfma_f32_16x16x32_bf16 v[22:25], v[22:25], v[70:73], 0
	s_waitcnt lgkmcnt(0)
	v_mfma_f32_16x16x32_bf16 v[22:25], v[26:29], v[66:69], v[22:25]
	ds_read_b128 v[26:29], v140 offset:43648
	s_waitcnt lgkmcnt(0)
	v_mfma_f32_16x16x32_bf16 v[22:25], v[26:29], v[34:37], v[22:25]
	ds_read_b128 v[26:29], v140 offset:43712
	s_waitcnt lgkmcnt(0)
	v_mfma_f32_16x16x32_bf16 v[22:25], v[26:29], v[74:77], v[22:25]
	ds_read_b128 v[26:29], v38
	s_waitcnt lgkmcnt(0)
	v_mfma_f32_16x16x32_bf16 v[26:29], v[26:29], v[70:73], 0
	v_mfma_f32_16x16x32_bf16 v[26:29], v[30:33], v[66:69], v[26:29]
	ds_read_b128 v[30:33], v38 offset:128
	s_waitcnt lgkmcnt(0)
	v_mfma_f32_16x16x32_bf16 v[26:29], v[30:33], v[34:37], v[26:29]
	ds_read_b128 v[30:33], v38 offset:192
	ds_read_b128 v[38:41], v140 offset:56640
	s_waitcnt lgkmcnt(1)
	v_mfma_f32_16x16x32_bf16 v[42:45], v[30:33], v[74:77], v[26:29]
	s_nop 3
	ds_read_b128 v[26:29], v140 offset:52224
	ds_read_b128 v[30:33], v140 offset:52288
	s_waitcnt lgkmcnt(1)
	v_mfma_f32_16x16x32_bf16 v[26:29], v[26:29], v[70:73], 0
	s_waitcnt lgkmcnt(0)
	v_mfma_f32_16x16x32_bf16 v[26:29], v[30:33], v[66:69], v[26:29]
	ds_read_b128 v[30:33], v140 offset:52352
	s_waitcnt lgkmcnt(0)
	v_mfma_f32_16x16x32_bf16 v[26:29], v[30:33], v[34:37], v[26:29]
	ds_read_b128 v[30:33], v140 offset:52416
	s_waitcnt lgkmcnt(0)
	v_mfma_f32_16x16x32_bf16 v[26:29], v[30:33], v[74:77], v[26:29]
	ds_read_b128 v[30:33], v140 offset:56576
	s_waitcnt lgkmcnt(0)
	v_mfma_f32_16x16x32_bf16 v[30:33], v[30:33], v[70:73], 0
	v_mfma_f32_16x16x32_bf16 v[30:33], v[38:41], v[66:69], v[30:33]
	ds_read_b128 v[38:41], v140 offset:56704
	s_waitcnt lgkmcnt(0)
	v_mfma_f32_16x16x32_bf16 v[30:33], v[38:41], v[34:37], v[30:33]
	ds_read_b128 v[38:41], v140 offset:56768
	s_waitcnt lgkmcnt(0)
	v_mfma_f32_16x16x32_bf16 v[38:41], v[38:41], v[74:77], v[30:33]
	s_nop 4
	ds_read_b128 v[30:33], v140 offset:60928
	s_waitcnt lgkmcnt(0)
	v_mfma_f32_16x16x32_bf16 v[30:33], v[30:33], v[70:73], 0
	v_mfma_f32_16x16x32_bf16 v[30:33], v[174:177], v[66:69], v[30:33]
	ds_read_b128 v[174:177], v140 offset:61056
	s_waitcnt lgkmcnt(0)
	v_mfma_f32_16x16x32_bf16 v[30:33], v[174:177], v[34:37], v[30:33]
	ds_read_b128 v[174:177], v140 offset:61120
	s_waitcnt lgkmcnt(0)
	v_mfma_f32_16x16x32_bf16 v[30:33], v[174:177], v[74:77], v[30:33]
	ds_read_b128 v[174:177], v87
	s_waitcnt lgkmcnt(0)
	v_mfma_f32_16x16x32_bf16 v[70:73], v[174:177], v[70:73], 0
	ds_read_b128 v[174:177], v87 offset:64
	s_waitcnt lgkmcnt(0)
	v_mfma_f32_16x16x32_bf16 v[66:69], v[174:177], v[66:69], v[70:73]
	s_nop 4
	ds_read_b128 v[70:73], v87 offset:128
	s_waitcnt lgkmcnt(0)
	v_mfma_f32_16x16x32_bf16 v[34:37], v[70:73], v[34:37], v[66:69]
	s_nop 2
	ds_read_b128 v[66:69], v87 offset:192
	s_waitcnt lgkmcnt(0)
	v_mfma_f32_16x16x32_bf16 v[34:37], v[66:69], v[74:77], v[34:37]
	v_max_f32_e32 v66, v5, v5
	v_max_f32_e32 v67, v4, v4
	v_max_f32_e32 v66, v67, v66
	v_max_f32_e32 v67, v65, v65
	v_max_f32_e32 v68, v64, v64
	v_max_f32_e32 v67, v68, v67
	v_max3_f32 v66, v2, v3, v66
	v_max3_f32 v67, v62, v63, v67
	v_max3_f32 v66, v66, s1, v67
	v_max_f32_e32 v67, v9, v9
	v_max_f32_e32 v68, v8, v8
	v_max_f32_e32 v67, v68, v67
	v_max_f32_e32 v68, v61, v61
	v_max_f32_e32 v69, v60, v60
	v_max_f32_e32 v68, v69, v68
	v_max3_f32 v67, v6, v7, v67
	v_max3_f32 v68, v58, v59, v68
	v_max3_f32 v66, v66, v67, v68
	v_max_f32_e32 v67, v13, v13
	v_max_f32_e32 v68, v12, v12
	v_max_f32_e32 v67, v68, v67
	v_max_f32_e32 v68, v57, v57
	v_max_f32_e32 v69, v56, v56
	v_max_f32_e32 v68, v69, v68
	v_max3_f32 v67, v10, v11, v67
	v_max3_f32 v68, v54, v55, v68
	v_max3_f32 v66, v66, v67, v68
	v_max_f32_e32 v67, v17, v17
	v_max_f32_e32 v68, v16, v16
	v_max_f32_e32 v67, v68, v67
	v_max_f32_e32 v68, v53, v53
	v_max_f32_e32 v69, v52, v52
	v_max_f32_e32 v68, v69, v68
	v_max3_f32 v67, v14, v15, v67
	v_max3_f32 v68, v50, v51, v68
	v_max3_f32 v66, v66, v67, v68
	v_max_f32_e32 v67, v21, v21
	v_max_f32_e32 v68, v20, v20
	v_max_f32_e32 v67, v68, v67
	v_max_f32_e32 v68, v49, v49
	v_max_f32_e32 v69, v48, v48
	v_max_f32_e32 v68, v69, v68
	v_max3_f32 v67, v18, v19, v67
	v_max3_f32 v68, v46, v47, v68
	v_max3_f32 v66, v66, v67, v68
	v_max_f32_e32 v67, v25, v25
	v_max_f32_e32 v68, v24, v24
	v_max_f32_e32 v67, v68, v67
	v_max_f32_e32 v68, v45, v45
	v_max_f32_e32 v69, v44, v44
	v_max_f32_e32 v68, v69, v68
	v_max3_f32 v67, v22, v23, v67
	v_max3_f32 v68, v42, v43, v68
	v_max3_f32 v66, v66, v67, v68
	v_max_f32_e32 v67, v29, v29
	v_max_f32_e32 v68, v28, v28
	v_max_f32_e32 v67, v68, v67
	v_max_f32_e32 v68, v41, v41
	v_max_f32_e32 v69, v40, v40
	v_max_f32_e32 v68, v69, v68
	v_max3_f32 v67, v26, v27, v67
	v_max3_f32 v68, v38, v39, v68
	v_max3_f32 v66, v66, v67, v68
	v_max_f32_e32 v67, v33, v33
	v_max_f32_e32 v68, v32, v32
	v_max_f32_e32 v67, v68, v67
	v_max_f32_e32 v68, v37, v37
	v_max_f32_e32 v69, v36, v36
	v_max_f32_e32 v68, v69, v68
	v_max3_f32 v67, v30, v31, v67
	v_max3_f32 v68, v34, v35, v68
	v_max3_f32 v67, v66, v67, v68
	v_and_b32_e32 v68, 64, v206
	v_xor_b32_e32 v66, 16, v206
	v_add_u32_e32 v68, 64, v68
	v_cmp_lt_i32_e32 vcc, v66, v68
	s_mov_b32 s1, 0xc2fc0000
	s_nop 0
	v_cndmask_b32_e32 v66, v206, v66, vcc
	v_lshlrev_b32_e32 v66, 2, v66
	ds_bpermute_b32 v69, v66, v67
	s_waitcnt lgkmcnt(0)
	v_max_f32_e32 v69, v69, v69
	v_max_f32_e32 v69, v67, v69
	v_xor_b32_e32 v67, 32, v206
	v_cmp_lt_i32_e32 vcc, v67, v68
	s_nop 1
	v_cndmask_b32_e32 v67, v206, v67, vcc
	v_lshlrev_b32_e32 v67, 2, v67
	ds_bpermute_b32 v68, v67, v69
	s_waitcnt lgkmcnt(0)
	v_max_f32_e32 v68, v68, v68
	v_max_f32_e32 v68, v69, v68
	v_sub_f32_e32 v2, v2, v68
	v_mul_f32_e32 v69, 0x3e0293ee, v2
	v_cmp_gt_f32_e32 vcc, s1, v69
	v_sub_f32_e32 v62, v62, v68
	v_sub_f32_e32 v3, v3, v68
	v_cndmask_b32_e32 v69, 0, v207, vcc
	v_fmac_f32_e32 v69, 0x3e0293ee, v2
	v_exp_f32_e32 v2, v69
	v_cndmask_b32_e32 v69, 0, v208, vcc
	v_sub_f32_e32 v63, v63, v68
	v_sub_f32_e32 v4, v4, v68
	v_ldexp_f32 v2, v2, v69
	v_mul_f32_e32 v69, 0x3e0293ee, v62
	v_cmp_gt_f32_e32 vcc, s1, v69
	v_sub_f32_e32 v64, v64, v68
	v_sub_f32_e32 v5, v5, v68
	v_cndmask_b32_e32 v69, 0, v207, vcc
	v_fmac_f32_e32 v69, 0x3e0293ee, v62
	v_exp_f32_e32 v62, v69
	v_cndmask_b32_e32 v69, 0, v208, vcc
	v_sub_f32_e32 v65, v65, v68
	v_sub_f32_e32 v6, v6, v68
	v_ldexp_f32 v62, v62, v69
	v_mul_f32_e32 v69, 0x3e0293ee, v3
	v_cmp_gt_f32_e32 vcc, s1, v69
	v_sub_f32_e32 v58, v58, v68
	v_sub_f32_e32 v7, v7, v68
	v_cndmask_b32_e32 v69, 0, v207, vcc
	v_fmac_f32_e32 v69, 0x3e0293ee, v3
	v_exp_f32_e32 v3, v69
	v_cndmask_b32_e32 v69, 0, v208, vcc
	v_sub_f32_e32 v59, v59, v68
	v_sub_f32_e32 v8, v8, v68
	v_ldexp_f32 v3, v3, v69
	v_mul_f32_e32 v69, 0x3e0293ee, v63
	v_cmp_gt_f32_e32 vcc, s1, v69
	v_bfe_u32 v73, v3, 16, 1
	v_add3_u32 v73, v3, v73, s60
	v_cndmask_b32_e32 v69, 0, v207, vcc
	v_fmac_f32_e32 v69, 0x3e0293ee, v63
	v_exp_f32_e32 v63, v69
	v_cndmask_b32_e32 v69, 0, v208, vcc
	v_sub_f32_e32 v60, v60, v68
	v_sub_f32_e32 v9, v9, v68
	v_ldexp_f32 v63, v63, v69
	v_mul_f32_e32 v69, 0x3e0293ee, v4
	v_cmp_gt_f32_e32 vcc, s1, v69
	v_sub_f32_e32 v61, v61, v68
	v_sub_f32_e32 v10, v10, v68
	v_cndmask_b32_e32 v69, 0, v207, vcc
	v_fmac_f32_e32 v69, 0x3e0293ee, v4
	v_exp_f32_e32 v4, v69
	v_cndmask_b32_e32 v69, 0, v208, vcc
	v_sub_f32_e32 v54, v54, v68
	v_sub_f32_e32 v11, v11, v68
	v_ldexp_f32 v4, v4, v69
	v_mul_f32_e32 v69, 0x3e0293ee, v64
	v_cmp_gt_f32_e32 vcc, s1, v69
	v_sub_f32_e32 v55, v55, v68
	v_sub_f32_e32 v12, v12, v68
	v_cndmask_b32_e32 v69, 0, v207, vcc
	v_fmac_f32_e32 v69, 0x3e0293ee, v64
	v_exp_f32_e32 v64, v69
	v_cndmask_b32_e32 v69, 0, v208, vcc
	v_sub_f32_e32 v56, v56, v68
	v_sub_f32_e32 v13, v13, v68
	v_ldexp_f32 v64, v64, v69
	v_mul_f32_e32 v69, 0x3e0293ee, v5
	v_cmp_gt_f32_e32 vcc, s1, v69
	v_sub_f32_e32 v57, v57, v68
	v_sub_f32_e32 v14, v14, v68
	v_cndmask_b32_e32 v69, 0, v207, vcc
	v_fmac_f32_e32 v69, 0x3e0293ee, v5
	v_exp_f32_e32 v5, v69
	v_cndmask_b32_e32 v69, 0, v208, vcc
	v_sub_f32_e32 v50, v50, v68
	v_sub_f32_e32 v15, v15, v68
	v_ldexp_f32 v5, v5, v69
	v_mul_f32_e32 v69, 0x3e0293ee, v65
	v_cmp_gt_f32_e32 vcc, s1, v69
	v_add_f32_e32 v70, v4, v5
	v_bfe_u32 v72, v5, 16, 1
	v_cndmask_b32_e32 v69, 0, v207, vcc
	v_fmac_f32_e32 v69, 0x3e0293ee, v65
	v_exp_f32_e32 v65, v69
	v_cndmask_b32_e32 v69, 0, v208, vcc
	v_sub_f32_e32 v51, v51, v68
	v_sub_f32_e32 v16, v16, v68
	v_ldexp_f32 v65, v65, v69
	v_add_f32_e32 v69, v2, v3
	v_add_f32_e32 v69, v69, v70
	v_add_f32_e32 v70, v62, v63
	v_add_f32_e32 v71, v64, v65
	v_add_f32_e32 v70, v70, v71
	v_add_f32_e32 v69, v69, v70
	v_bfe_u32 v70, v65, 16, 1
	v_bfe_u32 v71, v63, 16, 1
	v_add3_u32 v3, v5, v72, s60
	v_add3_u32 v63, v63, v71, s60
	v_add3_u32 v5, v65, v70, s60
	v_bfe_u32 v70, v4, 16, 1
	v_bfe_u32 v71, v62, 16, 1
	v_bfe_u32 v72, v64, 16, 1
	v_bfe_u32 v65, v2, 16, 1
	v_add3_u32 v64, v64, v72, s60
	v_add3_u32 v62, v62, v71, s60
	v_add3_u32 v4, v4, v70, s60
	v_add3_u32 v2, v2, v65, s60
	v_lshrrev_b32_e32 v65, 16, v4
	v_lshrrev_b32_e32 v4, 16, v62
	v_lshrrev_b32_e32 v62, 16, v64
	v_and_or_b32 v5, v5, s33, v62
	v_mul_f32_e32 v62, 0x3e0293ee, v6
	v_cmp_gt_f32_e32 vcc, s1, v62
	v_and_or_b32 v4, v63, s33, v4
	v_and_or_b32 v3, v3, s33, v65
	v_cndmask_b32_e32 v62, 0, v207, vcc
	v_fmac_f32_e32 v62, 0x3e0293ee, v6
	v_exp_f32_e32 v6, v62
	v_cndmask_b32_e32 v62, 0, v208, vcc
	v_sub_f32_e32 v52, v52, v68
	v_sub_f32_e32 v17, v17, v68
	v_ldexp_f32 v6, v6, v62
	v_mul_f32_e32 v62, 0x3e0293ee, v58
	v_cmp_gt_f32_e32 vcc, s1, v62
	v_sub_f32_e32 v53, v53, v68
	v_sub_f32_e32 v18, v18, v68
	v_cndmask_b32_e32 v62, 0, v207, vcc
	v_fmac_f32_e32 v62, 0x3e0293ee, v58
	v_exp_f32_e32 v58, v62
	v_cndmask_b32_e32 v62, 0, v208, vcc
	v_sub_f32_e32 v46, v46, v68
	v_sub_f32_e32 v19, v19, v68
	v_ldexp_f32 v58, v58, v62
	v_mul_f32_e32 v62, 0x3e0293ee, v7
	v_cmp_gt_f32_e32 vcc, s1, v62
	v_sub_f32_e32 v47, v47, v68
	v_sub_f32_e32 v20, v20, v68
	v_cndmask_b32_e32 v62, 0, v207, vcc
	v_fmac_f32_e32 v62, 0x3e0293ee, v7
	v_exp_f32_e32 v7, v62
	v_cndmask_b32_e32 v62, 0, v208, vcc
	v_sub_f32_e32 v48, v48, v68
	v_sub_f32_e32 v21, v21, v68
	v_ldexp_f32 v7, v7, v62
	v_mul_f32_e32 v62, 0x3e0293ee, v59
	v_cmp_gt_f32_e32 vcc, s1, v62
	v_sub_f32_e32 v49, v49, v68
	v_sub_f32_e32 v22, v22, v68
	v_cndmask_b32_e32 v62, 0, v207, vcc
	v_fmac_f32_e32 v62, 0x3e0293ee, v59
	v_exp_f32_e32 v59, v62
	v_cndmask_b32_e32 v62, 0, v208, vcc
	v_sub_f32_e32 v42, v42, v68
	v_sub_f32_e32 v23, v23, v68
	v_ldexp_f32 v59, v59, v62
	v_mul_f32_e32 v62, 0x3e0293ee, v8
	v_cmp_gt_f32_e32 vcc, s1, v62
	v_sub_f32_e32 v43, v43, v68
	v_sub_f32_e32 v24, v24, v68
	v_cndmask_b32_e32 v62, 0, v207, vcc
	v_fmac_f32_e32 v62, 0x3e0293ee, v8
	v_exp_f32_e32 v8, v62
	v_cndmask_b32_e32 v62, 0, v208, vcc
	v_sub_f32_e32 v44, v44, v68
	v_sub_f32_e32 v25, v25, v68
	v_ldexp_f32 v8, v8, v62
	v_mul_f32_e32 v62, 0x3e0293ee, v60
	v_cmp_gt_f32_e32 vcc, s1, v62
	v_sub_f32_e32 v45, v45, v68
	v_sub_f32_e32 v26, v26, v68
	v_cndmask_b32_e32 v62, 0, v207, vcc
	v_fmac_f32_e32 v62, 0x3e0293ee, v60
	v_exp_f32_e32 v60, v62
	v_cndmask_b32_e32 v62, 0, v208, vcc
	v_sub_f32_e32 v38, v38, v68
	v_sub_f32_e32 v27, v27, v68
	v_ldexp_f32 v60, v60, v62
	v_mul_f32_e32 v62, 0x3e0293ee, v9
	v_cmp_gt_f32_e32 vcc, s1, v62
	v_sub_f32_e32 v39, v39, v68
	v_sub_f32_e32 v28, v28, v68
	v_cndmask_b32_e32 v62, 0, v207, vcc
	v_fmac_f32_e32 v62, 0x3e0293ee, v9
	v_exp_f32_e32 v9, v62
	v_cndmask_b32_e32 v62, 0, v208, vcc
	v_sub_f32_e32 v40, v40, v68
	v_sub_f32_e32 v29, v29, v68
	v_ldexp_f32 v9, v9, v62
	v_mul_f32_e32 v62, 0x3e0293ee, v61
	v_cmp_gt_f32_e32 vcc, s1, v62
	v_add_f32_e32 v63, v8, v9
	v_bfe_u32 v65, v9, 16, 1
	v_cndmask_b32_e32 v62, 0, v207, vcc
	v_fmac_f32_e32 v62, 0x3e0293ee, v61
	v_exp_f32_e32 v61, v62
	v_cndmask_b32_e32 v62, 0, v208, vcc
	v_sub_f32_e32 v41, v41, v68
	v_sub_f32_e32 v30, v30, v68
	v_ldexp_f32 v61, v61, v62
	v_add_f32_e32 v62, v6, v7
	v_add_f32_e32 v62, v62, v63
	v_add_f32_e32 v63, v58, v59
	v_add_f32_e32 v64, v60, v61
	v_add_f32_e32 v63, v63, v64
	v_add_f32_e32 v62, v62, v63
	v_add_f32_e32 v62, v69, v62
	v_bfe_u32 v63, v61, 16, 1
	v_bfe_u32 v64, v59, 16, 1
	v_bfe_u32 v69, v7, 16, 1
	v_add3_u32 v69, v7, v69, s60
	v_add3_u32 v7, v9, v65, s60
	v_add3_u32 v59, v59, v64, s60
	v_add3_u32 v9, v61, v63, s60
	v_bfe_u32 v63, v8, 16, 1
	v_bfe_u32 v64, v58, 16, 1
	v_bfe_u32 v65, v60, 16, 1
	v_bfe_u32 v61, v6, 16, 1
	v_add3_u32 v60, v60, v65, s60
	v_add3_u32 v58, v58, v64, s60
	v_add3_u32 v8, v8, v63, s60
	v_add3_u32 v6, v6, v61, s60
	v_lshrrev_b32_e32 v61, 16, v8
	v_lshrrev_b32_e32 v8, 16, v58
	v_lshrrev_b32_e32 v58, 16, v60
	v_and_or_b32 v9, v9, s33, v58
	v_mul_f32_e32 v58, 0x3e0293ee, v10
	v_cmp_gt_f32_e32 vcc, s1, v58
	v_and_or_b32 v8, v59, s33, v8
	v_and_or_b32 v7, v7, s33, v61
	v_cndmask_b32_e32 v58, 0, v207, vcc
	v_fmac_f32_e32 v58, 0x3e0293ee, v10
	v_exp_f32_e32 v10, v58
	v_cndmask_b32_e32 v58, 0, v208, vcc
	v_sub_f32_e32 v34, v34, v68
	v_sub_f32_e32 v31, v31, v68
	v_ldexp_f32 v10, v10, v58
	v_mul_f32_e32 v58, 0x3e0293ee, v54
	v_cmp_gt_f32_e32 vcc, s1, v58
	v_sub_f32_e32 v35, v35, v68
	v_sub_f32_e32 v32, v32, v68
	v_cndmask_b32_e32 v58, 0, v207, vcc
	v_fmac_f32_e32 v58, 0x3e0293ee, v54
	v_exp_f32_e32 v54, v58
	v_cndmask_b32_e32 v58, 0, v208, vcc
	v_sub_f32_e32 v36, v36, v68
	v_sub_f32_e32 v33, v33, v68
	v_ldexp_f32 v54, v54, v58
	v_mul_f32_e32 v58, 0x3e0293ee, v11
	v_cmp_gt_f32_e32 vcc, s1, v58
	v_sub_f32_e32 v37, v37, v68
	v_lshrrev_b32_e32 v2, 16, v2
	v_cndmask_b32_e32 v58, 0, v207, vcc
	v_fmac_f32_e32 v58, 0x3e0293ee, v11
	v_exp_f32_e32 v11, v58
	v_cndmask_b32_e32 v58, 0, v208, vcc
	v_and_or_b32 v2, v73, s33, v2
	v_lshrrev_b32_e32 v6, 16, v6
	v_ldexp_f32 v11, v11, v58
	v_mul_f32_e32 v58, 0x3e0293ee, v55
	v_cmp_gt_f32_e32 vcc, s1, v58
	v_and_or_b32 v6, v69, s33, v6
	s_nop 0
	v_cndmask_b32_e32 v58, 0, v207, vcc
	v_fmac_f32_e32 v58, 0x3e0293ee, v55
	v_exp_f32_e32 v55, v58
	v_cndmask_b32_e32 v58, 0, v208, vcc
	v_ldexp_f32 v55, v55, v58
	v_mul_f32_e32 v58, 0x3e0293ee, v12
	v_cmp_gt_f32_e32 vcc, s1, v58
	s_nop 1
	v_cndmask_b32_e32 v58, 0, v207, vcc
	v_fmac_f32_e32 v58, 0x3e0293ee, v12
	v_exp_f32_e32 v12, v58
	v_cndmask_b32_e32 v58, 0, v208, vcc
	v_ldexp_f32 v12, v12, v58
	v_mul_f32_e32 v58, 0x3e0293ee, v56
	v_cmp_gt_f32_e32 vcc, s1, v58
	s_nop 1
	v_cndmask_b32_e32 v58, 0, v207, vcc
	v_fmac_f32_e32 v58, 0x3e0293ee, v56
	v_exp_f32_e32 v56, v58
	v_cndmask_b32_e32 v58, 0, v208, vcc
	v_ldexp_f32 v56, v56, v58
	v_mul_f32_e32 v58, 0x3e0293ee, v13
	v_cmp_gt_f32_e32 vcc, s1, v58
	s_nop 1
	v_cndmask_b32_e32 v58, 0, v207, vcc
	v_fmac_f32_e32 v58, 0x3e0293ee, v13
	v_exp_f32_e32 v13, v58
	v_cndmask_b32_e32 v58, 0, v208, vcc
	v_ldexp_f32 v13, v13, v58
	v_mul_f32_e32 v58, 0x3e0293ee, v57
	v_cmp_gt_f32_e32 vcc, s1, v58
	v_add_f32_e32 v59, v12, v13
	v_bfe_u32 v61, v13, 16, 1
	v_cndmask_b32_e32 v58, 0, v207, vcc
	v_fmac_f32_e32 v58, 0x3e0293ee, v57
	v_exp_f32_e32 v57, v58
	v_cndmask_b32_e32 v58, 0, v208, vcc
	v_ldexp_f32 v57, v57, v58
	v_add_f32_e32 v58, v10, v11
	v_add_f32_e32 v58, v58, v59
	v_add_f32_e32 v59, v54, v55
	v_add_f32_e32 v60, v56, v57
	v_add_f32_e32 v59, v59, v60
	v_add_f32_e32 v58, v58, v59
	v_add_f32_e32 v58, v58, v62
	v_bfe_u32 v59, v57, 16, 1
	v_bfe_u32 v60, v55, 16, 1
	v_bfe_u32 v62, v11, 16, 1
	v_add3_u32 v62, v11, v62, s60
	v_add3_u32 v11, v13, v61, s60
	v_add3_u32 v55, v55, v60, s60
	v_add3_u32 v13, v57, v59, s60
	v_bfe_u32 v59, v12, 16, 1
	v_bfe_u32 v60, v54, 16, 1
	v_bfe_u32 v61, v56, 16, 1
	v_bfe_u32 v57, v10, 16, 1
	v_add3_u32 v56, v56, v61, s60
	v_add3_u32 v54, v54, v60, s60
	v_add3_u32 v12, v12, v59, s60
	v_add3_u32 v10, v10, v57, s60
	v_lshrrev_b32_e32 v57, 16, v12
	v_lshrrev_b32_e32 v12, 16, v54
	v_lshrrev_b32_e32 v54, 16, v56
	v_and_or_b32 v13, v13, s33, v54
	v_mul_f32_e32 v54, 0x3e0293ee, v14
	v_cmp_gt_f32_e32 vcc, s1, v54
	v_and_or_b32 v12, v55, s33, v12
	v_and_or_b32 v11, v11, s33, v57
	v_cndmask_b32_e32 v54, 0, v207, vcc
	v_fmac_f32_e32 v54, 0x3e0293ee, v14
	v_exp_f32_e32 v14, v54
	v_cndmask_b32_e32 v54, 0, v208, vcc
	v_lshrrev_b32_e32 v10, 16, v10
	v_and_or_b32 v10, v62, s33, v10
	v_ldexp_f32 v14, v14, v54
	v_mul_f32_e32 v54, 0x3e0293ee, v50
	v_cmp_gt_f32_e32 vcc, s1, v54
	s_nop 1
	v_cndmask_b32_e32 v54, 0, v207, vcc
	v_fmac_f32_e32 v54, 0x3e0293ee, v50
	v_exp_f32_e32 v50, v54
	v_cndmask_b32_e32 v54, 0, v208, vcc
	v_ldexp_f32 v50, v50, v54
	v_mul_f32_e32 v54, 0x3e0293ee, v15
	v_cmp_gt_f32_e32 vcc, s1, v54
	s_nop 1
	v_cndmask_b32_e32 v54, 0, v207, vcc
	v_fmac_f32_e32 v54, 0x3e0293ee, v15
	v_exp_f32_e32 v15, v54
	v_cndmask_b32_e32 v54, 0, v208, vcc
	v_ldexp_f32 v15, v15, v54
	v_mul_f32_e32 v54, 0x3e0293ee, v51
	v_cmp_gt_f32_e32 vcc, s1, v54
	s_nop 1
	v_cndmask_b32_e32 v54, 0, v207, vcc
	v_fmac_f32_e32 v54, 0x3e0293ee, v51
	v_exp_f32_e32 v51, v54
	v_cndmask_b32_e32 v54, 0, v208, vcc
	v_ldexp_f32 v51, v51, v54
	v_mul_f32_e32 v54, 0x3e0293ee, v16
	v_cmp_gt_f32_e32 vcc, s1, v54
	s_nop 1
	v_cndmask_b32_e32 v54, 0, v207, vcc
	v_fmac_f32_e32 v54, 0x3e0293ee, v16
	v_exp_f32_e32 v16, v54
	v_cndmask_b32_e32 v54, 0, v208, vcc
	v_ldexp_f32 v16, v16, v54
	v_mul_f32_e32 v54, 0x3e0293ee, v52
	v_cmp_gt_f32_e32 vcc, s1, v54
	s_nop 1
	v_cndmask_b32_e32 v54, 0, v207, vcc
	v_fmac_f32_e32 v54, 0x3e0293ee, v52
	v_exp_f32_e32 v52, v54
	v_cndmask_b32_e32 v54, 0, v208, vcc
	v_ldexp_f32 v52, v52, v54
	v_mul_f32_e32 v54, 0x3e0293ee, v17
	v_cmp_gt_f32_e32 vcc, s1, v54
	s_nop 1
	v_cndmask_b32_e32 v54, 0, v207, vcc
	v_fmac_f32_e32 v54, 0x3e0293ee, v17
	v_exp_f32_e32 v17, v54
	v_cndmask_b32_e32 v54, 0, v208, vcc
	v_ldexp_f32 v17, v17, v54
	v_mul_f32_e32 v54, 0x3e0293ee, v53
	v_cmp_gt_f32_e32 vcc, s1, v54
	v_add_f32_e32 v55, v16, v17
	v_bfe_u32 v57, v17, 16, 1
	v_cndmask_b32_e32 v54, 0, v207, vcc
	v_fmac_f32_e32 v54, 0x3e0293ee, v53
	v_exp_f32_e32 v53, v54
	v_cndmask_b32_e32 v54, 0, v208, vcc
	v_ldexp_f32 v53, v53, v54
	v_add_f32_e32 v54, v14, v15
	v_add_f32_e32 v54, v54, v55
	v_add_f32_e32 v55, v50, v51
	v_add_f32_e32 v56, v52, v53
	v_add_f32_e32 v55, v55, v56
	v_add_f32_e32 v54, v54, v55
	v_add_f32_e32 v54, v54, v58
	v_bfe_u32 v55, v53, 16, 1
	v_bfe_u32 v56, v51, 16, 1
	v_bfe_u32 v58, v15, 16, 1
	v_add3_u32 v58, v15, v58, s60
	v_add3_u32 v15, v17, v57, s60
	v_add3_u32 v51, v51, v56, s60
	v_add3_u32 v17, v53, v55, s60
	v_bfe_u32 v55, v16, 16, 1
	v_bfe_u32 v56, v50, 16, 1
	v_bfe_u32 v57, v52, 16, 1
	v_bfe_u32 v53, v14, 16, 1
	v_add3_u32 v52, v52, v57, s60
	v_add3_u32 v50, v50, v56, s60
	v_add3_u32 v16, v16, v55, s60
	v_add3_u32 v14, v14, v53, s60
	v_lshrrev_b32_e32 v53, 16, v16
	v_lshrrev_b32_e32 v16, 16, v50
	v_lshrrev_b32_e32 v50, 16, v52
	v_and_or_b32 v17, v17, s33, v50
	v_mul_f32_e32 v50, 0x3e0293ee, v18
	v_cmp_gt_f32_e32 vcc, s1, v50
	v_and_or_b32 v16, v51, s33, v16
	v_and_or_b32 v15, v15, s33, v53
	v_cndmask_b32_e32 v50, 0, v207, vcc
	v_fmac_f32_e32 v50, 0x3e0293ee, v18
	v_exp_f32_e32 v18, v50
	v_cndmask_b32_e32 v50, 0, v208, vcc
	v_lshrrev_b32_e32 v14, 16, v14
	v_and_or_b32 v14, v58, s33, v14
	v_ldexp_f32 v18, v18, v50
	v_mul_f32_e32 v50, 0x3e0293ee, v46
	v_cmp_gt_f32_e32 vcc, s1, v50
	s_nop 1
	v_cndmask_b32_e32 v50, 0, v207, vcc
	v_fmac_f32_e32 v50, 0x3e0293ee, v46
	v_exp_f32_e32 v46, v50
	v_cndmask_b32_e32 v50, 0, v208, vcc
	v_ldexp_f32 v46, v46, v50
	v_mul_f32_e32 v50, 0x3e0293ee, v19
	v_cmp_gt_f32_e32 vcc, s1, v50
	s_nop 1
	v_cndmask_b32_e32 v50, 0, v207, vcc
	v_fmac_f32_e32 v50, 0x3e0293ee, v19
	v_exp_f32_e32 v19, v50
	v_cndmask_b32_e32 v50, 0, v208, vcc
	v_ldexp_f32 v19, v19, v50
	v_mul_f32_e32 v50, 0x3e0293ee, v47
	v_cmp_gt_f32_e32 vcc, s1, v50
	s_nop 1
	v_cndmask_b32_e32 v50, 0, v207, vcc
	v_fmac_f32_e32 v50, 0x3e0293ee, v47
	v_exp_f32_e32 v47, v50
	v_cndmask_b32_e32 v50, 0, v208, vcc
	v_ldexp_f32 v47, v47, v50
	v_mul_f32_e32 v50, 0x3e0293ee, v20
	v_cmp_gt_f32_e32 vcc, s1, v50
	s_nop 1
	v_cndmask_b32_e32 v50, 0, v207, vcc
	v_fmac_f32_e32 v50, 0x3e0293ee, v20
	v_exp_f32_e32 v20, v50
	v_cndmask_b32_e32 v50, 0, v208, vcc
	v_ldexp_f32 v20, v20, v50
	v_mul_f32_e32 v50, 0x3e0293ee, v48
	v_cmp_gt_f32_e32 vcc, s1, v50
	s_nop 1
	v_cndmask_b32_e32 v50, 0, v207, vcc
	v_fmac_f32_e32 v50, 0x3e0293ee, v48
	v_exp_f32_e32 v48, v50
	v_cndmask_b32_e32 v50, 0, v208, vcc
	v_ldexp_f32 v48, v48, v50
	v_mul_f32_e32 v50, 0x3e0293ee, v21
	v_cmp_gt_f32_e32 vcc, s1, v50
	s_nop 1
	v_cndmask_b32_e32 v50, 0, v207, vcc
	v_fmac_f32_e32 v50, 0x3e0293ee, v21
	v_exp_f32_e32 v21, v50
	v_cndmask_b32_e32 v50, 0, v208, vcc
	v_ldexp_f32 v21, v21, v50
	v_mul_f32_e32 v50, 0x3e0293ee, v49
	v_cmp_gt_f32_e32 vcc, s1, v50
	v_add_f32_e32 v51, v20, v21
	v_bfe_u32 v53, v21, 16, 1
	v_cndmask_b32_e32 v50, 0, v207, vcc
	v_fmac_f32_e32 v50, 0x3e0293ee, v49
	v_exp_f32_e32 v49, v50
	v_cndmask_b32_e32 v50, 0, v208, vcc
	v_ldexp_f32 v49, v49, v50
	v_add_f32_e32 v50, v18, v19
	v_add_f32_e32 v50, v50, v51
	v_add_f32_e32 v51, v46, v47
	v_add_f32_e32 v52, v48, v49
	v_add_f32_e32 v51, v51, v52
	v_add_f32_e32 v50, v50, v51
	v_add_f32_e32 v50, v50, v54
	v_bfe_u32 v51, v49, 16, 1
	v_bfe_u32 v52, v47, 16, 1
	v_bfe_u32 v54, v19, 16, 1
	v_add3_u32 v54, v19, v54, s60
	v_add3_u32 v19, v21, v53, s60
	v_add3_u32 v47, v47, v52, s60
	v_add3_u32 v21, v49, v51, s60
	v_bfe_u32 v51, v20, 16, 1
	v_bfe_u32 v52, v46, 16, 1
	v_bfe_u32 v53, v48, 16, 1
	v_bfe_u32 v49, v18, 16, 1
	v_add3_u32 v48, v48, v53, s60
	v_add3_u32 v46, v46, v52, s60
	v_add3_u32 v20, v20, v51, s60
	v_add3_u32 v18, v18, v49, s60
	v_lshrrev_b32_e32 v49, 16, v20
	v_lshrrev_b32_e32 v20, 16, v46
	v_lshrrev_b32_e32 v46, 16, v48
	v_and_or_b32 v21, v21, s33, v46
	v_mul_f32_e32 v46, 0x3e0293ee, v22
	v_cmp_gt_f32_e32 vcc, s1, v46
	v_and_or_b32 v20, v47, s33, v20
	v_and_or_b32 v19, v19, s33, v49
	v_cndmask_b32_e32 v46, 0, v207, vcc
	v_fmac_f32_e32 v46, 0x3e0293ee, v22
	v_exp_f32_e32 v22, v46
	v_cndmask_b32_e32 v46, 0, v208, vcc
	v_lshrrev_b32_e32 v18, 16, v18
	v_and_or_b32 v18, v54, s33, v18
	v_ldexp_f32 v22, v22, v46
	v_mul_f32_e32 v46, 0x3e0293ee, v42
	v_cmp_gt_f32_e32 vcc, s1, v46
	s_nop 1
	v_cndmask_b32_e32 v46, 0, v207, vcc
	v_fmac_f32_e32 v46, 0x3e0293ee, v42
	v_exp_f32_e32 v42, v46
	v_cndmask_b32_e32 v46, 0, v208, vcc
	v_ldexp_f32 v42, v42, v46
	v_mul_f32_e32 v46, 0x3e0293ee, v23
	v_cmp_gt_f32_e32 vcc, s1, v46
	s_nop 1
	v_cndmask_b32_e32 v46, 0, v207, vcc
	v_fmac_f32_e32 v46, 0x3e0293ee, v23
	v_exp_f32_e32 v23, v46
	v_cndmask_b32_e32 v46, 0, v208, vcc
	v_ldexp_f32 v23, v23, v46
	v_mul_f32_e32 v46, 0x3e0293ee, v43
	v_cmp_gt_f32_e32 vcc, s1, v46
	s_nop 1
	v_cndmask_b32_e32 v46, 0, v207, vcc
	v_fmac_f32_e32 v46, 0x3e0293ee, v43
	v_exp_f32_e32 v43, v46
	v_cndmask_b32_e32 v46, 0, v208, vcc
	v_ldexp_f32 v43, v43, v46
	v_mul_f32_e32 v46, 0x3e0293ee, v24
	v_cmp_gt_f32_e32 vcc, s1, v46
	s_nop 1
	v_cndmask_b32_e32 v46, 0, v207, vcc
	v_fmac_f32_e32 v46, 0x3e0293ee, v24
	v_exp_f32_e32 v24, v46
	v_cndmask_b32_e32 v46, 0, v208, vcc
	v_ldexp_f32 v24, v24, v46
	v_mul_f32_e32 v46, 0x3e0293ee, v44
	v_cmp_gt_f32_e32 vcc, s1, v46
	s_nop 1
	v_cndmask_b32_e32 v46, 0, v207, vcc
	v_fmac_f32_e32 v46, 0x3e0293ee, v44
	v_exp_f32_e32 v44, v46
	v_cndmask_b32_e32 v46, 0, v208, vcc
	v_ldexp_f32 v44, v44, v46
	v_mul_f32_e32 v46, 0x3e0293ee, v25
	v_cmp_gt_f32_e32 vcc, s1, v46
	s_nop 1
	v_cndmask_b32_e32 v46, 0, v207, vcc
	v_fmac_f32_e32 v46, 0x3e0293ee, v25
	v_exp_f32_e32 v25, v46
	v_cndmask_b32_e32 v46, 0, v208, vcc
	v_ldexp_f32 v25, v25, v46
	v_mul_f32_e32 v46, 0x3e0293ee, v45
	v_cmp_gt_f32_e32 vcc, s1, v46
	v_add_f32_e32 v47, v24, v25
	v_bfe_u32 v49, v25, 16, 1
	v_cndmask_b32_e32 v46, 0, v207, vcc
	v_fmac_f32_e32 v46, 0x3e0293ee, v45
	v_exp_f32_e32 v45, v46
	v_cndmask_b32_e32 v46, 0, v208, vcc
	v_ldexp_f32 v45, v45, v46
	v_add_f32_e32 v46, v22, v23
	v_add_f32_e32 v46, v46, v47
	v_add_f32_e32 v47, v42, v43
	v_add_f32_e32 v48, v44, v45
	v_add_f32_e32 v47, v47, v48
	v_add_f32_e32 v46, v46, v47
	v_add_f32_e32 v46, v46, v50
	v_bfe_u32 v47, v45, 16, 1
	v_bfe_u32 v48, v43, 16, 1
	v_bfe_u32 v50, v23, 16, 1
	v_add3_u32 v50, v23, v50, s60
	v_add3_u32 v23, v25, v49, s60
	v_add3_u32 v43, v43, v48, s60
	v_add3_u32 v25, v45, v47, s60
	v_bfe_u32 v47, v24, 16, 1
	v_bfe_u32 v48, v42, 16, 1
	v_bfe_u32 v49, v44, 16, 1
	v_bfe_u32 v45, v22, 16, 1
	v_add3_u32 v44, v44, v49, s60
	v_add3_u32 v42, v42, v48, s60
	v_add3_u32 v24, v24, v47, s60
	v_add3_u32 v22, v22, v45, s60
	v_lshrrev_b32_e32 v45, 16, v24
	v_lshrrev_b32_e32 v24, 16, v42
	v_lshrrev_b32_e32 v42, 16, v44
	v_and_or_b32 v25, v25, s33, v42
	v_mul_f32_e32 v42, 0x3e0293ee, v26
	v_cmp_gt_f32_e32 vcc, s1, v42
	v_and_or_b32 v24, v43, s33, v24
	v_and_or_b32 v23, v23, s33, v45
	v_cndmask_b32_e32 v42, 0, v207, vcc
	v_fmac_f32_e32 v42, 0x3e0293ee, v26
	v_exp_f32_e32 v26, v42
	v_cndmask_b32_e32 v42, 0, v208, vcc
	v_lshrrev_b32_e32 v22, 16, v22
	v_and_or_b32 v22, v50, s33, v22
	v_ldexp_f32 v26, v26, v42
	v_mul_f32_e32 v42, 0x3e0293ee, v38
	v_cmp_gt_f32_e32 vcc, s1, v42
	s_nop 1
	v_cndmask_b32_e32 v42, 0, v207, vcc
	v_fmac_f32_e32 v42, 0x3e0293ee, v38
	v_exp_f32_e32 v38, v42
	v_cndmask_b32_e32 v42, 0, v208, vcc
	v_ldexp_f32 v38, v38, v42
	v_mul_f32_e32 v42, 0x3e0293ee, v27
	v_cmp_gt_f32_e32 vcc, s1, v42
	s_nop 1
	v_cndmask_b32_e32 v42, 0, v207, vcc
	v_fmac_f32_e32 v42, 0x3e0293ee, v27
	v_exp_f32_e32 v27, v42
	v_cndmask_b32_e32 v42, 0, v208, vcc
	v_ldexp_f32 v27, v27, v42
	v_mul_f32_e32 v42, 0x3e0293ee, v39
	v_cmp_gt_f32_e32 vcc, s1, v42
	s_nop 1
	v_cndmask_b32_e32 v42, 0, v207, vcc
	v_fmac_f32_e32 v42, 0x3e0293ee, v39
	v_exp_f32_e32 v39, v42
	v_cndmask_b32_e32 v42, 0, v208, vcc
	v_ldexp_f32 v39, v39, v42
	v_mul_f32_e32 v42, 0x3e0293ee, v28
	v_cmp_gt_f32_e32 vcc, s1, v42
	s_nop 1
	v_cndmask_b32_e32 v42, 0, v207, vcc
	v_fmac_f32_e32 v42, 0x3e0293ee, v28
	v_exp_f32_e32 v28, v42
	v_cndmask_b32_e32 v42, 0, v208, vcc
	v_ldexp_f32 v28, v28, v42
	v_mul_f32_e32 v42, 0x3e0293ee, v40
	v_cmp_gt_f32_e32 vcc, s1, v42
	s_nop 1
	v_cndmask_b32_e32 v42, 0, v207, vcc
	v_fmac_f32_e32 v42, 0x3e0293ee, v40
	v_exp_f32_e32 v40, v42
	v_cndmask_b32_e32 v42, 0, v208, vcc
	v_ldexp_f32 v40, v40, v42
	v_mul_f32_e32 v42, 0x3e0293ee, v29
	v_cmp_gt_f32_e32 vcc, s1, v42
	s_nop 1
	v_cndmask_b32_e32 v42, 0, v207, vcc
	v_fmac_f32_e32 v42, 0x3e0293ee, v29
	v_exp_f32_e32 v29, v42
	v_cndmask_b32_e32 v42, 0, v208, vcc
	v_ldexp_f32 v29, v29, v42
	v_mul_f32_e32 v42, 0x3e0293ee, v41
	v_cmp_gt_f32_e32 vcc, s1, v42
	v_add_f32_e32 v43, v28, v29
	v_bfe_u32 v45, v29, 16, 1
	v_cndmask_b32_e32 v42, 0, v207, vcc
	v_fmac_f32_e32 v42, 0x3e0293ee, v41
	v_exp_f32_e32 v41, v42
	v_cndmask_b32_e32 v42, 0, v208, vcc
	v_ldexp_f32 v41, v41, v42
	v_add_f32_e32 v42, v26, v27
	v_add_f32_e32 v42, v42, v43
	v_add_f32_e32 v43, v38, v39
	v_add_f32_e32 v44, v40, v41
	v_add_f32_e32 v43, v43, v44
	v_add_f32_e32 v42, v42, v43
	v_add_f32_e32 v42, v42, v46
	v_bfe_u32 v43, v41, 16, 1
	v_bfe_u32 v44, v39, 16, 1
	v_bfe_u32 v46, v27, 16, 1
	v_add3_u32 v46, v27, v46, s60
	v_add3_u32 v27, v29, v45, s60
	v_add3_u32 v39, v39, v44, s60
	v_add3_u32 v29, v41, v43, s60
	v_bfe_u32 v43, v28, 16, 1
	v_bfe_u32 v44, v38, 16, 1
	v_bfe_u32 v45, v40, 16, 1
	v_bfe_u32 v41, v26, 16, 1
	v_add3_u32 v40, v40, v45, s60
	v_add3_u32 v38, v38, v44, s60
	v_add3_u32 v28, v28, v43, s60
	v_add3_u32 v26, v26, v41, s60
	v_lshrrev_b32_e32 v41, 16, v28
	v_lshrrev_b32_e32 v28, 16, v38
	v_lshrrev_b32_e32 v38, 16, v40
	v_and_or_b32 v29, v29, s33, v38
	v_mul_f32_e32 v38, 0x3e0293ee, v30
	v_cmp_gt_f32_e32 vcc, s1, v38
	v_and_or_b32 v28, v39, s33, v28
	v_and_or_b32 v27, v27, s33, v41
	v_cndmask_b32_e32 v38, 0, v207, vcc
	v_fmac_f32_e32 v38, 0x3e0293ee, v30
	v_exp_f32_e32 v30, v38
	v_cndmask_b32_e32 v38, 0, v208, vcc
	v_lshrrev_b32_e32 v26, 16, v26
	v_and_or_b32 v26, v46, s33, v26
	v_ldexp_f32 v30, v30, v38
	v_mul_f32_e32 v38, 0x3e0293ee, v34
	v_cmp_gt_f32_e32 vcc, s1, v38
	s_nop 1
	v_cndmask_b32_e32 v38, 0, v207, vcc
	v_fmac_f32_e32 v38, 0x3e0293ee, v34
	v_exp_f32_e32 v34, v38
	v_cndmask_b32_e32 v38, 0, v208, vcc
	v_ldexp_f32 v34, v34, v38
	v_mul_f32_e32 v38, 0x3e0293ee, v31
	v_cmp_gt_f32_e32 vcc, s1, v38
	s_nop 1
	v_cndmask_b32_e32 v38, 0, v207, vcc
	v_fmac_f32_e32 v38, 0x3e0293ee, v31
	v_exp_f32_e32 v31, v38
	v_cndmask_b32_e32 v38, 0, v208, vcc
	v_ldexp_f32 v31, v31, v38
	v_mul_f32_e32 v38, 0x3e0293ee, v35
	v_cmp_gt_f32_e32 vcc, s1, v38
	s_nop 1
	v_cndmask_b32_e32 v38, 0, v207, vcc
	v_fmac_f32_e32 v38, 0x3e0293ee, v35
	v_exp_f32_e32 v35, v38
	v_cndmask_b32_e32 v38, 0, v208, vcc
	v_ldexp_f32 v35, v35, v38
	v_mul_f32_e32 v38, 0x3e0293ee, v32
	v_cmp_gt_f32_e32 vcc, s1, v38
	s_nop 1
	v_cndmask_b32_e32 v38, 0, v207, vcc
	v_fmac_f32_e32 v38, 0x3e0293ee, v32
	v_exp_f32_e32 v32, v38
	v_cndmask_b32_e32 v38, 0, v208, vcc
	v_ldexp_f32 v32, v32, v38
	v_mul_f32_e32 v38, 0x3e0293ee, v36
	v_cmp_gt_f32_e32 vcc, s1, v38
	s_nop 1
	v_cndmask_b32_e32 v38, 0, v207, vcc
	v_fmac_f32_e32 v38, 0x3e0293ee, v36
	v_exp_f32_e32 v36, v38
	v_cndmask_b32_e32 v38, 0, v208, vcc
	v_ldexp_f32 v36, v36, v38
	v_mul_f32_e32 v38, 0x3e0293ee, v33
	v_cmp_gt_f32_e32 vcc, s1, v38
	s_nop 1
	v_cndmask_b32_e32 v38, 0, v207, vcc
	v_fmac_f32_e32 v38, 0x3e0293ee, v33
	v_exp_f32_e32 v33, v38
	v_cndmask_b32_e32 v38, 0, v208, vcc
	v_ldexp_f32 v33, v33, v38
	v_mul_f32_e32 v38, 0x3e0293ee, v37
	v_cmp_gt_f32_e32 vcc, s1, v38
	v_add_f32_e32 v39, v32, v33
	v_bfe_u32 v41, v33, 16, 1
	v_cndmask_b32_e32 v38, 0, v207, vcc
	v_fmac_f32_e32 v38, 0x3e0293ee, v37
	v_exp_f32_e32 v37, v38
	v_cndmask_b32_e32 v38, 0, v208, vcc
	v_ldexp_f32 v37, v37, v38
	v_add_f32_e32 v38, v30, v31
	v_add_f32_e32 v38, v38, v39
	v_add_f32_e32 v39, v34, v35
	v_add_f32_e32 v40, v36, v37
	v_add_f32_e32 v39, v39, v40
	v_add_f32_e32 v38, v38, v39
	v_add_f32_e32 v38, v38, v42
	v_bfe_u32 v39, v37, 16, 1
	v_bfe_u32 v40, v35, 16, 1
	v_bfe_u32 v42, v31, 16, 1
	v_add3_u32 v42, v31, v42, s60
	v_add3_u32 v31, v33, v41, s60
	v_add3_u32 v35, v35, v40, s60
	v_add3_u32 v33, v37, v39, s60
	v_bfe_u32 v39, v32, 16, 1
	v_bfe_u32 v40, v34, 16, 1
	v_bfe_u32 v41, v36, 16, 1
	v_bfe_u32 v37, v30, 16, 1
	v_add3_u32 v36, v36, v41, s60
	v_add3_u32 v34, v34, v40, s60
	v_add3_u32 v32, v32, v39, s60
	v_add3_u32 v30, v30, v37, s60
	v_lshrrev_b32_e32 v37, 16, v32
	v_lshrrev_b32_e32 v32, 16, v34
	v_lshrrev_b32_e32 v34, 16, v36
	v_and_or_b32 v33, v33, s33, v34
	ds_bpermute_b32 v34, v66, v38
	v_and_or_b32 v32, v35, s33, v32
	v_and_or_b32 v31, v31, s33, v37
	v_lshrrev_b32_e32 v30, 16, v30
	v_and_or_b32 v30, v42, s33, v30
	s_waitcnt lgkmcnt(0)
	v_add_f32_e32 v34, v38, v34
	ds_bpermute_b32 v35, v67, v34
	s_waitcnt lgkmcnt(0)
	v_add_f32_e32 v34, v34, v35
	v_rcp_f32_e32 v40, v34
	v_lshlrev_b64 v[34:35], 10, v[0:1]
	v_lshl_add_u64 v[34:35], s[16:17], 0, v[34:35]
	v_lshl_add_u64 v[34:35], v[34:35], 0, s[46:47]
	v_lshlrev_b32_e32 v0, 1, v80
	v_lshl_add_u64 v[38:39], v[34:35], 0, v[0:1]
	ds_read_u16 v46, v145
	ds_read_u16 v47, v145 offset:264
	ds_read_u16 v48, v145 offset:528
	ds_read_u16 v49, v145 offset:792
	ds_read_u16 v50, v145 offset:4224
	ds_read_u16 v51, v145 offset:4488
	ds_read_u16 v52, v145 offset:4752
	ds_read_u16 v53, v145 offset:5016
	ds_read_u16 v54, v145 offset:8448
	ds_read_u16 v55, v145 offset:8712
	ds_read_u16 v56, v145 offset:8976
	ds_read_u16 v57, v145 offset:9240
	ds_read_u16 v58, v145 offset:12672
	ds_read_u16 v59, v145 offset:12936
	ds_read_u16 v60, v145 offset:13200
	s_waitcnt lgkmcnt(7)
	ds_read_u16 v61, v145 offset:13464
	v_lshl_or_b32 v62, v47, 16, v46
	v_lshl_or_b32 v63, v49, 16, v48
	v_lshl_or_b32 v64, v51, 16, v50
	v_lshl_or_b32 v65, v53, 16, v52
	s_nop 1
	v_mfma_f32_16x16x32_bf16 v[34:37], v[62:65], v[2:5], 0
	ds_read_u16 v46, v145 offset:16896
	ds_read_u16 v47, v145 offset:17160
	ds_read_u16 v48, v145 offset:17424
	ds_read_u16 v49, v145 offset:17688
	ds_read_u16 v50, v145 offset:21120
	ds_read_u16 v51, v145 offset:21384
	ds_read_u16 v52, v145 offset:21648
	s_waitcnt lgkmcnt(7)
	ds_read_u16 v53, v145 offset:21912
	v_lshl_or_b32 v42, v55, 16, v54
	v_lshl_or_b32 v43, v57, 16, v56
	v_lshl_or_b32 v44, v59, 16, v58
	v_lshl_or_b32 v45, v61, 16, v60
	s_nop 1
	v_mfma_f32_16x16x32_bf16 v[34:37], v[42:45], v[6:9], v[34:37]
	ds_read_u16 v54, v145 offset:25344
	ds_read_u16 v55, v145 offset:25608
	ds_read_u16 v56, v145 offset:25872
	ds_read_u16 v57, v145 offset:26136
	ds_read_u16 v58, v145 offset:29568
	ds_read_u16 v59, v145 offset:29832
	ds_read_u16 v60, v145 offset:30096
	s_waitcnt lgkmcnt(7)
	ds_read_u16 v61, v145 offset:30360
	v_lshl_or_b32 v62, v47, 16, v46
	v_lshl_or_b32 v63, v49, 16, v48
	v_lshl_or_b32 v64, v51, 16, v50
	v_lshl_or_b32 v65, v53, 16, v52
	s_nop 1
	v_mfma_f32_16x16x32_bf16 v[34:37], v[62:65], v[10:13], v[34:37]
	ds_read_u16 v46, v145 offset:33792
	ds_read_u16 v47, v145 offset:34056
	ds_read_u16 v48, v145 offset:34320
	ds_read_u16 v49, v145 offset:34584
	ds_read_u16 v50, v145 offset:38016
	ds_read_u16 v51, v145 offset:38280
	ds_read_u16 v52, v145 offset:38544
	s_waitcnt lgkmcnt(7)
	ds_read_u16 v53, v145 offset:38808
	v_lshl_or_b32 v42, v55, 16, v54
	v_lshl_or_b32 v43, v57, 16, v56
	v_lshl_or_b32 v44, v59, 16, v58
	v_lshl_or_b32 v45, v61, 16, v60
	s_nop 1
	v_mfma_f32_16x16x32_bf16 v[34:37], v[42:45], v[14:17], v[34:37]
	ds_read_u16 v54, v145 offset:42240
	ds_read_u16 v55, v145 offset:42504
	ds_read_u16 v56, v145 offset:42768
	ds_read_u16 v57, v145 offset:43032
	ds_read_u16 v58, v145 offset:46464
	ds_read_u16 v59, v145 offset:46728
	ds_read_u16 v60, v145 offset:46992
	s_waitcnt lgkmcnt(7)
	ds_read_u16 v61, v145 offset:47256
	v_lshl_or_b32 v62, v47, 16, v46
	v_lshl_or_b32 v63, v49, 16, v48
	v_lshl_or_b32 v64, v51, 16, v50
	v_lshl_or_b32 v65, v53, 16, v52
	s_nop 1
	v_mfma_f32_16x16x32_bf16 v[34:37], v[62:65], v[18:21], v[34:37]
	ds_read_u16 v46, v145 offset:50688
	ds_read_u16 v47, v145 offset:50952
	ds_read_u16 v48, v145 offset:51216
	ds_read_u16 v49, v145 offset:51480
	ds_read_u16 v50, v145 offset:54912
	ds_read_u16 v51, v145 offset:55176
	ds_read_u16 v52, v145 offset:55440
	s_waitcnt lgkmcnt(7)
	ds_read_u16 v53, v145 offset:55704
	v_lshl_or_b32 v42, v55, 16, v54
	v_lshl_or_b32 v43, v57, 16, v56
	v_lshl_or_b32 v44, v59, 16, v58
	v_lshl_or_b32 v45, v61, 16, v60
	s_nop 1
	v_mfma_f32_16x16x32_bf16 v[34:37], v[42:45], v[22:25], v[34:37]
	ds_read_u16 v54, v145 offset:59136
	ds_read_u16 v55, v145 offset:59400
	ds_read_u16 v56, v145 offset:59664
	ds_read_u16 v57, v145 offset:59928
	ds_read_u16 v58, v145 offset:63360
	ds_read_u16 v59, v145 offset:63624
	ds_read_u16 v60, v145 offset:63888
	s_waitcnt lgkmcnt(7)
	ds_read_u16 v61, v145 offset:64152
	v_lshl_or_b32 v62, v47, 16, v46
	v_lshl_or_b32 v63, v49, 16, v48
	v_lshl_or_b32 v64, v51, 16, v50
	v_lshl_or_b32 v65, v53, 16, v52
	s_nop 1
	v_mfma_f32_16x16x32_bf16 v[34:37], v[62:65], v[26:29], v[34:37]
	ds_read_u16 v46, v145 offset:32
	ds_read_u16 v47, v145 offset:296
	ds_read_u16 v48, v145 offset:560
	ds_read_u16 v49, v145 offset:824
	ds_read_u16 v50, v145 offset:4256
	ds_read_u16 v51, v145 offset:4520
	ds_read_u16 v52, v145 offset:4784
	s_waitcnt lgkmcnt(7)
	ds_read_u16 v53, v145 offset:5048
	v_lshl_or_b32 v42, v55, 16, v54
	v_lshl_or_b32 v43, v57, 16, v56
	v_lshl_or_b32 v44, v59, 16, v58
	v_lshl_or_b32 v45, v61, 16, v60
	s_nop 1
	v_mfma_f32_16x16x32_bf16 v[34:37], v[42:45], v[30:33], v[34:37]
	s_and_saveexec_b64 s[24:25], s[6:7]
	s_cbranch_execz .LBB0_100
	s_nop 5
	v_mov_b32_e32 v43, v36
	v_mov_b32_e32 v36, v35
	v_mov_b32_e32 v42, v34
	v_pk_mul_f32 v[34:35], v[40:41], v[36:37] op_sel_hi:[0,1]
	v_pk_mul_f32 v[42:43], v[40:41], v[42:43] op_sel_hi:[0,1]
	v_and_b32_sdwa v37, v35, v202 dst_sel:DWORD dst_unused:UNUSED_PAD src0_sel:WORD_1 src1_sel:DWORD
	v_and_b32_sdwa v41, v34, v202 dst_sel:DWORD dst_unused:UNUSED_PAD src0_sel:WORD_1 src1_sel:DWORD
	v_and_b32_sdwa v0, v43, v202 dst_sel:DWORD dst_unused:UNUSED_PAD src0_sel:WORD_1 src1_sel:DWORD
	v_and_b32_sdwa v36, v42, v202 dst_sel:DWORD dst_unused:UNUSED_PAD src0_sel:WORD_1 src1_sel:DWORD
	v_add3_u32 v35, v35, v37, s60
	v_add3_u32 v34, v34, v41, s60
	v_add3_u32 v36, v42, v36, s60
	v_add3_u32 v0, v43, v0, s60
	v_and_b32_e32 v35, 0xffff0000, v35
	v_and_b32_e32 v34, 0xffff0000, v34
	v_or_b32_sdwa v35, v35, v0 dst_sel:DWORD dst_unused:UNUSED_PAD src0_sel:DWORD src1_sel:WORD_1
	v_or_b32_sdwa v34, v34, v36 dst_sel:DWORD dst_unused:UNUSED_PAD src0_sel:DWORD src1_sel:WORD_1
	global_store_dwordx2 v[38:39], v[34:35], off
.LBB0_100:
	s_or_b64 exec, exec, s[24:25]
	ds_read_u16 v54, v145 offset:8480
	ds_read_u16 v55, v145 offset:8744
	ds_read_u16 v56, v145 offset:9008
	ds_read_u16 v57, v145 offset:9272
	ds_read_u16 v58, v145 offset:12704
	ds_read_u16 v59, v145 offset:12968
	ds_read_u16 v60, v145 offset:13232
	s_waitcnt lgkmcnt(7)
	ds_read_u16 v61, v145 offset:13496
	v_lshl_or_b32 v62, v47, 16, v46
	v_lshl_or_b32 v63, v49, 16, v48
	v_lshl_or_b32 v64, v51, 16, v50
	v_lshl_or_b32 v65, v53, 16, v52
	s_nop 1
	v_mfma_f32_16x16x32_bf16 v[34:37], v[62:65], v[2:5], 0
	ds_read_u16 v46, v145 offset:16928
	ds_read_u16 v47, v145 offset:17192
	ds_read_u16 v48, v145 offset:17456
	ds_read_u16 v49, v145 offset:17720
	ds_read_u16 v50, v145 offset:21152
	ds_read_u16 v51, v145 offset:21416
	ds_read_u16 v52, v145 offset:21680
	s_waitcnt lgkmcnt(7)
	ds_read_u16 v53, v145 offset:21944
	v_lshl_or_b32 v42, v55, 16, v54
	v_lshl_or_b32 v43, v57, 16, v56
	v_lshl_or_b32 v44, v59, 16, v58
	v_lshl_or_b32 v45, v61, 16, v60
	s_nop 1
	v_mfma_f32_16x16x32_bf16 v[34:37], v[42:45], v[6:9], v[34:37]
	ds_read_u16 v54, v145 offset:25376
	ds_read_u16 v55, v145 offset:25640
	ds_read_u16 v56, v145 offset:25904
	ds_read_u16 v57, v145 offset:26168
	ds_read_u16 v58, v145 offset:29600
	ds_read_u16 v59, v145 offset:29864
	ds_read_u16 v60, v145 offset:30128
	s_waitcnt lgkmcnt(7)
	ds_read_u16 v61, v145 offset:30392
	v_lshl_or_b32 v62, v47, 16, v46
	v_lshl_or_b32 v63, v49, 16, v48
	v_lshl_or_b32 v64, v51, 16, v50
	v_lshl_or_b32 v65, v53, 16, v52
	s_nop 1
	v_mfma_f32_16x16x32_bf16 v[34:37], v[62:65], v[10:13], v[34:37]
	ds_read_u16 v46, v145 offset:33824
	ds_read_u16 v47, v145 offset:34088
	ds_read_u16 v48, v145 offset:34352
	ds_read_u16 v49, v145 offset:34616
	ds_read_u16 v50, v145 offset:38048
	ds_read_u16 v51, v145 offset:38312
	ds_read_u16 v52, v145 offset:38576
	s_waitcnt lgkmcnt(7)
	ds_read_u16 v53, v145 offset:38840
	v_lshl_or_b32 v42, v55, 16, v54
	v_lshl_or_b32 v43, v57, 16, v56
	v_lshl_or_b32 v44, v59, 16, v58
	v_lshl_or_b32 v45, v61, 16, v60
	s_nop 1
	v_mfma_f32_16x16x32_bf16 v[34:37], v[42:45], v[14:17], v[34:37]
	ds_read_u16 v54, v145 offset:42272
	ds_read_u16 v55, v145 offset:42536
	ds_read_u16 v56, v145 offset:42800
	ds_read_u16 v57, v145 offset:43064
	ds_read_u16 v58, v145 offset:46496
	ds_read_u16 v59, v145 offset:46760
	ds_read_u16 v60, v145 offset:47024
	s_waitcnt lgkmcnt(7)
	ds_read_u16 v61, v145 offset:47288
	v_lshl_or_b32 v62, v47, 16, v46
	v_lshl_or_b32 v63, v49, 16, v48
	v_lshl_or_b32 v64, v51, 16, v50
	v_lshl_or_b32 v65, v53, 16, v52
	s_nop 1
	v_mfma_f32_16x16x32_bf16 v[34:37], v[62:65], v[18:21], v[34:37]
	ds_read_u16 v46, v145 offset:50720
	ds_read_u16 v47, v145 offset:50984
	ds_read_u16 v48, v145 offset:51248
	ds_read_u16 v49, v145 offset:51512
	ds_read_u16 v50, v145 offset:54944
	ds_read_u16 v51, v145 offset:55208
	ds_read_u16 v52, v145 offset:55472
	s_waitcnt lgkmcnt(7)
	ds_read_u16 v53, v145 offset:55736
	v_lshl_or_b32 v42, v55, 16, v54
	v_lshl_or_b32 v43, v57, 16, v56
	v_lshl_or_b32 v44, v59, 16, v58
	v_lshl_or_b32 v45, v61, 16, v60
	s_nop 1
	v_mfma_f32_16x16x32_bf16 v[34:37], v[42:45], v[22:25], v[34:37]
	ds_read_u16 v54, v145 offset:59168
	ds_read_u16 v55, v145 offset:59432
	ds_read_u16 v56, v145 offset:59696
	ds_read_u16 v57, v145 offset:59960
	ds_read_u16 v58, v145 offset:63392
	ds_read_u16 v59, v145 offset:63656
	ds_read_u16 v60, v145 offset:63920
	s_waitcnt lgkmcnt(7)
	ds_read_u16 v61, v145 offset:64184
	v_lshl_or_b32 v62, v47, 16, v46
	v_lshl_or_b32 v63, v49, 16, v48
	v_lshl_or_b32 v64, v51, 16, v50
	v_lshl_or_b32 v65, v53, 16, v52
	s_nop 1
	v_mfma_f32_16x16x32_bf16 v[34:37], v[62:65], v[26:29], v[34:37]
	ds_read_u16 v46, v145 offset:64
	ds_read_u16 v47, v145 offset:328
	ds_read_u16 v48, v145 offset:592
	ds_read_u16 v49, v145 offset:856
	ds_read_u16 v50, v145 offset:4288
	ds_read_u16 v51, v145 offset:4552
	ds_read_u16 v52, v145 offset:4816
	s_waitcnt lgkmcnt(7)
	ds_read_u16 v53, v145 offset:5080
	v_lshl_or_b32 v42, v55, 16, v54
	v_lshl_or_b32 v43, v57, 16, v56
	v_lshl_or_b32 v44, v59, 16, v58
	v_lshl_or_b32 v45, v61, 16, v60
	s_nop 1
	v_mfma_f32_16x16x32_bf16 v[34:37], v[42:45], v[30:33], v[34:37]
	s_and_saveexec_b64 s[24:25], s[6:7]
	s_cbranch_execz .LBB0_102
	s_nop 5
	v_mov_b32_e32 v43, v36
	v_mov_b32_e32 v36, v35
	v_mov_b32_e32 v42, v34
	v_pk_mul_f32 v[34:35], v[40:41], v[36:37] op_sel_hi:[0,1]
	v_pk_mul_f32 v[42:43], v[40:41], v[42:43] op_sel_hi:[0,1]
	v_and_b32_sdwa v37, v35, v202 dst_sel:DWORD dst_unused:UNUSED_PAD src0_sel:WORD_1 src1_sel:DWORD
	v_and_b32_sdwa v41, v34, v202 dst_sel:DWORD dst_unused:UNUSED_PAD src0_sel:WORD_1 src1_sel:DWORD
	v_and_b32_sdwa v0, v43, v202 dst_sel:DWORD dst_unused:UNUSED_PAD src0_sel:WORD_1 src1_sel:DWORD
	v_and_b32_sdwa v36, v42, v202 dst_sel:DWORD dst_unused:UNUSED_PAD src0_sel:WORD_1 src1_sel:DWORD
	v_add3_u32 v35, v35, v37, s60
	v_add3_u32 v34, v34, v41, s60
	v_add3_u32 v36, v42, v36, s60
	v_add3_u32 v0, v43, v0, s60
	v_and_b32_e32 v35, 0xffff0000, v35
	v_and_b32_e32 v34, 0xffff0000, v34
	v_or_b32_sdwa v35, v35, v0 dst_sel:DWORD dst_unused:UNUSED_PAD src0_sel:DWORD src1_sel:WORD_1
	v_or_b32_sdwa v34, v34, v36 dst_sel:DWORD dst_unused:UNUSED_PAD src0_sel:DWORD src1_sel:WORD_1
	global_store_dwordx2 v[38:39], v[34:35], off offset:32
.LBB0_102:
	s_or_b64 exec, exec, s[24:25]
	ds_read_u16 v54, v145 offset:8512
	ds_read_u16 v55, v145 offset:8776
	ds_read_u16 v56, v145 offset:9040
	ds_read_u16 v57, v145 offset:9304
	ds_read_u16 v58, v145 offset:12736
	ds_read_u16 v59, v145 offset:13000
	ds_read_u16 v60, v145 offset:13264
	s_waitcnt lgkmcnt(7)
	ds_read_u16 v61, v145 offset:13528
	v_lshl_or_b32 v62, v47, 16, v46
	v_lshl_or_b32 v63, v49, 16, v48
	v_lshl_or_b32 v64, v51, 16, v50
	v_lshl_or_b32 v65, v53, 16, v52
	s_nop 1
	v_mfma_f32_16x16x32_bf16 v[34:37], v[62:65], v[2:5], 0
	ds_read_u16 v46, v145 offset:16960
	ds_read_u16 v47, v145 offset:17224
	ds_read_u16 v48, v145 offset:17488
	ds_read_u16 v49, v145 offset:17752
	ds_read_u16 v50, v145 offset:21184
	ds_read_u16 v51, v145 offset:21448
	ds_read_u16 v52, v145 offset:21712
	s_waitcnt lgkmcnt(7)
	ds_read_u16 v53, v145 offset:21976
	v_lshl_or_b32 v42, v55, 16, v54
	v_lshl_or_b32 v43, v57, 16, v56
	v_lshl_or_b32 v44, v59, 16, v58
	v_lshl_or_b32 v45, v61, 16, v60
	s_nop 1
	v_mfma_f32_16x16x32_bf16 v[34:37], v[42:45], v[6:9], v[34:37]
	ds_read_u16 v54, v145 offset:25408
	ds_read_u16 v55, v145 offset:25672
	ds_read_u16 v56, v145 offset:25936
	ds_read_u16 v57, v145 offset:26200
	ds_read_u16 v58, v145 offset:29632
	ds_read_u16 v59, v145 offset:29896
	ds_read_u16 v60, v145 offset:30160
	s_waitcnt lgkmcnt(7)
	ds_read_u16 v61, v145 offset:30424
	v_lshl_or_b32 v62, v47, 16, v46
	v_lshl_or_b32 v63, v49, 16, v48
	v_lshl_or_b32 v64, v51, 16, v50
	v_lshl_or_b32 v65, v53, 16, v52
	s_nop 1
	v_mfma_f32_16x16x32_bf16 v[34:37], v[62:65], v[10:13], v[34:37]
	ds_read_u16 v46, v145 offset:33856
	ds_read_u16 v47, v145 offset:34120
	ds_read_u16 v48, v145 offset:34384
	ds_read_u16 v49, v145 offset:34648
	ds_read_u16 v50, v145 offset:38080
	ds_read_u16 v51, v145 offset:38344
	ds_read_u16 v52, v145 offset:38608
	s_waitcnt lgkmcnt(7)
	ds_read_u16 v53, v145 offset:38872
	v_lshl_or_b32 v42, v55, 16, v54
	v_lshl_or_b32 v43, v57, 16, v56
	v_lshl_or_b32 v44, v59, 16, v58
	v_lshl_or_b32 v45, v61, 16, v60
	s_nop 1
	v_mfma_f32_16x16x32_bf16 v[34:37], v[42:45], v[14:17], v[34:37]
	ds_read_u16 v54, v145 offset:42304
	ds_read_u16 v55, v145 offset:42568
	ds_read_u16 v56, v145 offset:42832
	ds_read_u16 v57, v145 offset:43096
	ds_read_u16 v58, v145 offset:46528
	ds_read_u16 v59, v145 offset:46792
	ds_read_u16 v60, v145 offset:47056
	s_waitcnt lgkmcnt(7)
	ds_read_u16 v61, v145 offset:47320
	v_lshl_or_b32 v62, v47, 16, v46
	v_lshl_or_b32 v63, v49, 16, v48
	v_lshl_or_b32 v64, v51, 16, v50
	v_lshl_or_b32 v65, v53, 16, v52
	s_nop 1
	v_mfma_f32_16x16x32_bf16 v[34:37], v[62:65], v[18:21], v[34:37]
	ds_read_u16 v46, v145 offset:50752
	ds_read_u16 v47, v145 offset:51016
	ds_read_u16 v48, v145 offset:51280
	ds_read_u16 v49, v145 offset:51544
	ds_read_u16 v50, v145 offset:54976
	ds_read_u16 v51, v145 offset:55240
	ds_read_u16 v52, v145 offset:55504
	s_waitcnt lgkmcnt(7)
	ds_read_u16 v53, v145 offset:55768
	v_lshl_or_b32 v42, v55, 16, v54
	v_lshl_or_b32 v43, v57, 16, v56
	v_lshl_or_b32 v44, v59, 16, v58
	v_lshl_or_b32 v45, v61, 16, v60
	s_nop 1
	v_mfma_f32_16x16x32_bf16 v[34:37], v[42:45], v[22:25], v[34:37]
	ds_read_u16 v54, v145 offset:59200
	ds_read_u16 v55, v145 offset:59464
	ds_read_u16 v56, v145 offset:59728
	ds_read_u16 v57, v145 offset:59992
	ds_read_u16 v58, v145 offset:63424
	ds_read_u16 v59, v145 offset:63688
	ds_read_u16 v60, v145 offset:63952
	s_waitcnt lgkmcnt(7)
	ds_read_u16 v61, v145 offset:64216
	v_lshl_or_b32 v62, v47, 16, v46
	v_lshl_or_b32 v63, v49, 16, v48
	v_lshl_or_b32 v64, v51, 16, v50
	v_lshl_or_b32 v65, v53, 16, v52
	s_nop 1
	v_mfma_f32_16x16x32_bf16 v[34:37], v[62:65], v[26:29], v[34:37]
	ds_read_u16 v46, v145 offset:96
	ds_read_u16 v47, v145 offset:360
	ds_read_u16 v48, v145 offset:624
	ds_read_u16 v49, v145 offset:888
	ds_read_u16 v50, v145 offset:4320
	ds_read_u16 v51, v145 offset:4584
	ds_read_u16 v52, v145 offset:4848
	s_waitcnt lgkmcnt(7)
	ds_read_u16 v53, v145 offset:5112
	v_lshl_or_b32 v42, v55, 16, v54
	v_lshl_or_b32 v43, v57, 16, v56
	v_lshl_or_b32 v44, v59, 16, v58
	v_lshl_or_b32 v45, v61, 16, v60
	s_nop 1
	v_mfma_f32_16x16x32_bf16 v[34:37], v[42:45], v[30:33], v[34:37]
	s_and_saveexec_b64 s[24:25], s[6:7]
	s_cbranch_execz .LBB0_104
	s_nop 5
	v_mov_b32_e32 v43, v36
	v_mov_b32_e32 v36, v35
	v_mov_b32_e32 v42, v34
	v_pk_mul_f32 v[34:35], v[40:41], v[36:37] op_sel_hi:[0,1]
	v_pk_mul_f32 v[42:43], v[40:41], v[42:43] op_sel_hi:[0,1]
	v_and_b32_sdwa v37, v35, v202 dst_sel:DWORD dst_unused:UNUSED_PAD src0_sel:WORD_1 src1_sel:DWORD
	v_and_b32_sdwa v41, v34, v202 dst_sel:DWORD dst_unused:UNUSED_PAD src0_sel:WORD_1 src1_sel:DWORD
	v_and_b32_sdwa v0, v43, v202 dst_sel:DWORD dst_unused:UNUSED_PAD src0_sel:WORD_1 src1_sel:DWORD
	v_and_b32_sdwa v36, v42, v202 dst_sel:DWORD dst_unused:UNUSED_PAD src0_sel:WORD_1 src1_sel:DWORD
	v_add3_u32 v35, v35, v37, s60
	v_add3_u32 v34, v34, v41, s60
	v_add3_u32 v36, v42, v36, s60
	v_add3_u32 v0, v43, v0, s60
	v_and_b32_e32 v35, 0xffff0000, v35
	v_and_b32_e32 v34, 0xffff0000, v34
	v_or_b32_sdwa v35, v35, v0 dst_sel:DWORD dst_unused:UNUSED_PAD src0_sel:DWORD src1_sel:WORD_1
	v_or_b32_sdwa v34, v34, v36 dst_sel:DWORD dst_unused:UNUSED_PAD src0_sel:DWORD src1_sel:WORD_1
	global_store_dwordx2 v[38:39], v[34:35], off offset:64
.LBB0_104:
	s_or_b64 exec, exec, s[24:25]
	ds_read_u16 v54, v145 offset:8544
	ds_read_u16 v55, v145 offset:8808
	ds_read_u16 v56, v145 offset:9072
	ds_read_u16 v57, v145 offset:9336
	ds_read_u16 v58, v145 offset:12768
	ds_read_u16 v59, v145 offset:13032
	ds_read_u16 v60, v145 offset:13296
	s_waitcnt lgkmcnt(7)
	ds_read_u16 v61, v145 offset:13560
	v_lshl_or_b32 v62, v47, 16, v46
	v_lshl_or_b32 v63, v49, 16, v48
	v_lshl_or_b32 v64, v51, 16, v50
	v_lshl_or_b32 v65, v53, 16, v52
	s_nop 1
	v_mfma_f32_16x16x32_bf16 v[34:37], v[62:65], v[2:5], 0
	ds_read_u16 v46, v145 offset:16992
	ds_read_u16 v47, v145 offset:17256
	ds_read_u16 v48, v145 offset:17520
	ds_read_u16 v49, v145 offset:17784
	ds_read_u16 v50, v145 offset:21216
	ds_read_u16 v51, v145 offset:21480
	ds_read_u16 v52, v145 offset:21744
	s_waitcnt lgkmcnt(7)
	ds_read_u16 v53, v145 offset:22008
	v_lshl_or_b32 v42, v55, 16, v54
	v_lshl_or_b32 v43, v57, 16, v56
	v_lshl_or_b32 v44, v59, 16, v58
	v_lshl_or_b32 v45, v61, 16, v60
	s_nop 1
	v_mfma_f32_16x16x32_bf16 v[34:37], v[42:45], v[6:9], v[34:37]
	ds_read_u16 v54, v145 offset:25440
	ds_read_u16 v55, v145 offset:25704
	ds_read_u16 v56, v145 offset:25968
	ds_read_u16 v57, v145 offset:26232
	ds_read_u16 v58, v145 offset:29664
	ds_read_u16 v59, v145 offset:29928
	ds_read_u16 v60, v145 offset:30192
	s_waitcnt lgkmcnt(7)
	ds_read_u16 v61, v145 offset:30456
	v_lshl_or_b32 v62, v47, 16, v46
	v_lshl_or_b32 v63, v49, 16, v48
	v_lshl_or_b32 v64, v51, 16, v50
	v_lshl_or_b32 v65, v53, 16, v52
	s_nop 1
	v_mfma_f32_16x16x32_bf16 v[34:37], v[62:65], v[10:13], v[34:37]
	ds_read_u16 v46, v145 offset:33888
	ds_read_u16 v47, v145 offset:34152
	ds_read_u16 v48, v145 offset:34416
	ds_read_u16 v49, v145 offset:34680
	ds_read_u16 v50, v145 offset:38112
	ds_read_u16 v51, v145 offset:38376
	ds_read_u16 v52, v145 offset:38640
	s_waitcnt lgkmcnt(7)
	ds_read_u16 v53, v145 offset:38904
	v_lshl_or_b32 v42, v55, 16, v54
	v_lshl_or_b32 v43, v57, 16, v56
	v_lshl_or_b32 v44, v59, 16, v58
	v_lshl_or_b32 v45, v61, 16, v60
	s_nop 1
	v_mfma_f32_16x16x32_bf16 v[34:37], v[42:45], v[14:17], v[34:37]
	ds_read_u16 v54, v145 offset:42336
	ds_read_u16 v55, v145 offset:42600
	ds_read_u16 v56, v145 offset:42864
	ds_read_u16 v57, v145 offset:43128
	ds_read_u16 v58, v145 offset:46560
	ds_read_u16 v59, v145 offset:46824
	ds_read_u16 v60, v145 offset:47088
	s_waitcnt lgkmcnt(7)
	ds_read_u16 v61, v145 offset:47352
	v_lshl_or_b32 v62, v47, 16, v46
	v_lshl_or_b32 v63, v49, 16, v48
	v_lshl_or_b32 v64, v51, 16, v50
	v_lshl_or_b32 v65, v53, 16, v52
	s_nop 1
	v_mfma_f32_16x16x32_bf16 v[34:37], v[62:65], v[18:21], v[34:37]
	ds_read_u16 v46, v145 offset:50784
	ds_read_u16 v47, v145 offset:51048
	ds_read_u16 v48, v145 offset:51312
	ds_read_u16 v49, v145 offset:51576
	ds_read_u16 v50, v145 offset:55008
	ds_read_u16 v51, v145 offset:55272
	ds_read_u16 v52, v145 offset:55536
	s_waitcnt lgkmcnt(7)
	ds_read_u16 v53, v145 offset:55800
	v_lshl_or_b32 v42, v55, 16, v54
	v_lshl_or_b32 v43, v57, 16, v56
	v_lshl_or_b32 v44, v59, 16, v58
	v_lshl_or_b32 v45, v61, 16, v60
	s_nop 1
	v_mfma_f32_16x16x32_bf16 v[34:37], v[42:45], v[22:25], v[34:37]
	ds_read_u16 v54, v145 offset:59232
	ds_read_u16 v55, v145 offset:59496
	ds_read_u16 v56, v145 offset:59760
	ds_read_u16 v57, v145 offset:60024
	ds_read_u16 v58, v145 offset:63456
	ds_read_u16 v59, v145 offset:63720
	ds_read_u16 v60, v145 offset:63984
	s_waitcnt lgkmcnt(7)
	ds_read_u16 v61, v145 offset:64248
	v_lshl_or_b32 v62, v47, 16, v46
	v_lshl_or_b32 v63, v49, 16, v48
	v_lshl_or_b32 v64, v51, 16, v50
	v_lshl_or_b32 v65, v53, 16, v52
	s_nop 1
	v_mfma_f32_16x16x32_bf16 v[34:37], v[62:65], v[26:29], v[34:37]
	ds_read_u16 v46, v145 offset:128
	ds_read_u16 v47, v145 offset:392
	ds_read_u16 v48, v145 offset:656
	ds_read_u16 v49, v145 offset:920
	ds_read_u16 v50, v145 offset:4352
	ds_read_u16 v51, v145 offset:4616
	ds_read_u16 v52, v145 offset:4880
	s_waitcnt lgkmcnt(7)
	ds_read_u16 v53, v145 offset:5144
	v_lshl_or_b32 v42, v55, 16, v54
	v_lshl_or_b32 v43, v57, 16, v56
	v_lshl_or_b32 v44, v59, 16, v58
	v_lshl_or_b32 v45, v61, 16, v60
	s_nop 1
	v_mfma_f32_16x16x32_bf16 v[34:37], v[42:45], v[30:33], v[34:37]
	s_and_saveexec_b64 s[24:25], s[6:7]
	s_cbranch_execz .LBB0_106
	s_nop 5
	v_mov_b32_e32 v43, v36
	v_mov_b32_e32 v36, v35
	v_mov_b32_e32 v42, v34
	v_pk_mul_f32 v[34:35], v[40:41], v[36:37] op_sel_hi:[0,1]
	v_pk_mul_f32 v[42:43], v[40:41], v[42:43] op_sel_hi:[0,1]
	v_and_b32_sdwa v37, v35, v202 dst_sel:DWORD dst_unused:UNUSED_PAD src0_sel:WORD_1 src1_sel:DWORD
	v_and_b32_sdwa v41, v34, v202 dst_sel:DWORD dst_unused:UNUSED_PAD src0_sel:WORD_1 src1_sel:DWORD
	v_and_b32_sdwa v0, v43, v202 dst_sel:DWORD dst_unused:UNUSED_PAD src0_sel:WORD_1 src1_sel:DWORD
	v_and_b32_sdwa v36, v42, v202 dst_sel:DWORD dst_unused:UNUSED_PAD src0_sel:WORD_1 src1_sel:DWORD
	v_add3_u32 v35, v35, v37, s60
	v_add3_u32 v34, v34, v41, s60
	v_add3_u32 v36, v42, v36, s60
	v_add3_u32 v0, v43, v0, s60
	v_and_b32_e32 v35, 0xffff0000, v35
	v_and_b32_e32 v34, 0xffff0000, v34
	v_or_b32_sdwa v35, v35, v0 dst_sel:DWORD dst_unused:UNUSED_PAD src0_sel:DWORD src1_sel:WORD_1
	v_or_b32_sdwa v34, v34, v36 dst_sel:DWORD dst_unused:UNUSED_PAD src0_sel:DWORD src1_sel:WORD_1
	global_store_dwordx2 v[38:39], v[34:35], off offset:96
.LBB0_106:
	s_or_b64 exec, exec, s[24:25]
	ds_read_u16 v54, v145 offset:8576
	ds_read_u16 v55, v145 offset:8840
	ds_read_u16 v56, v145 offset:9104
	ds_read_u16 v57, v145 offset:9368
	ds_read_u16 v58, v145 offset:12800
	ds_read_u16 v59, v145 offset:13064
	ds_read_u16 v60, v145 offset:13328
	s_waitcnt lgkmcnt(7)
	ds_read_u16 v61, v145 offset:13592
	v_lshl_or_b32 v62, v47, 16, v46
	v_lshl_or_b32 v63, v49, 16, v48
	v_lshl_or_b32 v64, v51, 16, v50
	v_lshl_or_b32 v65, v53, 16, v52
	s_nop 1
	v_mfma_f32_16x16x32_bf16 v[34:37], v[62:65], v[2:5], 0
	ds_read_u16 v46, v145 offset:17024
	ds_read_u16 v47, v145 offset:17288
	ds_read_u16 v48, v145 offset:17552
	ds_read_u16 v49, v145 offset:17816
	ds_read_u16 v50, v145 offset:21248
	ds_read_u16 v51, v145 offset:21512
	ds_read_u16 v52, v145 offset:21776
	s_waitcnt lgkmcnt(7)
	ds_read_u16 v53, v145 offset:22040
	v_lshl_or_b32 v42, v55, 16, v54
	v_lshl_or_b32 v43, v57, 16, v56
	v_lshl_or_b32 v44, v59, 16, v58
	v_lshl_or_b32 v45, v61, 16, v60
	s_nop 1
	v_mfma_f32_16x16x32_bf16 v[34:37], v[42:45], v[6:9], v[34:37]
	ds_read_u16 v54, v145 offset:25472
	ds_read_u16 v55, v145 offset:25736
	ds_read_u16 v56, v145 offset:26000
	ds_read_u16 v57, v145 offset:26264
	ds_read_u16 v58, v145 offset:29696
	ds_read_u16 v59, v145 offset:29960
	ds_read_u16 v60, v145 offset:30224
	s_waitcnt lgkmcnt(7)
	ds_read_u16 v61, v145 offset:30488
	v_lshl_or_b32 v62, v47, 16, v46
	v_lshl_or_b32 v63, v49, 16, v48
	v_lshl_or_b32 v64, v51, 16, v50
	v_lshl_or_b32 v65, v53, 16, v52
	s_nop 1
	v_mfma_f32_16x16x32_bf16 v[34:37], v[62:65], v[10:13], v[34:37]
	ds_read_u16 v46, v145 offset:33920
	ds_read_u16 v47, v145 offset:34184
	ds_read_u16 v48, v145 offset:34448
	ds_read_u16 v49, v145 offset:34712
	ds_read_u16 v50, v145 offset:38144
	ds_read_u16 v51, v145 offset:38408
	ds_read_u16 v52, v145 offset:38672
	s_waitcnt lgkmcnt(7)
	ds_read_u16 v53, v145 offset:38936
	v_lshl_or_b32 v42, v55, 16, v54
	v_lshl_or_b32 v43, v57, 16, v56
	v_lshl_or_b32 v44, v59, 16, v58
	v_lshl_or_b32 v45, v61, 16, v60
	s_nop 1
	v_mfma_f32_16x16x32_bf16 v[34:37], v[42:45], v[14:17], v[34:37]
	ds_read_u16 v54, v145 offset:42368
	ds_read_u16 v55, v145 offset:42632
	ds_read_u16 v56, v145 offset:42896
	ds_read_u16 v57, v145 offset:43160
	ds_read_u16 v58, v145 offset:46592
	ds_read_u16 v59, v145 offset:46856
	ds_read_u16 v60, v145 offset:47120
	s_waitcnt lgkmcnt(7)
	ds_read_u16 v61, v145 offset:47384
	v_lshl_or_b32 v62, v47, 16, v46
	v_lshl_or_b32 v63, v49, 16, v48
	v_lshl_or_b32 v64, v51, 16, v50
	v_lshl_or_b32 v65, v53, 16, v52
	s_nop 1
	v_mfma_f32_16x16x32_bf16 v[34:37], v[62:65], v[18:21], v[34:37]
	ds_read_u16 v46, v145 offset:50816
	ds_read_u16 v47, v145 offset:51080
	ds_read_u16 v48, v145 offset:51344
	ds_read_u16 v49, v145 offset:51608
	ds_read_u16 v50, v145 offset:55040
	ds_read_u16 v51, v145 offset:55304
	ds_read_u16 v52, v145 offset:55568
	s_waitcnt lgkmcnt(7)
	ds_read_u16 v53, v145 offset:55832
	v_lshl_or_b32 v42, v55, 16, v54
	v_lshl_or_b32 v43, v57, 16, v56
	v_lshl_or_b32 v44, v59, 16, v58
	v_lshl_or_b32 v45, v61, 16, v60
	s_nop 1
	v_mfma_f32_16x16x32_bf16 v[34:37], v[42:45], v[22:25], v[34:37]
	ds_read_u16 v54, v145 offset:59264
	ds_read_u16 v55, v145 offset:59528
	ds_read_u16 v56, v145 offset:59792
	ds_read_u16 v57, v145 offset:60056
	ds_read_u16 v58, v145 offset:63488
	ds_read_u16 v59, v145 offset:63752
	ds_read_u16 v60, v145 offset:64016
	s_waitcnt lgkmcnt(7)
	ds_read_u16 v61, v145 offset:64280
	v_lshl_or_b32 v62, v47, 16, v46
	v_lshl_or_b32 v63, v49, 16, v48
	v_lshl_or_b32 v64, v51, 16, v50
	v_lshl_or_b32 v65, v53, 16, v52
	s_nop 1
	v_mfma_f32_16x16x32_bf16 v[34:37], v[62:65], v[26:29], v[34:37]
	ds_read_u16 v46, v145 offset:160
	ds_read_u16 v47, v145 offset:424
	ds_read_u16 v48, v145 offset:688
	ds_read_u16 v49, v145 offset:952
	ds_read_u16 v50, v145 offset:4384
	ds_read_u16 v51, v145 offset:4648
	ds_read_u16 v52, v145 offset:4912
	s_waitcnt lgkmcnt(7)
	ds_read_u16 v53, v145 offset:5176
	v_lshl_or_b32 v42, v55, 16, v54
	v_lshl_or_b32 v43, v57, 16, v56
	v_lshl_or_b32 v44, v59, 16, v58
	v_lshl_or_b32 v45, v61, 16, v60
	s_nop 1
	v_mfma_f32_16x16x32_bf16 v[34:37], v[42:45], v[30:33], v[34:37]
	s_and_saveexec_b64 s[24:25], s[6:7]
	s_cbranch_execz .LBB0_108
	s_nop 5
	v_mov_b32_e32 v43, v36
	v_mov_b32_e32 v36, v35
	v_mov_b32_e32 v42, v34
	v_pk_mul_f32 v[34:35], v[40:41], v[36:37] op_sel_hi:[0,1]
	v_pk_mul_f32 v[42:43], v[40:41], v[42:43] op_sel_hi:[0,1]
	v_and_b32_sdwa v37, v35, v202 dst_sel:DWORD dst_unused:UNUSED_PAD src0_sel:WORD_1 src1_sel:DWORD
	v_and_b32_sdwa v41, v34, v202 dst_sel:DWORD dst_unused:UNUSED_PAD src0_sel:WORD_1 src1_sel:DWORD
	v_and_b32_sdwa v0, v43, v202 dst_sel:DWORD dst_unused:UNUSED_PAD src0_sel:WORD_1 src1_sel:DWORD
	v_and_b32_sdwa v36, v42, v202 dst_sel:DWORD dst_unused:UNUSED_PAD src0_sel:WORD_1 src1_sel:DWORD
	v_add3_u32 v35, v35, v37, s60
	v_add3_u32 v34, v34, v41, s60
	v_add3_u32 v36, v42, v36, s60
	v_add3_u32 v0, v43, v0, s60
	v_and_b32_e32 v35, 0xffff0000, v35
	v_and_b32_e32 v34, 0xffff0000, v34
	v_or_b32_sdwa v35, v35, v0 dst_sel:DWORD dst_unused:UNUSED_PAD src0_sel:DWORD src1_sel:WORD_1
	v_or_b32_sdwa v34, v34, v36 dst_sel:DWORD dst_unused:UNUSED_PAD src0_sel:DWORD src1_sel:WORD_1
	global_store_dwordx2 v[38:39], v[34:35], off offset:128
.LBB0_108:
	s_or_b64 exec, exec, s[24:25]
	ds_read_u16 v54, v145 offset:8608
	ds_read_u16 v55, v145 offset:8872
	ds_read_u16 v56, v145 offset:9136
	ds_read_u16 v57, v145 offset:9400
	ds_read_u16 v58, v145 offset:12832
	ds_read_u16 v59, v145 offset:13096
	ds_read_u16 v60, v145 offset:13360
	s_waitcnt lgkmcnt(7)
	ds_read_u16 v61, v145 offset:13624
	v_lshl_or_b32 v62, v47, 16, v46
	v_lshl_or_b32 v63, v49, 16, v48
	v_lshl_or_b32 v64, v51, 16, v50
	v_lshl_or_b32 v65, v53, 16, v52
	s_nop 1
	v_mfma_f32_16x16x32_bf16 v[34:37], v[62:65], v[2:5], 0
	ds_read_u16 v46, v145 offset:17056
	ds_read_u16 v47, v145 offset:17320
	ds_read_u16 v48, v145 offset:17584
	ds_read_u16 v49, v145 offset:17848
	ds_read_u16 v50, v145 offset:21280
	ds_read_u16 v51, v145 offset:21544
	ds_read_u16 v52, v145 offset:21808
	s_waitcnt lgkmcnt(7)
	ds_read_u16 v53, v145 offset:22072
	v_lshl_or_b32 v42, v55, 16, v54
	v_lshl_or_b32 v43, v57, 16, v56
	v_lshl_or_b32 v44, v59, 16, v58
	v_lshl_or_b32 v45, v61, 16, v60
	s_nop 1
	v_mfma_f32_16x16x32_bf16 v[34:37], v[42:45], v[6:9], v[34:37]
	ds_read_u16 v54, v145 offset:25504
	ds_read_u16 v55, v145 offset:25768
	ds_read_u16 v56, v145 offset:26032
	ds_read_u16 v57, v145 offset:26296
	ds_read_u16 v58, v145 offset:29728
	ds_read_u16 v59, v145 offset:29992
	ds_read_u16 v60, v145 offset:30256
	s_waitcnt lgkmcnt(7)
	ds_read_u16 v61, v145 offset:30520
	v_lshl_or_b32 v62, v47, 16, v46
	v_lshl_or_b32 v63, v49, 16, v48
	v_lshl_or_b32 v64, v51, 16, v50
	v_lshl_or_b32 v65, v53, 16, v52
	s_nop 1
	v_mfma_f32_16x16x32_bf16 v[34:37], v[62:65], v[10:13], v[34:37]
	ds_read_u16 v46, v145 offset:33952
	ds_read_u16 v47, v145 offset:34216
	ds_read_u16 v48, v145 offset:34480
	ds_read_u16 v49, v145 offset:34744
	ds_read_u16 v50, v145 offset:38176
	ds_read_u16 v51, v145 offset:38440
	ds_read_u16 v52, v145 offset:38704
	s_waitcnt lgkmcnt(7)
	ds_read_u16 v53, v145 offset:38968
	v_lshl_or_b32 v42, v55, 16, v54
	v_lshl_or_b32 v43, v57, 16, v56
	v_lshl_or_b32 v44, v59, 16, v58
	v_lshl_or_b32 v45, v61, 16, v60
	s_nop 1
	v_mfma_f32_16x16x32_bf16 v[34:37], v[42:45], v[14:17], v[34:37]
	ds_read_u16 v54, v145 offset:42400
	ds_read_u16 v55, v145 offset:42664
	ds_read_u16 v56, v145 offset:42928
	ds_read_u16 v57, v145 offset:43192
	ds_read_u16 v58, v145 offset:46624
	ds_read_u16 v59, v145 offset:46888
	ds_read_u16 v60, v145 offset:47152
	s_waitcnt lgkmcnt(7)
	ds_read_u16 v61, v145 offset:47416
	v_lshl_or_b32 v62, v47, 16, v46
	v_lshl_or_b32 v63, v49, 16, v48
	v_lshl_or_b32 v64, v51, 16, v50
	v_lshl_or_b32 v65, v53, 16, v52
	s_nop 1
	v_mfma_f32_16x16x32_bf16 v[34:37], v[62:65], v[18:21], v[34:37]
	ds_read_u16 v46, v145 offset:50848
	ds_read_u16 v47, v145 offset:51112
	ds_read_u16 v48, v145 offset:51376
	ds_read_u16 v49, v145 offset:51640
	ds_read_u16 v50, v145 offset:55072
	ds_read_u16 v51, v145 offset:55336
	ds_read_u16 v52, v145 offset:55600
	s_waitcnt lgkmcnt(7)
	ds_read_u16 v53, v145 offset:55864
	v_lshl_or_b32 v42, v55, 16, v54
	v_lshl_or_b32 v43, v57, 16, v56
	v_lshl_or_b32 v44, v59, 16, v58
	v_lshl_or_b32 v45, v61, 16, v60
	s_nop 1
	v_mfma_f32_16x16x32_bf16 v[34:37], v[42:45], v[22:25], v[34:37]
	ds_read_u16 v54, v145 offset:59296
	ds_read_u16 v55, v145 offset:59560
	ds_read_u16 v56, v145 offset:59824
	ds_read_u16 v57, v145 offset:60088
	ds_read_u16 v58, v145 offset:63520
	ds_read_u16 v59, v145 offset:63784
	ds_read_u16 v60, v145 offset:64048
	s_waitcnt lgkmcnt(7)
	ds_read_u16 v61, v145 offset:64312
	v_lshl_or_b32 v62, v47, 16, v46
	v_lshl_or_b32 v63, v49, 16, v48
	v_lshl_or_b32 v64, v51, 16, v50
	v_lshl_or_b32 v65, v53, 16, v52
	s_nop 1
	v_mfma_f32_16x16x32_bf16 v[34:37], v[62:65], v[26:29], v[34:37]
	ds_read_u16 v46, v145 offset:192
	ds_read_u16 v47, v145 offset:456
	ds_read_u16 v48, v145 offset:720
	ds_read_u16 v49, v145 offset:984
	ds_read_u16 v50, v145 offset:4416
	ds_read_u16 v51, v145 offset:4680
	ds_read_u16 v52, v145 offset:4944
	s_waitcnt lgkmcnt(7)
	ds_read_u16 v53, v145 offset:5208
	v_lshl_or_b32 v42, v55, 16, v54
	v_lshl_or_b32 v43, v57, 16, v56
	v_lshl_or_b32 v44, v59, 16, v58
	v_lshl_or_b32 v45, v61, 16, v60
	s_nop 1
	v_mfma_f32_16x16x32_bf16 v[34:37], v[42:45], v[30:33], v[34:37]
	s_and_saveexec_b64 s[24:25], s[6:7]
	s_cbranch_execz .LBB0_110
	s_nop 5
	v_mov_b32_e32 v43, v36
	v_mov_b32_e32 v36, v35
	v_mov_b32_e32 v42, v34
	v_pk_mul_f32 v[34:35], v[40:41], v[36:37] op_sel_hi:[0,1]
	v_pk_mul_f32 v[42:43], v[40:41], v[42:43] op_sel_hi:[0,1]
	v_and_b32_sdwa v37, v35, v202 dst_sel:DWORD dst_unused:UNUSED_PAD src0_sel:WORD_1 src1_sel:DWORD
	v_and_b32_sdwa v41, v34, v202 dst_sel:DWORD dst_unused:UNUSED_PAD src0_sel:WORD_1 src1_sel:DWORD
	v_and_b32_sdwa v0, v43, v202 dst_sel:DWORD dst_unused:UNUSED_PAD src0_sel:WORD_1 src1_sel:DWORD
	v_and_b32_sdwa v36, v42, v202 dst_sel:DWORD dst_unused:UNUSED_PAD src0_sel:WORD_1 src1_sel:DWORD
	v_add3_u32 v35, v35, v37, s60
	v_add3_u32 v34, v34, v41, s60
	v_add3_u32 v36, v42, v36, s60
	v_add3_u32 v0, v43, v0, s60
	v_and_b32_e32 v35, 0xffff0000, v35
	v_and_b32_e32 v34, 0xffff0000, v34
	v_or_b32_sdwa v35, v35, v0 dst_sel:DWORD dst_unused:UNUSED_PAD src0_sel:DWORD src1_sel:WORD_1
	v_or_b32_sdwa v34, v34, v36 dst_sel:DWORD dst_unused:UNUSED_PAD src0_sel:DWORD src1_sel:WORD_1
	global_store_dwordx2 v[38:39], v[34:35], off offset:160
.LBB0_110:
	s_or_b64 exec, exec, s[24:25]
	ds_read_u16 v54, v145 offset:8640
	ds_read_u16 v55, v145 offset:8904
	ds_read_u16 v56, v145 offset:9168
	ds_read_u16 v57, v145 offset:9432
	ds_read_u16 v58, v145 offset:12864
	ds_read_u16 v59, v145 offset:13128
	ds_read_u16 v60, v145 offset:13392
	s_waitcnt lgkmcnt(7)
	ds_read_u16 v61, v145 offset:13656
	v_lshl_or_b32 v62, v47, 16, v46
	v_lshl_or_b32 v63, v49, 16, v48
	v_lshl_or_b32 v64, v51, 16, v50
	v_lshl_or_b32 v65, v53, 16, v52
	s_nop 1
	v_mfma_f32_16x16x32_bf16 v[34:37], v[62:65], v[2:5], 0
	ds_read_u16 v46, v145 offset:17088
	ds_read_u16 v47, v145 offset:17352
	ds_read_u16 v48, v145 offset:17616
	ds_read_u16 v49, v145 offset:17880
	ds_read_u16 v50, v145 offset:21312
	ds_read_u16 v51, v145 offset:21576
	ds_read_u16 v52, v145 offset:21840
	s_waitcnt lgkmcnt(7)
	ds_read_u16 v53, v145 offset:22104
	v_lshl_or_b32 v42, v55, 16, v54
	v_lshl_or_b32 v43, v57, 16, v56
	v_lshl_or_b32 v44, v59, 16, v58
	v_lshl_or_b32 v45, v61, 16, v60
	s_nop 1
	v_mfma_f32_16x16x32_bf16 v[34:37], v[42:45], v[6:9], v[34:37]
	ds_read_u16 v54, v145 offset:25536
	ds_read_u16 v55, v145 offset:25800
	ds_read_u16 v56, v145 offset:26064
	ds_read_u16 v57, v145 offset:26328
	ds_read_u16 v58, v145 offset:29760
	ds_read_u16 v59, v145 offset:30024
	ds_read_u16 v60, v145 offset:30288
	s_waitcnt lgkmcnt(7)
	ds_read_u16 v61, v145 offset:30552
	v_lshl_or_b32 v62, v47, 16, v46
	v_lshl_or_b32 v63, v49, 16, v48
	v_lshl_or_b32 v64, v51, 16, v50
	v_lshl_or_b32 v65, v53, 16, v52
	s_nop 1
	v_mfma_f32_16x16x32_bf16 v[34:37], v[62:65], v[10:13], v[34:37]
	ds_read_u16 v46, v145 offset:33984
	ds_read_u16 v47, v145 offset:34248
	ds_read_u16 v48, v145 offset:34512
	ds_read_u16 v49, v145 offset:34776
	ds_read_u16 v50, v145 offset:38208
	ds_read_u16 v51, v145 offset:38472
	ds_read_u16 v52, v145 offset:38736
	s_waitcnt lgkmcnt(7)
	ds_read_u16 v53, v145 offset:39000
	v_lshl_or_b32 v42, v55, 16, v54
	v_lshl_or_b32 v43, v57, 16, v56
	v_lshl_or_b32 v44, v59, 16, v58
	v_lshl_or_b32 v45, v61, 16, v60
	s_nop 1
	v_mfma_f32_16x16x32_bf16 v[34:37], v[42:45], v[14:17], v[34:37]
	ds_read_u16 v54, v145 offset:42432
	ds_read_u16 v55, v145 offset:42696
	ds_read_u16 v56, v145 offset:42960
	ds_read_u16 v57, v145 offset:43224
	ds_read_u16 v58, v145 offset:46656
	ds_read_u16 v59, v145 offset:46920
	ds_read_u16 v60, v145 offset:47184
	s_waitcnt lgkmcnt(7)
	ds_read_u16 v61, v145 offset:47448
	v_lshl_or_b32 v62, v47, 16, v46
	v_lshl_or_b32 v63, v49, 16, v48
	v_lshl_or_b32 v64, v51, 16, v50
	v_lshl_or_b32 v65, v53, 16, v52
	s_nop 1
	v_mfma_f32_16x16x32_bf16 v[34:37], v[62:65], v[18:21], v[34:37]
	ds_read_u16 v46, v145 offset:50880
	ds_read_u16 v47, v145 offset:51144
	ds_read_u16 v48, v145 offset:51408
	ds_read_u16 v49, v145 offset:51672
	ds_read_u16 v50, v145 offset:55104
	ds_read_u16 v51, v145 offset:55368
	ds_read_u16 v52, v145 offset:55632
	s_waitcnt lgkmcnt(7)
	ds_read_u16 v53, v145 offset:55896
	v_lshl_or_b32 v42, v55, 16, v54
	v_lshl_or_b32 v43, v57, 16, v56
	v_lshl_or_b32 v44, v59, 16, v58
	v_lshl_or_b32 v45, v61, 16, v60
	s_nop 1
	v_mfma_f32_16x16x32_bf16 v[34:37], v[42:45], v[22:25], v[34:37]
	ds_read_u16 v54, v145 offset:59328
	ds_read_u16 v55, v145 offset:59592
	ds_read_u16 v56, v145 offset:59856
	ds_read_u16 v57, v145 offset:60120
	ds_read_u16 v58, v145 offset:63552
	ds_read_u16 v59, v145 offset:63816
	ds_read_u16 v60, v145 offset:64080
	s_waitcnt lgkmcnt(7)
	ds_read_u16 v61, v145 offset:64344
	v_lshl_or_b32 v62, v47, 16, v46
	v_lshl_or_b32 v63, v49, 16, v48
	v_lshl_or_b32 v64, v51, 16, v50
	v_lshl_or_b32 v65, v53, 16, v52
	s_nop 1
	v_mfma_f32_16x16x32_bf16 v[34:37], v[62:65], v[26:29], v[34:37]
	ds_read_u16 v46, v145 offset:224
	ds_read_u16 v47, v145 offset:488
	ds_read_u16 v48, v145 offset:752
	ds_read_u16 v49, v145 offset:1016
	ds_read_u16 v50, v145 offset:4448
	ds_read_u16 v51, v145 offset:4712
	ds_read_u16 v52, v145 offset:4976
	s_waitcnt lgkmcnt(7)
	ds_read_u16 v53, v145 offset:5240
	v_lshl_or_b32 v42, v55, 16, v54
	v_lshl_or_b32 v43, v57, 16, v56
	v_lshl_or_b32 v44, v59, 16, v58
	v_lshl_or_b32 v45, v61, 16, v60
	s_nop 1
	v_mfma_f32_16x16x32_bf16 v[34:37], v[42:45], v[30:33], v[34:37]
	s_and_saveexec_b64 s[24:25], s[6:7]
	s_cbranch_execz .LBB0_112
	s_nop 5
	v_mov_b32_e32 v43, v36
	v_mov_b32_e32 v36, v35
	v_mov_b32_e32 v42, v34
	v_pk_mul_f32 v[34:35], v[40:41], v[36:37] op_sel_hi:[0,1]
	v_pk_mul_f32 v[42:43], v[40:41], v[42:43] op_sel_hi:[0,1]
	v_and_b32_sdwa v37, v35, v202 dst_sel:DWORD dst_unused:UNUSED_PAD src0_sel:WORD_1 src1_sel:DWORD
	v_and_b32_sdwa v41, v34, v202 dst_sel:DWORD dst_unused:UNUSED_PAD src0_sel:WORD_1 src1_sel:DWORD
	v_and_b32_sdwa v0, v43, v202 dst_sel:DWORD dst_unused:UNUSED_PAD src0_sel:WORD_1 src1_sel:DWORD
	v_and_b32_sdwa v36, v42, v202 dst_sel:DWORD dst_unused:UNUSED_PAD src0_sel:WORD_1 src1_sel:DWORD
	v_add3_u32 v35, v35, v37, s60
	v_add3_u32 v34, v34, v41, s60
	v_add3_u32 v36, v42, v36, s60
	v_add3_u32 v0, v43, v0, s60
	v_and_b32_e32 v35, 0xffff0000, v35
	v_and_b32_e32 v34, 0xffff0000, v34
	v_or_b32_sdwa v35, v35, v0 dst_sel:DWORD dst_unused:UNUSED_PAD src0_sel:DWORD src1_sel:WORD_1
	v_or_b32_sdwa v34, v34, v36 dst_sel:DWORD dst_unused:UNUSED_PAD src0_sel:DWORD src1_sel:WORD_1
	global_store_dwordx2 v[38:39], v[34:35], off offset:192
.LBB0_112:
	s_or_b64 exec, exec, s[24:25]
	ds_read_u16 v54, v145 offset:8672
	ds_read_u16 v55, v145 offset:8936
	ds_read_u16 v56, v145 offset:9200
	ds_read_u16 v57, v145 offset:9464
	ds_read_u16 v58, v145 offset:12896
	ds_read_u16 v59, v145 offset:13160
	ds_read_u16 v60, v145 offset:13424
	s_waitcnt lgkmcnt(7)
	ds_read_u16 v61, v145 offset:13688
	v_lshl_or_b32 v62, v47, 16, v46
	v_lshl_or_b32 v63, v49, 16, v48
	v_lshl_or_b32 v64, v51, 16, v50
	v_lshl_or_b32 v65, v53, 16, v52
	s_nop 1
	v_mfma_f32_16x16x32_bf16 v[2:5], v[62:65], v[2:5], 0
	ds_read_u16 v46, v145 offset:17120
	ds_read_u16 v47, v145 offset:17384
	ds_read_u16 v48, v145 offset:17648
	ds_read_u16 v49, v145 offset:17912
	ds_read_u16 v50, v145 offset:21344
	ds_read_u16 v51, v145 offset:21608
	ds_read_u16 v52, v145 offset:21872
	s_waitcnt lgkmcnt(7)
	ds_read_u16 v53, v145 offset:22136
	v_lshl_or_b32 v42, v55, 16, v54
	v_lshl_or_b32 v43, v57, 16, v56
	v_lshl_or_b32 v44, v59, 16, v58
	v_lshl_or_b32 v45, v61, 16, v60
	s_nop 1
	v_mfma_f32_16x16x32_bf16 v[2:5], v[42:45], v[6:9], v[2:5]
	ds_read_u16 v54, v145 offset:25568
	ds_read_u16 v55, v145 offset:25832
	ds_read_u16 v56, v145 offset:26096
	ds_read_u16 v57, v145 offset:26360
	ds_read_u16 v58, v145 offset:29792
	ds_read_u16 v59, v145 offset:30056
	ds_read_u16 v60, v145 offset:30320
	s_waitcnt lgkmcnt(7)
	ds_read_u16 v61, v145 offset:30584
	v_lshl_or_b32 v62, v47, 16, v46
	v_lshl_or_b32 v63, v49, 16, v48
	v_lshl_or_b32 v64, v51, 16, v50
	v_lshl_or_b32 v65, v53, 16, v52
	s_nop 1
	v_mfma_f32_16x16x32_bf16 v[2:5], v[62:65], v[10:13], v[2:5]
	ds_read_u16 v46, v145 offset:34016
	ds_read_u16 v47, v145 offset:34280
	ds_read_u16 v48, v145 offset:34544
	ds_read_u16 v49, v145 offset:34808
	ds_read_u16 v50, v145 offset:38240
	ds_read_u16 v51, v145 offset:38504
	ds_read_u16 v52, v145 offset:38768
	s_waitcnt lgkmcnt(7)
	ds_read_u16 v53, v145 offset:39032
	v_lshl_or_b32 v42, v55, 16, v54
	v_lshl_or_b32 v43, v57, 16, v56
	v_lshl_or_b32 v44, v59, 16, v58
	v_lshl_or_b32 v45, v61, 16, v60
	s_nop 1
	v_mfma_f32_16x16x32_bf16 v[2:5], v[42:45], v[14:17], v[2:5]
	ds_read_u16 v54, v145 offset:42464
	ds_read_u16 v55, v145 offset:42728
	ds_read_u16 v56, v145 offset:42992
	ds_read_u16 v57, v145 offset:43256
	ds_read_u16 v58, v145 offset:46688
	ds_read_u16 v59, v145 offset:46952
	ds_read_u16 v60, v145 offset:47216
	s_waitcnt lgkmcnt(7)
	ds_read_u16 v61, v145 offset:47480
	v_lshl_or_b32 v62, v47, 16, v46
	v_lshl_or_b32 v63, v49, 16, v48
	v_lshl_or_b32 v64, v51, 16, v50
	v_lshl_or_b32 v65, v53, 16, v52
	s_nop 1
	v_mfma_f32_16x16x32_bf16 v[2:5], v[62:65], v[18:21], v[2:5]
	ds_read_u16 v46, v145 offset:50912
	ds_read_u16 v47, v145 offset:51176
	ds_read_u16 v48, v145 offset:51440
	ds_read_u16 v49, v145 offset:51704
	ds_read_u16 v50, v145 offset:55136
	ds_read_u16 v51, v145 offset:55400
	ds_read_u16 v52, v145 offset:55664
	s_waitcnt lgkmcnt(7)
	ds_read_u16 v53, v145 offset:55928
	v_lshl_or_b32 v42, v55, 16, v54
	v_lshl_or_b32 v43, v57, 16, v56
	v_lshl_or_b32 v44, v59, 16, v58
	v_lshl_or_b32 v45, v61, 16, v60
	s_nop 1
	v_mfma_f32_16x16x32_bf16 v[2:5], v[42:45], v[22:25], v[2:5]
	ds_read_u16 v54, v145 offset:59360
	ds_read_u16 v55, v145 offset:59624
	ds_read_u16 v56, v145 offset:59888
	ds_read_u16 v57, v145 offset:60152
	ds_read_u16 v58, v145 offset:63584
	ds_read_u16 v59, v145 offset:63848
	ds_read_u16 v60, v145 offset:64112
	s_waitcnt lgkmcnt(7)
	ds_read_u16 v61, v145 offset:64376
	v_lshl_or_b32 v62, v47, 16, v46
	v_lshl_or_b32 v63, v49, 16, v48
	v_lshl_or_b32 v64, v51, 16, v50
	v_lshl_or_b32 v65, v53, 16, v52
	s_nop 1
	v_mfma_f32_16x16x32_bf16 v[2:5], v[62:65], v[26:29], v[2:5]
	s_waitcnt lgkmcnt(0)
	v_lshl_or_b32 v42, v55, 16, v54
	v_lshl_or_b32 v43, v57, 16, v56
	v_lshl_or_b32 v44, v59, 16, v58
	v_lshl_or_b32 v45, v61, 16, v60
	s_nop 1
	v_mfma_f32_16x16x32_bf16 v[2:5], v[42:45], v[30:33], v[2:5]
	s_and_saveexec_b64 s[24:25], s[6:7]
	s_cbranch_execz .LBB0_114
	s_nop 5
	v_mov_b32_e32 v6, v2
	v_mov_b32_e32 v7, v4
	v_pk_mul_f32 v[6:7], v[40:41], v[6:7] op_sel_hi:[0,1]
	v_mov_b32_e32 v4, v3
	v_pk_mul_f32 v[2:3], v[40:41], v[4:5] op_sel_hi:[0,1]
	v_and_b32_sdwa v4, v6, v202 dst_sel:DWORD dst_unused:UNUSED_PAD src0_sel:WORD_1 src1_sel:DWORD
	v_add3_u32 v4, v6, v4, s60
	v_and_b32_sdwa v5, v3, v202 dst_sel:DWORD dst_unused:UNUSED_PAD src0_sel:WORD_1 src1_sel:DWORD
	v_and_b32_sdwa v6, v2, v202 dst_sel:DWORD dst_unused:UNUSED_PAD src0_sel:WORD_1 src1_sel:DWORD
	v_and_b32_sdwa v0, v7, v202 dst_sel:DWORD dst_unused:UNUSED_PAD src0_sel:WORD_1 src1_sel:DWORD
	v_add3_u32 v3, v3, v5, s60
	v_add3_u32 v2, v2, v6, s60
	v_add3_u32 v0, v7, v0, s60
	v_and_b32_e32 v3, 0xffff0000, v3
	v_and_b32_e32 v2, 0xffff0000, v2
	v_or_b32_sdwa v3, v3, v0 dst_sel:DWORD dst_unused:UNUSED_PAD src0_sel:DWORD src1_sel:WORD_1
	v_or_b32_sdwa v2, v2, v4 dst_sel:DWORD dst_unused:UNUSED_PAD src0_sel:DWORD src1_sel:WORD_1
	global_store_dwordx2 v[38:39], v[2:3], off offset:224

.LBB0_125:
	s_or_b64 exec, exec, s[24:25]
	s_waitcnt vmcnt(0)
	v_bfe_u32 v0, v30, 16, 1
	v_add3_u32 v0, v30, v0, s60
	v_bfe_u32 v30, v31, 16, 1
	v_lshrrev_b32_e32 v0, 16, v0
	v_add3_u32 v30, v31, v30, s60
	v_and_or_b32 v34, v30, s33, v0
	v_bfe_u32 v0, v32, 16, 1
	v_add3_u32 v0, v32, v0, s60
	v_bfe_u32 v30, v33, 16, 1
	v_lshrrev_b32_e32 v0, 16, v0
	v_add3_u32 v30, v33, v30, s60
	v_and_or_b32 v35, v30, s33, v0
	v_bfe_u32 v0, v26, 16, 1
	v_add3_u32 v0, v26, v0, s60
	v_bfe_u32 v26, v27, 16, 1
	v_lshrrev_b32_e32 v0, 16, v0
	v_add3_u32 v26, v27, v26, s60
	v_and_or_b32 v36, v26, s33, v0
	v_bfe_u32 v0, v28, 16, 1
	v_add3_u32 v0, v28, v0, s60
	v_bfe_u32 v26, v29, 16, 1
	v_lshrrev_b32_e32 v0, 16, v0
	v_add3_u32 v26, v29, v26, s60
	v_and_or_b32 v37, v26, s33, v0
	v_bfe_u32 v0, v18, 16, 1
	v_add3_u32 v0, v18, v0, s60
	v_bfe_u32 v18, v19, 16, 1
	v_lshrrev_b32_e32 v0, 16, v0
	v_add3_u32 v18, v19, v18, s60
	v_and_or_b32 v66, v18, s33, v0
	v_bfe_u32 v0, v20, 16, 1
	v_add3_u32 v0, v20, v0, s60
	v_bfe_u32 v18, v21, 16, 1
	v_lshrrev_b32_e32 v0, 16, v0
	v_add3_u32 v18, v21, v18, s60
	v_and_or_b32 v67, v18, s33, v0
	v_bfe_u32 v0, v10, 16, 1
	v_add3_u32 v0, v10, v0, s60
	v_bfe_u32 v10, v11, 16, 1
	v_lshrrev_b32_e32 v0, 16, v0
	v_add3_u32 v10, v11, v10, s60
	v_and_or_b32 v68, v10, s33, v0
	v_bfe_u32 v0, v12, 16, 1
	v_add3_u32 v0, v12, v0, s60
	v_bfe_u32 v10, v13, 16, 1
	v_lshrrev_b32_e32 v0, 16, v0
	v_add3_u32 v10, v13, v10, s60
	v_and_or_b32 v69, v10, s33, v0
	v_bfe_u32 v0, v6, 16, 1
	v_add3_u32 v0, v6, v0, s60
	v_bfe_u32 v6, v7, 16, 1
	v_lshrrev_b32_e32 v0, 16, v0
	v_add3_u32 v6, v7, v6, s60
	v_and_or_b32 v70, v6, s33, v0
	v_bfe_u32 v0, v8, 16, 1
	v_add3_u32 v0, v8, v0, s60
	v_bfe_u32 v6, v9, 16, 1
	v_lshrrev_b32_e32 v0, 16, v0
	v_add3_u32 v6, v9, v6, s60
	v_and_or_b32 v71, v6, s33, v0
	v_bfe_u32 v0, v2, 16, 1
	v_add3_u32 v0, v2, v0, s60
	v_bfe_u32 v2, v3, 16, 1
	v_lshrrev_b32_e32 v0, 16, v0
	v_add3_u32 v2, v3, v2, s60
	v_and_or_b32 v72, v2, s33, v0
	v_bfe_u32 v0, v4, 16, 1
	v_add3_u32 v0, v4, v0, s60
	v_bfe_u32 v2, v5, 16, 1
	v_lshrrev_b32_e32 v0, 16, v0
	v_add3_u32 v2, v5, v2, s60
	v_and_or_b32 v73, v2, s33, v0
	v_bfe_u32 v0, v22, 16, 1
	v_add3_u32 v0, v22, v0, s60
	v_bfe_u32 v2, v23, 16, 1
	v_lshrrev_b32_e32 v0, 16, v0
	v_add3_u32 v2, v23, v2, s60
	v_and_or_b32 v74, v2, s33, v0
	v_bfe_u32 v0, v24, 16, 1
	v_add3_u32 v0, v24, v0, s60
	v_bfe_u32 v2, v25, 16, 1
	v_lshrrev_b32_e32 v0, 16, v0
	v_add3_u32 v2, v25, v2, s60
	v_and_or_b32 v75, v2, s33, v0
	v_bfe_u32 v0, v14, 16, 1
	v_add3_u32 v0, v14, v0, s60
	v_bfe_u32 v2, v15, 16, 1
	v_lshrrev_b32_e32 v0, 16, v0
	v_add3_u32 v2, v15, v2, s60
	v_and_or_b32 v76, v2, s33, v0
	v_bfe_u32 v0, v16, 16, 1
	v_add3_u32 v0, v16, v0, s60
	v_bfe_u32 v2, v17, 16, 1
	v_lshrrev_b32_e32 v0, 16, v0
	v_add3_u32 v2, v17, v2, s60
	v_and_or_b32 v77, v2, s33, v0
	ds_read_b128 v[2:5], v140
	ds_read_b128 v[6:9], v140 offset:64
	s_waitcnt lgkmcnt(1)
	v_mfma_f32_16x16x32_bf16 v[2:5], v[2:5], v[70:73], 0
	ds_read_b128 v[10:13], v140 offset:4416
	v_add_u32_e32 v0, v137, v141
	s_mov_b32 s1, 0xff61b1e6
	s_waitcnt lgkmcnt(1)
	v_mfma_f32_16x16x32_bf16 v[2:5], v[6:9], v[66:69], v[2:5]
	ds_read_b128 v[6:9], v140 offset:128
	s_lshl_b32 s46, s0, 1
	ds_read_b128 v[14:17], v0 offset:64
	s_waitcnt lgkmcnt(1)
	v_mfma_f32_16x16x32_bf16 v[2:5], v[6:9], v[34:37], v[2:5]
	ds_read_b128 v[6:9], v140 offset:192
	ds_read_b128 v[26:29], v140 offset:39232
	ds_read_b128 v[18:21], v140 offset:21824
	s_waitcnt lgkmcnt(2)
	v_mfma_f32_16x16x32_bf16 v[2:5], v[6:9], v[74:77], v[2:5]
	ds_read_b128 v[6:9], v140 offset:4352
	ds_read_b128 v[38:41], v140 offset:56640
	ds_read_b128 v[166:169], v140 offset:60992
	s_waitcnt lgkmcnt(2)
	v_mfma_f32_16x16x32_bf16 v[6:9], v[6:9], v[70:73], 0
	v_mfma_f32_16x16x32_bf16 v[6:9], v[10:13], v[66:69], v[6:9]
	ds_read_b128 v[10:13], v140 offset:4480
	s_waitcnt lgkmcnt(0)
	v_mfma_f32_16x16x32_bf16 v[6:9], v[10:13], v[34:37], v[6:9]
	ds_read_b128 v[10:13], v140 offset:4544
	s_waitcnt lgkmcnt(0)
	v_mfma_f32_16x16x32_bf16 v[62:65], v[10:13], v[74:77], v[6:9]
	s_nop 4
	ds_read_b128 v[6:9], v140 offset:8704
	ds_read_b128 v[10:13], v140 offset:8768
	s_waitcnt lgkmcnt(1)
	v_mfma_f32_16x16x32_bf16 v[6:9], v[6:9], v[70:73], 0
	s_waitcnt lgkmcnt(0)
	v_mfma_f32_16x16x32_bf16 v[6:9], v[10:13], v[66:69], v[6:9]
	ds_read_b128 v[10:13], v140 offset:8832
	s_waitcnt lgkmcnt(0)
	v_mfma_f32_16x16x32_bf16 v[6:9], v[10:13], v[34:37], v[6:9]
	ds_read_b128 v[10:13], v140 offset:8896
	s_waitcnt lgkmcnt(0)
	v_mfma_f32_16x16x32_bf16 v[6:9], v[10:13], v[74:77], v[6:9]
	ds_read_b128 v[10:13], v0
	s_waitcnt lgkmcnt(0)
	v_mfma_f32_16x16x32_bf16 v[10:13], v[10:13], v[70:73], 0
	v_mfma_f32_16x16x32_bf16 v[10:13], v[14:17], v[66:69], v[10:13]
	ds_read_b128 v[14:17], v0 offset:128
	s_waitcnt lgkmcnt(0)
	v_mfma_f32_16x16x32_bf16 v[10:13], v[14:17], v[34:37], v[10:13]
	ds_read_b128 v[14:17], v0 offset:192
	v_add_u32_e32 v0, v137, v142
	ds_read_b128 v[22:25], v0 offset:64
	s_waitcnt lgkmcnt(1)
	v_mfma_f32_16x16x32_bf16 v[58:61], v[14:17], v[74:77], v[10:13]
	s_nop 2
	ds_read_b128 v[10:13], v140 offset:17408
	ds_read_b128 v[14:17], v140 offset:17472
	s_waitcnt lgkmcnt(1)
	v_mfma_f32_16x16x32_bf16 v[10:13], v[10:13], v[70:73], 0
	s_waitcnt lgkmcnt(0)
	v_mfma_f32_16x16x32_bf16 v[10:13], v[14:17], v[66:69], v[10:13]
	ds_read_b128 v[14:17], v140 offset:17536
	s_waitcnt lgkmcnt(0)
	v_mfma_f32_16x16x32_bf16 v[10:13], v[14:17], v[34:37], v[10:13]
	ds_read_b128 v[14:17], v140 offset:17600
	s_waitcnt lgkmcnt(0)
	v_mfma_f32_16x16x32_bf16 v[10:13], v[14:17], v[74:77], v[10:13]
	ds_read_b128 v[14:17], v140 offset:21760
	s_waitcnt lgkmcnt(0)
	v_mfma_f32_16x16x32_bf16 v[14:17], v[14:17], v[70:73], 0
	v_mfma_f32_16x16x32_bf16 v[14:17], v[18:21], v[66:69], v[14:17]
	ds_read_b128 v[18:21], v140 offset:21888
	s_waitcnt lgkmcnt(0)
	v_mfma_f32_16x16x32_bf16 v[14:17], v[18:21], v[34:37], v[14:17]
	ds_read_b128 v[18:21], v140 offset:21952
	s_waitcnt lgkmcnt(0)
	v_mfma_f32_16x16x32_bf16 v[54:57], v[18:21], v[74:77], v[14:17]
	s_nop 4
	ds_read_b128 v[14:17], v140 offset:26112
	ds_read_b128 v[18:21], v140 offset:26176
	s_waitcnt lgkmcnt(1)
	v_mfma_f32_16x16x32_bf16 v[14:17], v[14:17], v[70:73], 0
	s_waitcnt lgkmcnt(0)
	v_mfma_f32_16x16x32_bf16 v[14:17], v[18:21], v[66:69], v[14:17]
	ds_read_b128 v[18:21], v140 offset:26240
	s_waitcnt lgkmcnt(0)
	v_mfma_f32_16x16x32_bf16 v[14:17], v[18:21], v[34:37], v[14:17]
	ds_read_b128 v[18:21], v140 offset:26304
	s_waitcnt lgkmcnt(0)
	v_mfma_f32_16x16x32_bf16 v[14:17], v[18:21], v[74:77], v[14:17]
	ds_read_b128 v[18:21], v0
	s_waitcnt lgkmcnt(0)
	v_mfma_f32_16x16x32_bf16 v[18:21], v[18:21], v[70:73], 0
	v_mfma_f32_16x16x32_bf16 v[18:21], v[22:25], v[66:69], v[18:21]
	ds_read_b128 v[22:25], v0 offset:128
	s_waitcnt lgkmcnt(0)
	v_mfma_f32_16x16x32_bf16 v[18:21], v[22:25], v[34:37], v[18:21]
	ds_read_b128 v[22:25], v0 offset:192
	v_add_u32_e32 v0, v137, v143
	ds_read_b128 v[30:33], v0 offset:64
	s_waitcnt lgkmcnt(1)
	v_mfma_f32_16x16x32_bf16 v[50:53], v[22:25], v[74:77], v[18:21]
	s_nop 2
	ds_read_b128 v[18:21], v140 offset:34816
	ds_read_b128 v[22:25], v140 offset:34880
	s_waitcnt lgkmcnt(1)
	v_mfma_f32_16x16x32_bf16 v[18:21], v[18:21], v[70:73], 0
	s_waitcnt lgkmcnt(0)
	v_mfma_f32_16x16x32_bf16 v[18:21], v[22:25], v[66:69], v[18:21]
	ds_read_b128 v[22:25], v140 offset:34944
	s_waitcnt lgkmcnt(0)
	v_mfma_f32_16x16x32_bf16 v[18:21], v[22:25], v[34:37], v[18:21]
	ds_read_b128 v[22:25], v140 offset:35008
	s_waitcnt lgkmcnt(0)
	v_mfma_f32_16x16x32_bf16 v[18:21], v[22:25], v[74:77], v[18:21]
	ds_read_b128 v[22:25], v140 offset:39168
	s_waitcnt lgkmcnt(0)
	v_mfma_f32_16x16x32_bf16 v[22:25], v[22:25], v[70:73], 0
	v_mfma_f32_16x16x32_bf16 v[22:25], v[26:29], v[66:69], v[22:25]
	ds_read_b128 v[26:29], v140 offset:39296
	s_waitcnt lgkmcnt(0)
	v_mfma_f32_16x16x32_bf16 v[22:25], v[26:29], v[34:37], v[22:25]
	ds_read_b128 v[26:29], v140 offset:39360
	s_waitcnt lgkmcnt(0)
	v_mfma_f32_16x16x32_bf16 v[46:49], v[26:29], v[74:77], v[22:25]
	s_nop 4
	ds_read_b128 v[22:25], v140 offset:43520
	ds_read_b128 v[26:29], v140 offset:43584
	s_waitcnt lgkmcnt(1)
	v_mfma_f32_16x16x32_bf16 v[22:25], v[22:25], v[70:73], 0
	s_waitcnt lgkmcnt(0)
	v_mfma_f32_16x16x32_bf16 v[22:25], v[26:29], v[66:69], v[22:25]
	ds_read_b128 v[26:29], v140 offset:43648
	s_waitcnt lgkmcnt(0)
	v_mfma_f32_16x16x32_bf16 v[22:25], v[26:29], v[34:37], v[22:25]
	ds_read_b128 v[26:29], v140 offset:43712
	s_waitcnt lgkmcnt(0)
	v_mfma_f32_16x16x32_bf16 v[22:25], v[26:29], v[74:77], v[22:25]
	ds_read_b128 v[26:29], v0
	s_waitcnt lgkmcnt(0)
	v_mfma_f32_16x16x32_bf16 v[26:29], v[26:29], v[70:73], 0
	v_mfma_f32_16x16x32_bf16 v[26:29], v[30:33], v[66:69], v[26:29]
	ds_read_b128 v[30:33], v0 offset:128
	s_waitcnt lgkmcnt(0)
	v_mfma_f32_16x16x32_bf16 v[26:29], v[30:33], v[34:37], v[26:29]
	ds_read_b128 v[30:33], v0 offset:192
	v_add_u32_e32 v0, v137, v144
	s_waitcnt lgkmcnt(0)
	v_mfma_f32_16x16x32_bf16 v[42:45], v[30:33], v[74:77], v[26:29]
	s_nop 3
	ds_read_b128 v[26:29], v140 offset:52224
	ds_read_b128 v[30:33], v140 offset:52288
	s_waitcnt lgkmcnt(1)
	v_mfma_f32_16x16x32_bf16 v[26:29], v[26:29], v[70:73], 0
	s_waitcnt lgkmcnt(0)
	v_mfma_f32_16x16x32_bf16 v[26:29], v[30:33], v[66:69], v[26:29]
	ds_read_b128 v[30:33], v140 offset:52352
	s_waitcnt lgkmcnt(0)
	v_mfma_f32_16x16x32_bf16 v[26:29], v[30:33], v[34:37], v[26:29]
	ds_read_b128 v[30:33], v140 offset:52416
	s_waitcnt lgkmcnt(0)
	v_mfma_f32_16x16x32_bf16 v[26:29], v[30:33], v[74:77], v[26:29]
	ds_read_b128 v[30:33], v140 offset:56576
	s_waitcnt lgkmcnt(0)
	v_mfma_f32_16x16x32_bf16 v[30:33], v[30:33], v[70:73], 0
	v_mfma_f32_16x16x32_bf16 v[30:33], v[38:41], v[66:69], v[30:33]
	ds_read_b128 v[38:41], v140 offset:56704
	s_waitcnt lgkmcnt(0)
	v_mfma_f32_16x16x32_bf16 v[30:33], v[38:41], v[34:37], v[30:33]
	ds_read_b128 v[38:41], v140 offset:56768
	s_waitcnt lgkmcnt(0)
	v_mfma_f32_16x16x32_bf16 v[38:41], v[38:41], v[74:77], v[30:33]
	s_nop 4
	ds_read_b128 v[30:33], v140 offset:60928
	s_waitcnt lgkmcnt(0)
	v_mfma_f32_16x16x32_bf16 v[30:33], v[30:33], v[70:73], 0
	v_mfma_f32_16x16x32_bf16 v[30:33], v[166:169], v[66:69], v[30:33]
	ds_read_b128 v[166:169], v140 offset:61056
	s_waitcnt lgkmcnt(0)
	v_mfma_f32_16x16x32_bf16 v[30:33], v[166:169], v[34:37], v[30:33]
	ds_read_b128 v[166:169], v140 offset:61120
	s_waitcnt lgkmcnt(0)
	v_mfma_f32_16x16x32_bf16 v[30:33], v[166:169], v[74:77], v[30:33]
	ds_read_b128 v[166:169], v0
	s_waitcnt lgkmcnt(0)
	v_mfma_f32_16x16x32_bf16 v[70:73], v[166:169], v[70:73], 0
	ds_read_b128 v[166:169], v0 offset:64
	s_waitcnt lgkmcnt(0)
	v_mfma_f32_16x16x32_bf16 v[66:69], v[166:169], v[66:69], v[70:73]
	s_nop 4
	ds_read_b128 v[70:73], v0 offset:128
	s_waitcnt lgkmcnt(0)
	v_mfma_f32_16x16x32_bf16 v[34:37], v[70:73], v[34:37], v[66:69]
	s_nop 2
	ds_read_b128 v[66:69], v0 offset:192
	v_max_f32_e32 v0, v5, v5
	s_waitcnt lgkmcnt(0)
	v_mfma_f32_16x16x32_bf16 v[34:37], v[66:69], v[74:77], v[34:37]
	v_max_f32_e32 v66, v4, v4
	v_max_f32_e32 v0, v66, v0
	v_max_f32_e32 v66, v65, v65
	v_max_f32_e32 v67, v64, v64
	v_max_f32_e32 v66, v67, v66
	v_max3_f32 v0, v2, v3, v0
	v_max3_f32 v66, v62, v63, v66
	v_max3_f32 v0, v0, s1, v66
	v_max_f32_e32 v66, v9, v9
	v_max_f32_e32 v67, v8, v8
	v_max_f32_e32 v66, v67, v66
	v_max_f32_e32 v67, v61, v61
	v_max_f32_e32 v68, v60, v60
	v_max_f32_e32 v67, v68, v67
	v_max3_f32 v66, v6, v7, v66
	v_max3_f32 v67, v58, v59, v67
	v_max3_f32 v0, v0, v66, v67
	v_max_f32_e32 v66, v13, v13
	v_max_f32_e32 v67, v12, v12
	v_max_f32_e32 v66, v67, v66
	v_max_f32_e32 v67, v57, v57
	v_max_f32_e32 v68, v56, v56
	v_max_f32_e32 v67, v68, v67
	v_max3_f32 v66, v10, v11, v66
	v_max3_f32 v67, v54, v55, v67
	v_max3_f32 v0, v0, v66, v67
	v_max_f32_e32 v66, v17, v17
	v_max_f32_e32 v67, v16, v16
	v_max_f32_e32 v66, v67, v66
	v_max_f32_e32 v67, v53, v53
	v_max_f32_e32 v68, v52, v52
	v_max_f32_e32 v67, v68, v67
	v_max3_f32 v66, v14, v15, v66
	v_max3_f32 v67, v50, v51, v67
	v_max3_f32 v0, v0, v66, v67
	v_max_f32_e32 v66, v21, v21
	v_max_f32_e32 v67, v20, v20
	v_max_f32_e32 v66, v67, v66
	v_max_f32_e32 v67, v49, v49
	v_max_f32_e32 v68, v48, v48
	v_max_f32_e32 v67, v68, v67
	v_max3_f32 v66, v18, v19, v66
	v_max3_f32 v67, v46, v47, v67
	v_max3_f32 v0, v0, v66, v67
	v_max_f32_e32 v66, v25, v25
	v_max_f32_e32 v67, v24, v24
	v_max_f32_e32 v66, v67, v66
	v_max_f32_e32 v67, v45, v45
	v_max_f32_e32 v68, v44, v44
	v_max_f32_e32 v67, v68, v67
	v_max3_f32 v66, v22, v23, v66
	v_max3_f32 v67, v42, v43, v67
	v_max3_f32 v0, v0, v66, v67
	v_max_f32_e32 v66, v29, v29
	v_max_f32_e32 v67, v28, v28
	v_max_f32_e32 v66, v67, v66
	v_max_f32_e32 v67, v41, v41
	v_max_f32_e32 v68, v40, v40
	v_max_f32_e32 v67, v68, v67
	v_max3_f32 v66, v26, v27, v66
	v_max3_f32 v67, v38, v39, v67
	v_max3_f32 v0, v0, v66, v67
	v_max_f32_e32 v66, v33, v33
	v_max_f32_e32 v67, v32, v32
	v_max_f32_e32 v66, v67, v66
	v_max_f32_e32 v67, v37, v37
	v_max_f32_e32 v68, v36, v36
	v_max_f32_e32 v67, v68, v67
	v_max3_f32 v66, v30, v31, v66
	v_max3_f32 v67, v34, v35, v67
	v_max3_f32 v66, v0, v66, v67
	v_and_b32_e32 v67, 64, v206
	v_xor_b32_e32 v0, 16, v206
	v_add_u32_e32 v67, 64, v67
	v_cmp_lt_i32_e32 vcc, v0, v67
	s_mov_b32 s1, 0xc2fc0000
	s_nop 0
	v_cndmask_b32_e32 v0, v206, v0, vcc
	v_lshlrev_b32_e32 v0, 2, v0
	ds_bpermute_b32 v68, v0, v66
	s_waitcnt lgkmcnt(0)
	v_max_f32_e32 v68, v68, v68
	v_max_f32_e32 v68, v66, v68
	v_xor_b32_e32 v66, 32, v206
	v_cmp_lt_i32_e32 vcc, v66, v67
	s_nop 1
	v_cndmask_b32_e32 v66, v206, v66, vcc
	v_lshlrev_b32_e32 v66, 2, v66
	ds_bpermute_b32 v67, v66, v68
	s_waitcnt lgkmcnt(0)
	v_max_f32_e32 v67, v67, v67
	v_max_f32_e32 v67, v68, v67
	v_sub_f32_e32 v2, v2, v67
	v_mul_f32_e32 v68, 0x3e0293ee, v2
	v_cmp_gt_f32_e32 vcc, s1, v68
	v_sub_f32_e32 v62, v62, v67
	v_sub_f32_e32 v3, v3, v67
	v_cndmask_b32_e32 v68, 0, v207, vcc
	v_fmac_f32_e32 v68, 0x3e0293ee, v2
	v_exp_f32_e32 v2, v68
	v_cndmask_b32_e32 v68, 0, v208, vcc
	v_sub_f32_e32 v63, v63, v67
	v_sub_f32_e32 v4, v4, v67
	v_ldexp_f32 v2, v2, v68
	v_mul_f32_e32 v68, 0x3e0293ee, v62
	v_cmp_gt_f32_e32 vcc, s1, v68
	v_sub_f32_e32 v64, v64, v67
	v_sub_f32_e32 v5, v5, v67
	v_cndmask_b32_e32 v68, 0, v207, vcc
	v_fmac_f32_e32 v68, 0x3e0293ee, v62
	v_exp_f32_e32 v62, v68
	v_cndmask_b32_e32 v68, 0, v208, vcc
	v_sub_f32_e32 v65, v65, v67
	v_sub_f32_e32 v6, v6, v67
	v_ldexp_f32 v62, v62, v68
	v_mul_f32_e32 v68, 0x3e0293ee, v3
	v_cmp_gt_f32_e32 vcc, s1, v68
	v_sub_f32_e32 v58, v58, v67
	v_sub_f32_e32 v7, v7, v67
	v_cndmask_b32_e32 v68, 0, v207, vcc
	v_fmac_f32_e32 v68, 0x3e0293ee, v3
	v_exp_f32_e32 v3, v68
	v_cndmask_b32_e32 v68, 0, v208, vcc
	v_sub_f32_e32 v59, v59, v67
	v_sub_f32_e32 v8, v8, v67
	v_ldexp_f32 v3, v3, v68
	v_mul_f32_e32 v68, 0x3e0293ee, v63
	v_cmp_gt_f32_e32 vcc, s1, v68
	v_bfe_u32 v72, v3, 16, 1
	v_add3_u32 v72, v3, v72, s60
	v_cndmask_b32_e32 v68, 0, v207, vcc
	v_fmac_f32_e32 v68, 0x3e0293ee, v63
	v_exp_f32_e32 v63, v68
	v_cndmask_b32_e32 v68, 0, v208, vcc
	v_sub_f32_e32 v60, v60, v67
	v_sub_f32_e32 v9, v9, v67
	v_ldexp_f32 v63, v63, v68
	v_mul_f32_e32 v68, 0x3e0293ee, v4
	v_cmp_gt_f32_e32 vcc, s1, v68
	v_sub_f32_e32 v61, v61, v67
	v_sub_f32_e32 v10, v10, v67
	v_cndmask_b32_e32 v68, 0, v207, vcc
	v_fmac_f32_e32 v68, 0x3e0293ee, v4
	v_exp_f32_e32 v4, v68
	v_cndmask_b32_e32 v68, 0, v208, vcc
	v_sub_f32_e32 v54, v54, v67
	v_sub_f32_e32 v11, v11, v67
	v_ldexp_f32 v4, v4, v68
	v_mul_f32_e32 v68, 0x3e0293ee, v64
	v_cmp_gt_f32_e32 vcc, s1, v68
	v_sub_f32_e32 v55, v55, v67
	v_sub_f32_e32 v12, v12, v67
	v_cndmask_b32_e32 v68, 0, v207, vcc
	v_fmac_f32_e32 v68, 0x3e0293ee, v64
	v_exp_f32_e32 v64, v68
	v_cndmask_b32_e32 v68, 0, v208, vcc
	v_sub_f32_e32 v56, v56, v67
	v_sub_f32_e32 v13, v13, v67
	v_ldexp_f32 v64, v64, v68
	v_mul_f32_e32 v68, 0x3e0293ee, v5
	v_cmp_gt_f32_e32 vcc, s1, v68
	v_sub_f32_e32 v57, v57, v67
	v_sub_f32_e32 v14, v14, v67
	v_cndmask_b32_e32 v68, 0, v207, vcc
	v_fmac_f32_e32 v68, 0x3e0293ee, v5
	v_exp_f32_e32 v5, v68
	v_cndmask_b32_e32 v68, 0, v208, vcc
	v_sub_f32_e32 v50, v50, v67
	v_sub_f32_e32 v15, v15, v67
	v_ldexp_f32 v5, v5, v68
	v_mul_f32_e32 v68, 0x3e0293ee, v65
	v_cmp_gt_f32_e32 vcc, s1, v68
	v_add_f32_e32 v69, v4, v5
	v_bfe_u32 v71, v5, 16, 1
	v_cndmask_b32_e32 v68, 0, v207, vcc
	v_fmac_f32_e32 v68, 0x3e0293ee, v65
	v_exp_f32_e32 v65, v68
	v_cndmask_b32_e32 v68, 0, v208, vcc
	v_sub_f32_e32 v51, v51, v67
	v_sub_f32_e32 v16, v16, v67
	v_ldexp_f32 v65, v65, v68
	v_add_f32_e32 v68, v2, v3
	v_add_f32_e32 v68, v68, v69
	v_add_f32_e32 v69, v62, v63
	v_add_f32_e32 v70, v64, v65
	v_add_f32_e32 v69, v69, v70
	v_add_f32_e32 v68, v68, v69
	v_bfe_u32 v69, v65, 16, 1
	v_bfe_u32 v70, v63, 16, 1
	v_add3_u32 v3, v5, v71, s60
	v_add3_u32 v63, v63, v70, s60
	v_add3_u32 v5, v65, v69, s60
	v_bfe_u32 v69, v4, 16, 1
	v_bfe_u32 v70, v62, 16, 1
	v_bfe_u32 v71, v64, 16, 1
	v_bfe_u32 v65, v2, 16, 1
	v_add3_u32 v64, v64, v71, s60
	v_add3_u32 v62, v62, v70, s60
	v_add3_u32 v4, v4, v69, s60
	v_add3_u32 v2, v2, v65, s60
	v_lshrrev_b32_e32 v65, 16, v4
	v_lshrrev_b32_e32 v4, 16, v62
	v_lshrrev_b32_e32 v62, 16, v64
	v_and_or_b32 v5, v5, s33, v62
	v_mul_f32_e32 v62, 0x3e0293ee, v6
	v_cmp_gt_f32_e32 vcc, s1, v62
	v_and_or_b32 v4, v63, s33, v4
	v_and_or_b32 v3, v3, s33, v65
	v_cndmask_b32_e32 v62, 0, v207, vcc
	v_fmac_f32_e32 v62, 0x3e0293ee, v6
	v_exp_f32_e32 v6, v62
	v_cndmask_b32_e32 v62, 0, v208, vcc
	v_sub_f32_e32 v52, v52, v67
	v_sub_f32_e32 v17, v17, v67
	v_ldexp_f32 v6, v6, v62
	v_mul_f32_e32 v62, 0x3e0293ee, v58
	v_cmp_gt_f32_e32 vcc, s1, v62
	v_sub_f32_e32 v53, v53, v67
	v_sub_f32_e32 v18, v18, v67
	v_cndmask_b32_e32 v62, 0, v207, vcc
	v_fmac_f32_e32 v62, 0x3e0293ee, v58
	v_exp_f32_e32 v58, v62
	v_cndmask_b32_e32 v62, 0, v208, vcc
	v_sub_f32_e32 v46, v46, v67
	v_sub_f32_e32 v19, v19, v67
	v_ldexp_f32 v58, v58, v62
	v_mul_f32_e32 v62, 0x3e0293ee, v7
	v_cmp_gt_f32_e32 vcc, s1, v62
	v_sub_f32_e32 v47, v47, v67
	v_sub_f32_e32 v20, v20, v67
	v_cndmask_b32_e32 v62, 0, v207, vcc
	v_fmac_f32_e32 v62, 0x3e0293ee, v7
	v_exp_f32_e32 v7, v62
	v_cndmask_b32_e32 v62, 0, v208, vcc
	v_sub_f32_e32 v48, v48, v67
	v_sub_f32_e32 v21, v21, v67
	v_ldexp_f32 v7, v7, v62
	v_mul_f32_e32 v62, 0x3e0293ee, v59
	v_cmp_gt_f32_e32 vcc, s1, v62
	v_sub_f32_e32 v49, v49, v67
	v_sub_f32_e32 v22, v22, v67
	v_cndmask_b32_e32 v62, 0, v207, vcc
	v_fmac_f32_e32 v62, 0x3e0293ee, v59
	v_exp_f32_e32 v59, v62
	v_cndmask_b32_e32 v62, 0, v208, vcc
	v_sub_f32_e32 v42, v42, v67
	v_sub_f32_e32 v23, v23, v67
	v_ldexp_f32 v59, v59, v62
	v_mul_f32_e32 v62, 0x3e0293ee, v8
	v_cmp_gt_f32_e32 vcc, s1, v62
	v_sub_f32_e32 v43, v43, v67
	v_sub_f32_e32 v24, v24, v67
	v_cndmask_b32_e32 v62, 0, v207, vcc
	v_fmac_f32_e32 v62, 0x3e0293ee, v8
	v_exp_f32_e32 v8, v62
	v_cndmask_b32_e32 v62, 0, v208, vcc
	v_sub_f32_e32 v44, v44, v67
	v_sub_f32_e32 v25, v25, v67
	v_ldexp_f32 v8, v8, v62
	v_mul_f32_e32 v62, 0x3e0293ee, v60
	v_cmp_gt_f32_e32 vcc, s1, v62
	v_sub_f32_e32 v45, v45, v67
	v_sub_f32_e32 v26, v26, v67
	v_cndmask_b32_e32 v62, 0, v207, vcc
	v_fmac_f32_e32 v62, 0x3e0293ee, v60
	v_exp_f32_e32 v60, v62
	v_cndmask_b32_e32 v62, 0, v208, vcc
	v_sub_f32_e32 v38, v38, v67
	v_sub_f32_e32 v27, v27, v67
	v_ldexp_f32 v60, v60, v62
	v_mul_f32_e32 v62, 0x3e0293ee, v9
	v_cmp_gt_f32_e32 vcc, s1, v62
	v_sub_f32_e32 v39, v39, v67
	v_sub_f32_e32 v28, v28, v67
	v_cndmask_b32_e32 v62, 0, v207, vcc
	v_fmac_f32_e32 v62, 0x3e0293ee, v9
	v_exp_f32_e32 v9, v62
	v_cndmask_b32_e32 v62, 0, v208, vcc
	v_sub_f32_e32 v40, v40, v67
	v_sub_f32_e32 v29, v29, v67
	v_ldexp_f32 v9, v9, v62
	v_mul_f32_e32 v62, 0x3e0293ee, v61
	v_cmp_gt_f32_e32 vcc, s1, v62
	v_add_f32_e32 v63, v8, v9
	v_bfe_u32 v65, v9, 16, 1
	v_cndmask_b32_e32 v62, 0, v207, vcc
	v_fmac_f32_e32 v62, 0x3e0293ee, v61
	v_exp_f32_e32 v61, v62
	v_cndmask_b32_e32 v62, 0, v208, vcc
	v_sub_f32_e32 v41, v41, v67
	v_sub_f32_e32 v30, v30, v67
	v_ldexp_f32 v61, v61, v62
	v_add_f32_e32 v62, v6, v7
	v_add_f32_e32 v62, v62, v63
	v_add_f32_e32 v63, v58, v59
	v_add_f32_e32 v64, v60, v61
	v_add_f32_e32 v63, v63, v64
	v_add_f32_e32 v62, v62, v63
	v_add_f32_e32 v62, v68, v62
	v_bfe_u32 v63, v61, 16, 1
	v_bfe_u32 v64, v59, 16, 1
	v_bfe_u32 v68, v7, 16, 1
	v_add3_u32 v68, v7, v68, s60
	v_add3_u32 v7, v9, v65, s60
	v_add3_u32 v59, v59, v64, s60
	v_add3_u32 v9, v61, v63, s60
	v_bfe_u32 v63, v8, 16, 1
	v_bfe_u32 v64, v58, 16, 1
	v_bfe_u32 v65, v60, 16, 1
	v_bfe_u32 v61, v6, 16, 1
	v_add3_u32 v60, v60, v65, s60
	v_add3_u32 v58, v58, v64, s60
	v_add3_u32 v8, v8, v63, s60
	v_add3_u32 v6, v6, v61, s60
	v_lshrrev_b32_e32 v61, 16, v8
	v_lshrrev_b32_e32 v8, 16, v58
	v_lshrrev_b32_e32 v58, 16, v60
	v_and_or_b32 v9, v9, s33, v58
	v_mul_f32_e32 v58, 0x3e0293ee, v10
	v_cmp_gt_f32_e32 vcc, s1, v58
	v_and_or_b32 v8, v59, s33, v8
	v_and_or_b32 v7, v7, s33, v61
	v_cndmask_b32_e32 v58, 0, v207, vcc
	v_fmac_f32_e32 v58, 0x3e0293ee, v10
	v_exp_f32_e32 v10, v58
	v_cndmask_b32_e32 v58, 0, v208, vcc
	v_sub_f32_e32 v34, v34, v67
	v_sub_f32_e32 v31, v31, v67
	v_ldexp_f32 v10, v10, v58
	v_mul_f32_e32 v58, 0x3e0293ee, v54
	v_cmp_gt_f32_e32 vcc, s1, v58
	v_sub_f32_e32 v35, v35, v67
	v_sub_f32_e32 v32, v32, v67
	v_cndmask_b32_e32 v58, 0, v207, vcc
	v_fmac_f32_e32 v58, 0x3e0293ee, v54
	v_exp_f32_e32 v54, v58
	v_cndmask_b32_e32 v58, 0, v208, vcc
	v_sub_f32_e32 v36, v36, v67
	v_sub_f32_e32 v33, v33, v67
	v_ldexp_f32 v54, v54, v58
	v_mul_f32_e32 v58, 0x3e0293ee, v11
	v_cmp_gt_f32_e32 vcc, s1, v58
	v_sub_f32_e32 v37, v37, v67
	v_lshrrev_b32_e32 v2, 16, v2
	v_cndmask_b32_e32 v58, 0, v207, vcc
	v_fmac_f32_e32 v58, 0x3e0293ee, v11
	v_exp_f32_e32 v11, v58
	v_cndmask_b32_e32 v58, 0, v208, vcc
	v_and_or_b32 v2, v72, s33, v2
	v_lshrrev_b32_e32 v6, 16, v6
	v_ldexp_f32 v11, v11, v58
	v_mul_f32_e32 v58, 0x3e0293ee, v55
	v_cmp_gt_f32_e32 vcc, s1, v58
	v_and_or_b32 v6, v68, s33, v6
	s_nop 0
	v_cndmask_b32_e32 v58, 0, v207, vcc
	v_fmac_f32_e32 v58, 0x3e0293ee, v55
	v_exp_f32_e32 v55, v58
	v_cndmask_b32_e32 v58, 0, v208, vcc
	v_ldexp_f32 v55, v55, v58
	v_mul_f32_e32 v58, 0x3e0293ee, v12
	v_cmp_gt_f32_e32 vcc, s1, v58
	s_nop 1
	v_cndmask_b32_e32 v58, 0, v207, vcc
	v_fmac_f32_e32 v58, 0x3e0293ee, v12
	v_exp_f32_e32 v12, v58
	v_cndmask_b32_e32 v58, 0, v208, vcc
	v_ldexp_f32 v12, v12, v58
	v_mul_f32_e32 v58, 0x3e0293ee, v56
	v_cmp_gt_f32_e32 vcc, s1, v58
	s_nop 1
	v_cndmask_b32_e32 v58, 0, v207, vcc
	v_fmac_f32_e32 v58, 0x3e0293ee, v56
	v_exp_f32_e32 v56, v58
	v_cndmask_b32_e32 v58, 0, v208, vcc
	v_ldexp_f32 v56, v56, v58
	v_mul_f32_e32 v58, 0x3e0293ee, v13
	v_cmp_gt_f32_e32 vcc, s1, v58
	s_nop 1
	v_cndmask_b32_e32 v58, 0, v207, vcc
	v_fmac_f32_e32 v58, 0x3e0293ee, v13
	v_exp_f32_e32 v13, v58
	v_cndmask_b32_e32 v58, 0, v208, vcc
	v_ldexp_f32 v13, v13, v58
	v_mul_f32_e32 v58, 0x3e0293ee, v57
	v_cmp_gt_f32_e32 vcc, s1, v58
	v_add_f32_e32 v59, v12, v13
	v_bfe_u32 v61, v13, 16, 1
	v_cndmask_b32_e32 v58, 0, v207, vcc
	v_fmac_f32_e32 v58, 0x3e0293ee, v57
	v_exp_f32_e32 v57, v58
	v_cndmask_b32_e32 v58, 0, v208, vcc
	v_ldexp_f32 v57, v57, v58
	v_add_f32_e32 v58, v10, v11
	v_add_f32_e32 v58, v58, v59
	v_add_f32_e32 v59, v54, v55
	v_add_f32_e32 v60, v56, v57
	v_add_f32_e32 v59, v59, v60
	v_add_f32_e32 v58, v58, v59
	v_add_f32_e32 v58, v58, v62
	v_bfe_u32 v59, v57, 16, 1
	v_bfe_u32 v60, v55, 16, 1
	v_bfe_u32 v62, v11, 16, 1
	v_add3_u32 v62, v11, v62, s60
	v_add3_u32 v11, v13, v61, s60
	v_add3_u32 v55, v55, v60, s60
	v_add3_u32 v13, v57, v59, s60
	v_bfe_u32 v59, v12, 16, 1
	v_bfe_u32 v60, v54, 16, 1
	v_bfe_u32 v61, v56, 16, 1
	v_bfe_u32 v57, v10, 16, 1
	v_add3_u32 v56, v56, v61, s60
	v_add3_u32 v54, v54, v60, s60
	v_add3_u32 v12, v12, v59, s60
	v_add3_u32 v10, v10, v57, s60
	v_lshrrev_b32_e32 v57, 16, v12
	v_lshrrev_b32_e32 v12, 16, v54
	v_lshrrev_b32_e32 v54, 16, v56
	v_and_or_b32 v13, v13, s33, v54
	v_mul_f32_e32 v54, 0x3e0293ee, v14
	v_cmp_gt_f32_e32 vcc, s1, v54
	v_and_or_b32 v12, v55, s33, v12
	v_and_or_b32 v11, v11, s33, v57
	v_cndmask_b32_e32 v54, 0, v207, vcc
	v_fmac_f32_e32 v54, 0x3e0293ee, v14
	v_exp_f32_e32 v14, v54
	v_cndmask_b32_e32 v54, 0, v208, vcc
	v_lshrrev_b32_e32 v10, 16, v10
	v_and_or_b32 v10, v62, s33, v10
	v_ldexp_f32 v14, v14, v54
	v_mul_f32_e32 v54, 0x3e0293ee, v50
	v_cmp_gt_f32_e32 vcc, s1, v54
	s_nop 1
	v_cndmask_b32_e32 v54, 0, v207, vcc
	v_fmac_f32_e32 v54, 0x3e0293ee, v50
	v_exp_f32_e32 v50, v54
	v_cndmask_b32_e32 v54, 0, v208, vcc
	v_ldexp_f32 v50, v50, v54
	v_mul_f32_e32 v54, 0x3e0293ee, v15
	v_cmp_gt_f32_e32 vcc, s1, v54
	s_nop 1
	v_cndmask_b32_e32 v54, 0, v207, vcc
	v_fmac_f32_e32 v54, 0x3e0293ee, v15
	v_exp_f32_e32 v15, v54
	v_cndmask_b32_e32 v54, 0, v208, vcc
	v_ldexp_f32 v15, v15, v54
	v_mul_f32_e32 v54, 0x3e0293ee, v51
	v_cmp_gt_f32_e32 vcc, s1, v54
	s_nop 1
	v_cndmask_b32_e32 v54, 0, v207, vcc
	v_fmac_f32_e32 v54, 0x3e0293ee, v51
	v_exp_f32_e32 v51, v54
	v_cndmask_b32_e32 v54, 0, v208, vcc
	v_ldexp_f32 v51, v51, v54
	v_mul_f32_e32 v54, 0x3e0293ee, v16
	v_cmp_gt_f32_e32 vcc, s1, v54
	s_nop 1
	v_cndmask_b32_e32 v54, 0, v207, vcc
	v_fmac_f32_e32 v54, 0x3e0293ee, v16
	v_exp_f32_e32 v16, v54
	v_cndmask_b32_e32 v54, 0, v208, vcc
	v_ldexp_f32 v16, v16, v54
	v_mul_f32_e32 v54, 0x3e0293ee, v52
	v_cmp_gt_f32_e32 vcc, s1, v54
	s_nop 1
	v_cndmask_b32_e32 v54, 0, v207, vcc
	v_fmac_f32_e32 v54, 0x3e0293ee, v52
	v_exp_f32_e32 v52, v54
	v_cndmask_b32_e32 v54, 0, v208, vcc
	v_ldexp_f32 v52, v52, v54
	v_mul_f32_e32 v54, 0x3e0293ee, v17
	v_cmp_gt_f32_e32 vcc, s1, v54
	s_nop 1
	v_cndmask_b32_e32 v54, 0, v207, vcc
	v_fmac_f32_e32 v54, 0x3e0293ee, v17
	v_exp_f32_e32 v17, v54
	v_cndmask_b32_e32 v54, 0, v208, vcc
	v_ldexp_f32 v17, v17, v54
	v_mul_f32_e32 v54, 0x3e0293ee, v53
	v_cmp_gt_f32_e32 vcc, s1, v54
	v_add_f32_e32 v55, v16, v17
	v_bfe_u32 v57, v17, 16, 1
	v_cndmask_b32_e32 v54, 0, v207, vcc
	v_fmac_f32_e32 v54, 0x3e0293ee, v53
	v_exp_f32_e32 v53, v54
	v_cndmask_b32_e32 v54, 0, v208, vcc
	v_ldexp_f32 v53, v53, v54
	v_add_f32_e32 v54, v14, v15
	v_add_f32_e32 v54, v54, v55
	v_add_f32_e32 v55, v50, v51
	v_add_f32_e32 v56, v52, v53
	v_add_f32_e32 v55, v55, v56
	v_add_f32_e32 v54, v54, v55
	v_add_f32_e32 v54, v54, v58
	v_bfe_u32 v55, v53, 16, 1
	v_bfe_u32 v56, v51, 16, 1
	v_bfe_u32 v58, v15, 16, 1
	v_add3_u32 v58, v15, v58, s60
	v_add3_u32 v15, v17, v57, s60
	v_add3_u32 v51, v51, v56, s60
	v_add3_u32 v17, v53, v55, s60
	v_bfe_u32 v55, v16, 16, 1
	v_bfe_u32 v56, v50, 16, 1
	v_bfe_u32 v57, v52, 16, 1
	v_bfe_u32 v53, v14, 16, 1
	v_add3_u32 v52, v52, v57, s60
	v_add3_u32 v50, v50, v56, s60
	v_add3_u32 v16, v16, v55, s60
	v_add3_u32 v14, v14, v53, s60
	v_lshrrev_b32_e32 v53, 16, v16
	v_lshrrev_b32_e32 v16, 16, v50
	v_lshrrev_b32_e32 v50, 16, v52
	v_and_or_b32 v17, v17, s33, v50
	v_mul_f32_e32 v50, 0x3e0293ee, v18
	v_cmp_gt_f32_e32 vcc, s1, v50
	v_and_or_b32 v16, v51, s33, v16
	v_and_or_b32 v15, v15, s33, v53
	v_cndmask_b32_e32 v50, 0, v207, vcc
	v_fmac_f32_e32 v50, 0x3e0293ee, v18
	v_exp_f32_e32 v18, v50
	v_cndmask_b32_e32 v50, 0, v208, vcc
	v_lshrrev_b32_e32 v14, 16, v14
	v_and_or_b32 v14, v58, s33, v14
	v_ldexp_f32 v18, v18, v50
	v_mul_f32_e32 v50, 0x3e0293ee, v46
	v_cmp_gt_f32_e32 vcc, s1, v50
	s_nop 1
	v_cndmask_b32_e32 v50, 0, v207, vcc
	v_fmac_f32_e32 v50, 0x3e0293ee, v46
	v_exp_f32_e32 v46, v50
	v_cndmask_b32_e32 v50, 0, v208, vcc
	v_ldexp_f32 v46, v46, v50
	v_mul_f32_e32 v50, 0x3e0293ee, v19
	v_cmp_gt_f32_e32 vcc, s1, v50
	s_nop 1
	v_cndmask_b32_e32 v50, 0, v207, vcc
	v_fmac_f32_e32 v50, 0x3e0293ee, v19
	v_exp_f32_e32 v19, v50
	v_cndmask_b32_e32 v50, 0, v208, vcc
	v_ldexp_f32 v19, v19, v50
	v_mul_f32_e32 v50, 0x3e0293ee, v47
	v_cmp_gt_f32_e32 vcc, s1, v50
	s_nop 1
	v_cndmask_b32_e32 v50, 0, v207, vcc
	v_fmac_f32_e32 v50, 0x3e0293ee, v47
	v_exp_f32_e32 v47, v50
	v_cndmask_b32_e32 v50, 0, v208, vcc
	v_ldexp_f32 v47, v47, v50
	v_mul_f32_e32 v50, 0x3e0293ee, v20
	v_cmp_gt_f32_e32 vcc, s1, v50
	s_nop 1
	v_cndmask_b32_e32 v50, 0, v207, vcc
	v_fmac_f32_e32 v50, 0x3e0293ee, v20
	v_exp_f32_e32 v20, v50
	v_cndmask_b32_e32 v50, 0, v208, vcc
	v_ldexp_f32 v20, v20, v50
	v_mul_f32_e32 v50, 0x3e0293ee, v48
	v_cmp_gt_f32_e32 vcc, s1, v50
	s_nop 1
	v_cndmask_b32_e32 v50, 0, v207, vcc
	v_fmac_f32_e32 v50, 0x3e0293ee, v48
	v_exp_f32_e32 v48, v50
	v_cndmask_b32_e32 v50, 0, v208, vcc
	v_ldexp_f32 v48, v48, v50
	v_mul_f32_e32 v50, 0x3e0293ee, v21
	v_cmp_gt_f32_e32 vcc, s1, v50
	s_nop 1
	v_cndmask_b32_e32 v50, 0, v207, vcc
	v_fmac_f32_e32 v50, 0x3e0293ee, v21
	v_exp_f32_e32 v21, v50
	v_cndmask_b32_e32 v50, 0, v208, vcc
	v_ldexp_f32 v21, v21, v50
	v_mul_f32_e32 v50, 0x3e0293ee, v49
	v_cmp_gt_f32_e32 vcc, s1, v50
	v_add_f32_e32 v51, v20, v21
	v_bfe_u32 v53, v21, 16, 1
	v_cndmask_b32_e32 v50, 0, v207, vcc
	v_fmac_f32_e32 v50, 0x3e0293ee, v49
	v_exp_f32_e32 v49, v50
	v_cndmask_b32_e32 v50, 0, v208, vcc
	v_ldexp_f32 v49, v49, v50
	v_add_f32_e32 v50, v18, v19
	v_add_f32_e32 v50, v50, v51
	v_add_f32_e32 v51, v46, v47
	v_add_f32_e32 v52, v48, v49
	v_add_f32_e32 v51, v51, v52
	v_add_f32_e32 v50, v50, v51
	v_add_f32_e32 v50, v50, v54
	v_bfe_u32 v51, v49, 16, 1
	v_bfe_u32 v52, v47, 16, 1
	v_bfe_u32 v54, v19, 16, 1
	v_add3_u32 v54, v19, v54, s60
	v_add3_u32 v19, v21, v53, s60
	v_add3_u32 v47, v47, v52, s60
	v_add3_u32 v21, v49, v51, s60
	v_bfe_u32 v51, v20, 16, 1
	v_bfe_u32 v52, v46, 16, 1
	v_bfe_u32 v53, v48, 16, 1
	v_bfe_u32 v49, v18, 16, 1
	v_add3_u32 v48, v48, v53, s60
	v_add3_u32 v46, v46, v52, s60
	v_add3_u32 v20, v20, v51, s60
	v_add3_u32 v18, v18, v49, s60
	v_lshrrev_b32_e32 v49, 16, v20
	v_lshrrev_b32_e32 v20, 16, v46
	v_lshrrev_b32_e32 v46, 16, v48
	v_and_or_b32 v21, v21, s33, v46
	v_mul_f32_e32 v46, 0x3e0293ee, v22
	v_cmp_gt_f32_e32 vcc, s1, v46
	v_and_or_b32 v20, v47, s33, v20
	v_and_or_b32 v19, v19, s33, v49
	v_cndmask_b32_e32 v46, 0, v207, vcc
	v_fmac_f32_e32 v46, 0x3e0293ee, v22
	v_exp_f32_e32 v22, v46
	v_cndmask_b32_e32 v46, 0, v208, vcc
	v_lshrrev_b32_e32 v18, 16, v18
	v_and_or_b32 v18, v54, s33, v18
	v_ldexp_f32 v22, v22, v46
	v_mul_f32_e32 v46, 0x3e0293ee, v42
	v_cmp_gt_f32_e32 vcc, s1, v46
	s_nop 1
	v_cndmask_b32_e32 v46, 0, v207, vcc
	v_fmac_f32_e32 v46, 0x3e0293ee, v42
	v_exp_f32_e32 v42, v46
	v_cndmask_b32_e32 v46, 0, v208, vcc
	v_ldexp_f32 v42, v42, v46
	v_mul_f32_e32 v46, 0x3e0293ee, v23
	v_cmp_gt_f32_e32 vcc, s1, v46
	s_nop 1
	v_cndmask_b32_e32 v46, 0, v207, vcc
	v_fmac_f32_e32 v46, 0x3e0293ee, v23
	v_exp_f32_e32 v23, v46
	v_cndmask_b32_e32 v46, 0, v208, vcc
	v_ldexp_f32 v23, v23, v46
	v_mul_f32_e32 v46, 0x3e0293ee, v43
	v_cmp_gt_f32_e32 vcc, s1, v46
	s_nop 1
	v_cndmask_b32_e32 v46, 0, v207, vcc
	v_fmac_f32_e32 v46, 0x3e0293ee, v43
	v_exp_f32_e32 v43, v46
	v_cndmask_b32_e32 v46, 0, v208, vcc
	v_ldexp_f32 v43, v43, v46
	v_mul_f32_e32 v46, 0x3e0293ee, v24
	v_cmp_gt_f32_e32 vcc, s1, v46
	s_nop 1
	v_cndmask_b32_e32 v46, 0, v207, vcc
	v_fmac_f32_e32 v46, 0x3e0293ee, v24
	v_exp_f32_e32 v24, v46
	v_cndmask_b32_e32 v46, 0, v208, vcc
	v_ldexp_f32 v24, v24, v46
	v_mul_f32_e32 v46, 0x3e0293ee, v44
	v_cmp_gt_f32_e32 vcc, s1, v46
	s_nop 1
	v_cndmask_b32_e32 v46, 0, v207, vcc
	v_fmac_f32_e32 v46, 0x3e0293ee, v44
	v_exp_f32_e32 v44, v46
	v_cndmask_b32_e32 v46, 0, v208, vcc
	v_ldexp_f32 v44, v44, v46
	v_mul_f32_e32 v46, 0x3e0293ee, v25
	v_cmp_gt_f32_e32 vcc, s1, v46
	s_nop 1
	v_cndmask_b32_e32 v46, 0, v207, vcc
	v_fmac_f32_e32 v46, 0x3e0293ee, v25
	v_exp_f32_e32 v25, v46
	v_cndmask_b32_e32 v46, 0, v208, vcc
	v_ldexp_f32 v25, v25, v46
	v_mul_f32_e32 v46, 0x3e0293ee, v45
	v_cmp_gt_f32_e32 vcc, s1, v46
	v_add_f32_e32 v47, v24, v25
	v_bfe_u32 v49, v25, 16, 1
	v_cndmask_b32_e32 v46, 0, v207, vcc
	v_fmac_f32_e32 v46, 0x3e0293ee, v45
	v_exp_f32_e32 v45, v46
	v_cndmask_b32_e32 v46, 0, v208, vcc
	v_ldexp_f32 v45, v45, v46
	v_add_f32_e32 v46, v22, v23
	v_add_f32_e32 v46, v46, v47
	v_add_f32_e32 v47, v42, v43
	v_add_f32_e32 v48, v44, v45
	v_add_f32_e32 v47, v47, v48
	v_add_f32_e32 v46, v46, v47
	v_add_f32_e32 v46, v46, v50
	v_bfe_u32 v47, v45, 16, 1
	v_bfe_u32 v48, v43, 16, 1
	v_bfe_u32 v50, v23, 16, 1
	v_add3_u32 v50, v23, v50, s60
	v_add3_u32 v23, v25, v49, s60
	v_add3_u32 v43, v43, v48, s60
	v_add3_u32 v25, v45, v47, s60
	v_bfe_u32 v47, v24, 16, 1
	v_bfe_u32 v48, v42, 16, 1
	v_bfe_u32 v49, v44, 16, 1
	v_bfe_u32 v45, v22, 16, 1
	v_add3_u32 v44, v44, v49, s60
	v_add3_u32 v42, v42, v48, s60
	v_add3_u32 v24, v24, v47, s60
	v_add3_u32 v22, v22, v45, s60
	v_lshrrev_b32_e32 v45, 16, v24
	v_lshrrev_b32_e32 v24, 16, v42
	v_lshrrev_b32_e32 v42, 16, v44
	v_and_or_b32 v25, v25, s33, v42
	v_mul_f32_e32 v42, 0x3e0293ee, v26
	v_cmp_gt_f32_e32 vcc, s1, v42
	v_and_or_b32 v24, v43, s33, v24
	v_and_or_b32 v23, v23, s33, v45
	v_cndmask_b32_e32 v42, 0, v207, vcc
	v_fmac_f32_e32 v42, 0x3e0293ee, v26
	v_exp_f32_e32 v26, v42
	v_cndmask_b32_e32 v42, 0, v208, vcc
	v_lshrrev_b32_e32 v22, 16, v22
	v_and_or_b32 v22, v50, s33, v22
	v_ldexp_f32 v26, v26, v42
	v_mul_f32_e32 v42, 0x3e0293ee, v38
	v_cmp_gt_f32_e32 vcc, s1, v42
	s_nop 1
	v_cndmask_b32_e32 v42, 0, v207, vcc
	v_fmac_f32_e32 v42, 0x3e0293ee, v38
	v_exp_f32_e32 v38, v42
	v_cndmask_b32_e32 v42, 0, v208, vcc
	v_ldexp_f32 v38, v38, v42
	v_mul_f32_e32 v42, 0x3e0293ee, v27
	v_cmp_gt_f32_e32 vcc, s1, v42
	s_nop 1
	v_cndmask_b32_e32 v42, 0, v207, vcc
	v_fmac_f32_e32 v42, 0x3e0293ee, v27
	v_exp_f32_e32 v27, v42
	v_cndmask_b32_e32 v42, 0, v208, vcc
	v_ldexp_f32 v27, v27, v42
	v_mul_f32_e32 v42, 0x3e0293ee, v39
	v_cmp_gt_f32_e32 vcc, s1, v42
	s_nop 1
	v_cndmask_b32_e32 v42, 0, v207, vcc
	v_fmac_f32_e32 v42, 0x3e0293ee, v39
	v_exp_f32_e32 v39, v42
	v_cndmask_b32_e32 v42, 0, v208, vcc
	v_ldexp_f32 v39, v39, v42
	v_mul_f32_e32 v42, 0x3e0293ee, v28
	v_cmp_gt_f32_e32 vcc, s1, v42
	s_nop 1
	v_cndmask_b32_e32 v42, 0, v207, vcc
	v_fmac_f32_e32 v42, 0x3e0293ee, v28
	v_exp_f32_e32 v28, v42
	v_cndmask_b32_e32 v42, 0, v208, vcc
	v_ldexp_f32 v28, v28, v42
	v_mul_f32_e32 v42, 0x3e0293ee, v40
	v_cmp_gt_f32_e32 vcc, s1, v42
	s_nop 1
	v_cndmask_b32_e32 v42, 0, v207, vcc
	v_fmac_f32_e32 v42, 0x3e0293ee, v40
	v_exp_f32_e32 v40, v42
	v_cndmask_b32_e32 v42, 0, v208, vcc
	v_ldexp_f32 v40, v40, v42
	v_mul_f32_e32 v42, 0x3e0293ee, v29
	v_cmp_gt_f32_e32 vcc, s1, v42
	s_nop 1
	v_cndmask_b32_e32 v42, 0, v207, vcc
	v_fmac_f32_e32 v42, 0x3e0293ee, v29
	v_exp_f32_e32 v29, v42
	v_cndmask_b32_e32 v42, 0, v208, vcc
	v_ldexp_f32 v29, v29, v42
	v_mul_f32_e32 v42, 0x3e0293ee, v41
	v_cmp_gt_f32_e32 vcc, s1, v42
	v_add_f32_e32 v43, v28, v29
	v_bfe_u32 v45, v29, 16, 1
	v_cndmask_b32_e32 v42, 0, v207, vcc
	v_fmac_f32_e32 v42, 0x3e0293ee, v41
	v_exp_f32_e32 v41, v42
	v_cndmask_b32_e32 v42, 0, v208, vcc
	v_ldexp_f32 v41, v41, v42
	v_add_f32_e32 v42, v26, v27
	v_add_f32_e32 v42, v42, v43
	v_add_f32_e32 v43, v38, v39
	v_add_f32_e32 v44, v40, v41
	v_add_f32_e32 v43, v43, v44
	v_add_f32_e32 v42, v42, v43
	v_add_f32_e32 v42, v42, v46
	v_bfe_u32 v43, v41, 16, 1
	v_bfe_u32 v44, v39, 16, 1
	v_bfe_u32 v46, v27, 16, 1
	v_add3_u32 v46, v27, v46, s60
	v_add3_u32 v27, v29, v45, s60
	v_add3_u32 v39, v39, v44, s60
	v_add3_u32 v29, v41, v43, s60
	v_bfe_u32 v43, v28, 16, 1
	v_bfe_u32 v44, v38, 16, 1
	v_bfe_u32 v45, v40, 16, 1
	v_bfe_u32 v41, v26, 16, 1
	v_add3_u32 v40, v40, v45, s60
	v_add3_u32 v38, v38, v44, s60
	v_add3_u32 v28, v28, v43, s60
	v_add3_u32 v26, v26, v41, s60
	v_lshrrev_b32_e32 v41, 16, v28
	v_lshrrev_b32_e32 v28, 16, v38
	v_lshrrev_b32_e32 v38, 16, v40
	v_and_or_b32 v29, v29, s33, v38
	v_mul_f32_e32 v38, 0x3e0293ee, v30
	v_cmp_gt_f32_e32 vcc, s1, v38
	v_and_or_b32 v28, v39, s33, v28
	v_and_or_b32 v27, v27, s33, v41
	v_cndmask_b32_e32 v38, 0, v207, vcc
	v_fmac_f32_e32 v38, 0x3e0293ee, v30
	v_exp_f32_e32 v30, v38
	v_cndmask_b32_e32 v38, 0, v208, vcc
	v_lshrrev_b32_e32 v26, 16, v26
	v_and_or_b32 v26, v46, s33, v26
	v_ldexp_f32 v30, v30, v38
	v_mul_f32_e32 v38, 0x3e0293ee, v34
	v_cmp_gt_f32_e32 vcc, s1, v38
	s_nop 1
	v_cndmask_b32_e32 v38, 0, v207, vcc
	v_fmac_f32_e32 v38, 0x3e0293ee, v34
	v_exp_f32_e32 v34, v38
	v_cndmask_b32_e32 v38, 0, v208, vcc
	v_ldexp_f32 v34, v34, v38
	v_mul_f32_e32 v38, 0x3e0293ee, v31
	v_cmp_gt_f32_e32 vcc, s1, v38
	s_nop 1
	v_cndmask_b32_e32 v38, 0, v207, vcc
	v_fmac_f32_e32 v38, 0x3e0293ee, v31
	v_exp_f32_e32 v31, v38
	v_cndmask_b32_e32 v38, 0, v208, vcc
	v_ldexp_f32 v31, v31, v38
	v_mul_f32_e32 v38, 0x3e0293ee, v35
	v_cmp_gt_f32_e32 vcc, s1, v38
	s_nop 1
	v_cndmask_b32_e32 v38, 0, v207, vcc
	v_fmac_f32_e32 v38, 0x3e0293ee, v35
	v_exp_f32_e32 v35, v38
	v_cndmask_b32_e32 v38, 0, v208, vcc
	v_ldexp_f32 v35, v35, v38
	v_mul_f32_e32 v38, 0x3e0293ee, v32
	v_cmp_gt_f32_e32 vcc, s1, v38
	s_nop 1
	v_cndmask_b32_e32 v38, 0, v207, vcc
	v_fmac_f32_e32 v38, 0x3e0293ee, v32
	v_exp_f32_e32 v32, v38
	v_cndmask_b32_e32 v38, 0, v208, vcc
	v_ldexp_f32 v32, v32, v38
	v_mul_f32_e32 v38, 0x3e0293ee, v36
	v_cmp_gt_f32_e32 vcc, s1, v38
	s_nop 1
	v_cndmask_b32_e32 v38, 0, v207, vcc
	v_fmac_f32_e32 v38, 0x3e0293ee, v36
	v_exp_f32_e32 v36, v38
	v_cndmask_b32_e32 v38, 0, v208, vcc
	v_ldexp_f32 v36, v36, v38
	v_mul_f32_e32 v38, 0x3e0293ee, v33
	v_cmp_gt_f32_e32 vcc, s1, v38
	s_nop 1
	v_cndmask_b32_e32 v38, 0, v207, vcc
	v_fmac_f32_e32 v38, 0x3e0293ee, v33
	v_exp_f32_e32 v33, v38
	v_cndmask_b32_e32 v38, 0, v208, vcc
	v_ldexp_f32 v33, v33, v38
	v_mul_f32_e32 v38, 0x3e0293ee, v37
	v_cmp_gt_f32_e32 vcc, s1, v38
	v_add_f32_e32 v39, v32, v33
	v_bfe_u32 v41, v33, 16, 1
	v_cndmask_b32_e32 v38, 0, v207, vcc
	v_fmac_f32_e32 v38, 0x3e0293ee, v37
	v_exp_f32_e32 v37, v38
	v_cndmask_b32_e32 v38, 0, v208, vcc
	v_ldexp_f32 v37, v37, v38
	v_add_f32_e32 v38, v30, v31
	v_add_f32_e32 v38, v38, v39
	v_add_f32_e32 v39, v34, v35
	v_add_f32_e32 v40, v36, v37
	v_add_f32_e32 v39, v39, v40
	v_add_f32_e32 v38, v38, v39
	v_add_f32_e32 v38, v38, v42
	ds_bpermute_b32 v0, v0, v38
	v_bfe_u32 v39, v37, 16, 1
	v_bfe_u32 v40, v35, 16, 1
	v_bfe_u32 v42, v31, 16, 1
	v_add3_u32 v42, v31, v42, s60
	v_add3_u32 v31, v33, v41, s60
	v_add3_u32 v35, v35, v40, s60
	v_add3_u32 v33, v37, v39, s60
	v_bfe_u32 v39, v32, 16, 1
	v_bfe_u32 v40, v34, 16, 1
	v_bfe_u32 v41, v36, 16, 1
	v_bfe_u32 v37, v30, 16, 1
	v_add3_u32 v36, v36, v41, s60
	v_add3_u32 v34, v34, v40, s60
	v_add3_u32 v32, v32, v39, s60
	v_add3_u32 v30, v30, v37, s60
	v_lshrrev_b32_e32 v37, 16, v32
	v_lshrrev_b32_e32 v32, 16, v34
	v_lshrrev_b32_e32 v34, 16, v36
	s_waitcnt lgkmcnt(0)
	v_add_f32_e32 v0, v38, v0
	v_and_or_b32 v33, v33, s33, v34
	ds_bpermute_b32 v34, v66, v0
	v_and_or_b32 v32, v35, s33, v32
	v_and_or_b32 v31, v31, s33, v37
	v_lshrrev_b32_e32 v30, 16, v30
	v_and_or_b32 v30, v42, s33, v30
	s_waitcnt lgkmcnt(0)
	v_add_f32_e32 v0, v0, v34
	v_lshlrev_b64 v[34:35], 10, v[120:121]
	v_lshl_add_u64 v[34:35], s[16:17], 0, v[34:35]
	v_rcp_f32_e32 v40, v0
	v_lshl_add_u64 v[34:35], v[34:35], 0, s[46:47]
	v_lshlrev_b32_e32 v0, 1, v80
	v_lshl_add_u64 v[38:39], v[34:35], 0, v[0:1]
	ds_read_u16 v46, v145
	ds_read_u16 v47, v145 offset:264
	ds_read_u16 v48, v145 offset:528
	ds_read_u16 v49, v145 offset:792
	ds_read_u16 v50, v145 offset:4224
	ds_read_u16 v51, v145 offset:4488
	ds_read_u16 v52, v145 offset:4752
	ds_read_u16 v53, v145 offset:5016
	ds_read_u16 v54, v145 offset:8448
	ds_read_u16 v55, v145 offset:8712
	ds_read_u16 v56, v145 offset:8976
	ds_read_u16 v57, v145 offset:9240
	ds_read_u16 v58, v145 offset:12672
	ds_read_u16 v59, v145 offset:12936
	ds_read_u16 v60, v145 offset:13200
	s_waitcnt lgkmcnt(7)
	ds_read_u16 v61, v145 offset:13464
	v_lshl_or_b32 v62, v47, 16, v46
	v_lshl_or_b32 v63, v49, 16, v48
	v_lshl_or_b32 v64, v51, 16, v50
	v_lshl_or_b32 v65, v53, 16, v52
	s_nop 1
	v_mfma_f32_16x16x32_bf16 v[34:37], v[62:65], v[2:5], 0
	ds_read_u16 v46, v145 offset:16896
	ds_read_u16 v47, v145 offset:17160
	ds_read_u16 v48, v145 offset:17424
	ds_read_u16 v49, v145 offset:17688
	ds_read_u16 v50, v145 offset:21120
	ds_read_u16 v51, v145 offset:21384
	ds_read_u16 v52, v145 offset:21648
	s_waitcnt lgkmcnt(7)
	ds_read_u16 v53, v145 offset:21912
	v_lshl_or_b32 v42, v55, 16, v54
	v_lshl_or_b32 v43, v57, 16, v56
	v_lshl_or_b32 v44, v59, 16, v58
	v_lshl_or_b32 v45, v61, 16, v60
	s_nop 1
	v_mfma_f32_16x16x32_bf16 v[34:37], v[42:45], v[6:9], v[34:37]
	ds_read_u16 v54, v145 offset:25344
	ds_read_u16 v55, v145 offset:25608
	ds_read_u16 v56, v145 offset:25872
	ds_read_u16 v57, v145 offset:26136
	ds_read_u16 v58, v145 offset:29568
	ds_read_u16 v59, v145 offset:29832
	ds_read_u16 v60, v145 offset:30096
	s_waitcnt lgkmcnt(7)
	ds_read_u16 v61, v145 offset:30360
	v_lshl_or_b32 v62, v47, 16, v46
	v_lshl_or_b32 v63, v49, 16, v48
	v_lshl_or_b32 v64, v51, 16, v50
	v_lshl_or_b32 v65, v53, 16, v52
	s_nop 1
	v_mfma_f32_16x16x32_bf16 v[34:37], v[62:65], v[10:13], v[34:37]
	ds_read_u16 v46, v145 offset:33792
	ds_read_u16 v47, v145 offset:34056
	ds_read_u16 v48, v145 offset:34320
	ds_read_u16 v49, v145 offset:34584
	ds_read_u16 v50, v145 offset:38016
	ds_read_u16 v51, v145 offset:38280
	ds_read_u16 v52, v145 offset:38544
	s_waitcnt lgkmcnt(7)
	ds_read_u16 v53, v145 offset:38808
	v_lshl_or_b32 v42, v55, 16, v54
	v_lshl_or_b32 v43, v57, 16, v56
	v_lshl_or_b32 v44, v59, 16, v58
	v_lshl_or_b32 v45, v61, 16, v60
	s_nop 1
	v_mfma_f32_16x16x32_bf16 v[34:37], v[42:45], v[14:17], v[34:37]
	ds_read_u16 v54, v145 offset:42240
	ds_read_u16 v55, v145 offset:42504
	ds_read_u16 v56, v145 offset:42768
	ds_read_u16 v57, v145 offset:43032
	ds_read_u16 v58, v145 offset:46464
	ds_read_u16 v59, v145 offset:46728
	ds_read_u16 v60, v145 offset:46992
	s_waitcnt lgkmcnt(7)
	ds_read_u16 v61, v145 offset:47256
	v_lshl_or_b32 v62, v47, 16, v46
	v_lshl_or_b32 v63, v49, 16, v48
	v_lshl_or_b32 v64, v51, 16, v50
	v_lshl_or_b32 v65, v53, 16, v52
	s_nop 1
	v_mfma_f32_16x16x32_bf16 v[34:37], v[62:65], v[18:21], v[34:37]
	ds_read_u16 v46, v145 offset:50688
	ds_read_u16 v47, v145 offset:50952
	ds_read_u16 v48, v145 offset:51216
	ds_read_u16 v49, v145 offset:51480
	ds_read_u16 v50, v145 offset:54912
	ds_read_u16 v51, v145 offset:55176
	ds_read_u16 v52, v145 offset:55440
	s_waitcnt lgkmcnt(7)
	ds_read_u16 v53, v145 offset:55704
	v_lshl_or_b32 v42, v55, 16, v54
	v_lshl_or_b32 v43, v57, 16, v56
	v_lshl_or_b32 v44, v59, 16, v58
	v_lshl_or_b32 v45, v61, 16, v60
	s_nop 1
	v_mfma_f32_16x16x32_bf16 v[34:37], v[42:45], v[22:25], v[34:37]
	ds_read_u16 v54, v145 offset:59136
	ds_read_u16 v55, v145 offset:59400
	ds_read_u16 v56, v145 offset:59664
	ds_read_u16 v57, v145 offset:59928
	ds_read_u16 v58, v145 offset:63360
	ds_read_u16 v59, v145 offset:63624
	ds_read_u16 v60, v145 offset:63888
	s_waitcnt lgkmcnt(7)
	ds_read_u16 v61, v145 offset:64152
	v_lshl_or_b32 v62, v47, 16, v46
	v_lshl_or_b32 v63, v49, 16, v48
	v_lshl_or_b32 v64, v51, 16, v50
	v_lshl_or_b32 v65, v53, 16, v52
	s_nop 1
	v_mfma_f32_16x16x32_bf16 v[34:37], v[62:65], v[26:29], v[34:37]
	ds_read_u16 v46, v145 offset:32
	ds_read_u16 v47, v145 offset:296
	ds_read_u16 v48, v145 offset:560
	ds_read_u16 v49, v145 offset:824
	ds_read_u16 v50, v145 offset:4256
	ds_read_u16 v51, v145 offset:4520
	ds_read_u16 v52, v145 offset:4784
	s_waitcnt lgkmcnt(7)
	ds_read_u16 v53, v145 offset:5048
	v_lshl_or_b32 v42, v55, 16, v54
	v_lshl_or_b32 v43, v57, 16, v56
	v_lshl_or_b32 v44, v59, 16, v58
	v_lshl_or_b32 v45, v61, 16, v60
	s_nop 1
	v_mfma_f32_16x16x32_bf16 v[34:37], v[42:45], v[30:33], v[34:37]
	s_and_saveexec_b64 s[24:25], s[8:9]
	s_cbranch_execz .LBB0_127
	s_nop 5
	v_mov_b32_e32 v43, v36
	v_mov_b32_e32 v36, v35
	v_mov_b32_e32 v42, v34
	v_pk_mul_f32 v[34:35], v[40:41], v[36:37] op_sel_hi:[0,1]
	v_pk_mul_f32 v[42:43], v[40:41], v[42:43] op_sel_hi:[0,1]
	v_and_b32_sdwa v37, v35, v202 dst_sel:DWORD dst_unused:UNUSED_PAD src0_sel:WORD_1 src1_sel:DWORD
	v_and_b32_sdwa v41, v34, v202 dst_sel:DWORD dst_unused:UNUSED_PAD src0_sel:WORD_1 src1_sel:DWORD
	v_and_b32_sdwa v0, v43, v202 dst_sel:DWORD dst_unused:UNUSED_PAD src0_sel:WORD_1 src1_sel:DWORD
	v_and_b32_sdwa v36, v42, v202 dst_sel:DWORD dst_unused:UNUSED_PAD src0_sel:WORD_1 src1_sel:DWORD
	v_add3_u32 v35, v35, v37, s60
	v_add3_u32 v34, v34, v41, s60
	v_add3_u32 v36, v42, v36, s60
	v_add3_u32 v0, v43, v0, s60
	v_and_b32_e32 v35, 0xffff0000, v35
	v_and_b32_e32 v34, 0xffff0000, v34
	v_or_b32_sdwa v35, v35, v0 dst_sel:DWORD dst_unused:UNUSED_PAD src0_sel:DWORD src1_sel:WORD_1
	v_or_b32_sdwa v34, v34, v36 dst_sel:DWORD dst_unused:UNUSED_PAD src0_sel:DWORD src1_sel:WORD_1
	global_store_dwordx2 v[38:39], v[34:35], off
.LBB0_127:
	s_or_b64 exec, exec, s[24:25]
	ds_read_u16 v54, v145 offset:8480
	ds_read_u16 v55, v145 offset:8744
	ds_read_u16 v56, v145 offset:9008
	ds_read_u16 v57, v145 offset:9272
	ds_read_u16 v58, v145 offset:12704
	ds_read_u16 v59, v145 offset:12968
	ds_read_u16 v60, v145 offset:13232
	s_waitcnt lgkmcnt(7)
	ds_read_u16 v61, v145 offset:13496
	v_lshl_or_b32 v62, v47, 16, v46
	v_lshl_or_b32 v63, v49, 16, v48
	v_lshl_or_b32 v64, v51, 16, v50
	v_lshl_or_b32 v65, v53, 16, v52
	s_nop 1
	v_mfma_f32_16x16x32_bf16 v[34:37], v[62:65], v[2:5], 0
	ds_read_u16 v46, v145 offset:16928
	ds_read_u16 v47, v145 offset:17192
	ds_read_u16 v48, v145 offset:17456
	ds_read_u16 v49, v145 offset:17720
	ds_read_u16 v50, v145 offset:21152
	ds_read_u16 v51, v145 offset:21416
	ds_read_u16 v52, v145 offset:21680
	s_waitcnt lgkmcnt(7)
	ds_read_u16 v53, v145 offset:21944
	v_lshl_or_b32 v42, v55, 16, v54
	v_lshl_or_b32 v43, v57, 16, v56
	v_lshl_or_b32 v44, v59, 16, v58
	v_lshl_or_b32 v45, v61, 16, v60
	s_nop 1
	v_mfma_f32_16x16x32_bf16 v[34:37], v[42:45], v[6:9], v[34:37]
	ds_read_u16 v54, v145 offset:25376
	ds_read_u16 v55, v145 offset:25640
	ds_read_u16 v56, v145 offset:25904
	ds_read_u16 v57, v145 offset:26168
	ds_read_u16 v58, v145 offset:29600
	ds_read_u16 v59, v145 offset:29864
	ds_read_u16 v60, v145 offset:30128
	s_waitcnt lgkmcnt(7)
	ds_read_u16 v61, v145 offset:30392
	v_lshl_or_b32 v62, v47, 16, v46
	v_lshl_or_b32 v63, v49, 16, v48
	v_lshl_or_b32 v64, v51, 16, v50
	v_lshl_or_b32 v65, v53, 16, v52
	s_nop 1
	v_mfma_f32_16x16x32_bf16 v[34:37], v[62:65], v[10:13], v[34:37]
	ds_read_u16 v46, v145 offset:33824
	ds_read_u16 v47, v145 offset:34088
	ds_read_u16 v48, v145 offset:34352
	ds_read_u16 v49, v145 offset:34616
	ds_read_u16 v50, v145 offset:38048
	ds_read_u16 v51, v145 offset:38312
	ds_read_u16 v52, v145 offset:38576
	s_waitcnt lgkmcnt(7)
	ds_read_u16 v53, v145 offset:38840
	v_lshl_or_b32 v42, v55, 16, v54
	v_lshl_or_b32 v43, v57, 16, v56
	v_lshl_or_b32 v44, v59, 16, v58
	v_lshl_or_b32 v45, v61, 16, v60
	s_nop 1
	v_mfma_f32_16x16x32_bf16 v[34:37], v[42:45], v[14:17], v[34:37]
	ds_read_u16 v54, v145 offset:42272
	ds_read_u16 v55, v145 offset:42536
	ds_read_u16 v56, v145 offset:42800
	ds_read_u16 v57, v145 offset:43064
	ds_read_u16 v58, v145 offset:46496
	ds_read_u16 v59, v145 offset:46760
	ds_read_u16 v60, v145 offset:47024
	s_waitcnt lgkmcnt(7)
	ds_read_u16 v61, v145 offset:47288
	v_lshl_or_b32 v62, v47, 16, v46
	v_lshl_or_b32 v63, v49, 16, v48
	v_lshl_or_b32 v64, v51, 16, v50
	v_lshl_or_b32 v65, v53, 16, v52
	s_nop 1
	v_mfma_f32_16x16x32_bf16 v[34:37], v[62:65], v[18:21], v[34:37]
	ds_read_u16 v46, v145 offset:50720
	ds_read_u16 v47, v145 offset:50984
	ds_read_u16 v48, v145 offset:51248
	ds_read_u16 v49, v145 offset:51512
	ds_read_u16 v50, v145 offset:54944
	ds_read_u16 v51, v145 offset:55208
	ds_read_u16 v52, v145 offset:55472
	s_waitcnt lgkmcnt(7)
	ds_read_u16 v53, v145 offset:55736
	v_lshl_or_b32 v42, v55, 16, v54
	v_lshl_or_b32 v43, v57, 16, v56
	v_lshl_or_b32 v44, v59, 16, v58
	v_lshl_or_b32 v45, v61, 16, v60
	s_nop 1
	v_mfma_f32_16x16x32_bf16 v[34:37], v[42:45], v[22:25], v[34:37]
	ds_read_u16 v54, v145 offset:59168
	ds_read_u16 v55, v145 offset:59432
	ds_read_u16 v56, v145 offset:59696
	ds_read_u16 v57, v145 offset:59960
	ds_read_u16 v58, v145 offset:63392
	ds_read_u16 v59, v145 offset:63656
	ds_read_u16 v60, v145 offset:63920
	s_waitcnt lgkmcnt(7)
	ds_read_u16 v61, v145 offset:64184
	v_lshl_or_b32 v62, v47, 16, v46
	v_lshl_or_b32 v63, v49, 16, v48
	v_lshl_or_b32 v64, v51, 16, v50
	v_lshl_or_b32 v65, v53, 16, v52
	s_nop 1
	v_mfma_f32_16x16x32_bf16 v[34:37], v[62:65], v[26:29], v[34:37]
	ds_read_u16 v46, v145 offset:64
	ds_read_u16 v47, v145 offset:328
	ds_read_u16 v48, v145 offset:592
	ds_read_u16 v49, v145 offset:856
	ds_read_u16 v50, v145 offset:4288
	ds_read_u16 v51, v145 offset:4552
	ds_read_u16 v52, v145 offset:4816
	s_waitcnt lgkmcnt(7)
	ds_read_u16 v53, v145 offset:5080
	v_lshl_or_b32 v42, v55, 16, v54
	v_lshl_or_b32 v43, v57, 16, v56
	v_lshl_or_b32 v44, v59, 16, v58
	v_lshl_or_b32 v45, v61, 16, v60
	s_nop 1
	v_mfma_f32_16x16x32_bf16 v[34:37], v[42:45], v[30:33], v[34:37]
	s_and_saveexec_b64 s[24:25], s[8:9]
	s_cbranch_execz .LBB0_129
	s_nop 5
	v_mov_b32_e32 v43, v36
	v_mov_b32_e32 v36, v35
	v_mov_b32_e32 v42, v34
	v_pk_mul_f32 v[34:35], v[40:41], v[36:37] op_sel_hi:[0,1]
	v_pk_mul_f32 v[42:43], v[40:41], v[42:43] op_sel_hi:[0,1]
	v_and_b32_sdwa v37, v35, v202 dst_sel:DWORD dst_unused:UNUSED_PAD src0_sel:WORD_1 src1_sel:DWORD
	v_and_b32_sdwa v41, v34, v202 dst_sel:DWORD dst_unused:UNUSED_PAD src0_sel:WORD_1 src1_sel:DWORD
	v_and_b32_sdwa v0, v43, v202 dst_sel:DWORD dst_unused:UNUSED_PAD src0_sel:WORD_1 src1_sel:DWORD
	v_and_b32_sdwa v36, v42, v202 dst_sel:DWORD dst_unused:UNUSED_PAD src0_sel:WORD_1 src1_sel:DWORD
	v_add3_u32 v35, v35, v37, s60
	v_add3_u32 v34, v34, v41, s60
	v_add3_u32 v36, v42, v36, s60
	v_add3_u32 v0, v43, v0, s60
	v_and_b32_e32 v35, 0xffff0000, v35
	v_and_b32_e32 v34, 0xffff0000, v34
	v_or_b32_sdwa v35, v35, v0 dst_sel:DWORD dst_unused:UNUSED_PAD src0_sel:DWORD src1_sel:WORD_1
	v_or_b32_sdwa v34, v34, v36 dst_sel:DWORD dst_unused:UNUSED_PAD src0_sel:DWORD src1_sel:WORD_1
	global_store_dwordx2 v[38:39], v[34:35], off offset:32
.LBB0_129:
	s_or_b64 exec, exec, s[24:25]
	ds_read_u16 v54, v145 offset:8512
	ds_read_u16 v55, v145 offset:8776
	ds_read_u16 v56, v145 offset:9040
	ds_read_u16 v57, v145 offset:9304
	ds_read_u16 v58, v145 offset:12736
	ds_read_u16 v59, v145 offset:13000
	ds_read_u16 v60, v145 offset:13264
	s_waitcnt lgkmcnt(7)
	ds_read_u16 v61, v145 offset:13528
	v_lshl_or_b32 v62, v47, 16, v46
	v_lshl_or_b32 v63, v49, 16, v48
	v_lshl_or_b32 v64, v51, 16, v50
	v_lshl_or_b32 v65, v53, 16, v52
	s_nop 1
	v_mfma_f32_16x16x32_bf16 v[34:37], v[62:65], v[2:5], 0
	ds_read_u16 v46, v145 offset:16960
	ds_read_u16 v47, v145 offset:17224
	ds_read_u16 v48, v145 offset:17488
	ds_read_u16 v49, v145 offset:17752
	ds_read_u16 v50, v145 offset:21184
	ds_read_u16 v51, v145 offset:21448
	ds_read_u16 v52, v145 offset:21712
	s_waitcnt lgkmcnt(7)
	ds_read_u16 v53, v145 offset:21976
	v_lshl_or_b32 v42, v55, 16, v54
	v_lshl_or_b32 v43, v57, 16, v56
	v_lshl_or_b32 v44, v59, 16, v58
	v_lshl_or_b32 v45, v61, 16, v60
	s_nop 1
	v_mfma_f32_16x16x32_bf16 v[34:37], v[42:45], v[6:9], v[34:37]
	ds_read_u16 v54, v145 offset:25408
	ds_read_u16 v55, v145 offset:25672
	ds_read_u16 v56, v145 offset:25936
	ds_read_u16 v57, v145 offset:26200
	ds_read_u16 v58, v145 offset:29632
	ds_read_u16 v59, v145 offset:29896
	ds_read_u16 v60, v145 offset:30160
	s_waitcnt lgkmcnt(7)
	ds_read_u16 v61, v145 offset:30424
	v_lshl_or_b32 v62, v47, 16, v46
	v_lshl_or_b32 v63, v49, 16, v48
	v_lshl_or_b32 v64, v51, 16, v50
	v_lshl_or_b32 v65, v53, 16, v52
	s_nop 1
	v_mfma_f32_16x16x32_bf16 v[34:37], v[62:65], v[10:13], v[34:37]
	ds_read_u16 v46, v145 offset:33856
	ds_read_u16 v47, v145 offset:34120
	ds_read_u16 v48, v145 offset:34384
	ds_read_u16 v49, v145 offset:34648
	ds_read_u16 v50, v145 offset:38080
	ds_read_u16 v51, v145 offset:38344
	ds_read_u16 v52, v145 offset:38608
	s_waitcnt lgkmcnt(7)
	ds_read_u16 v53, v145 offset:38872
	v_lshl_or_b32 v42, v55, 16, v54
	v_lshl_or_b32 v43, v57, 16, v56
	v_lshl_or_b32 v44, v59, 16, v58
	v_lshl_or_b32 v45, v61, 16, v60
	s_nop 1
	v_mfma_f32_16x16x32_bf16 v[34:37], v[42:45], v[14:17], v[34:37]
	ds_read_u16 v54, v145 offset:42304
	ds_read_u16 v55, v145 offset:42568
	ds_read_u16 v56, v145 offset:42832
	ds_read_u16 v57, v145 offset:43096
	ds_read_u16 v58, v145 offset:46528
	ds_read_u16 v59, v145 offset:46792
	ds_read_u16 v60, v145 offset:47056
	s_waitcnt lgkmcnt(7)
	ds_read_u16 v61, v145 offset:47320
	v_lshl_or_b32 v62, v47, 16, v46
	v_lshl_or_b32 v63, v49, 16, v48
	v_lshl_or_b32 v64, v51, 16, v50
	v_lshl_or_b32 v65, v53, 16, v52
	s_nop 1
	v_mfma_f32_16x16x32_bf16 v[34:37], v[62:65], v[18:21], v[34:37]
	ds_read_u16 v46, v145 offset:50752
	ds_read_u16 v47, v145 offset:51016
	ds_read_u16 v48, v145 offset:51280
	ds_read_u16 v49, v145 offset:51544
	ds_read_u16 v50, v145 offset:54976
	ds_read_u16 v51, v145 offset:55240
	ds_read_u16 v52, v145 offset:55504
	s_waitcnt lgkmcnt(7)
	ds_read_u16 v53, v145 offset:55768
	v_lshl_or_b32 v42, v55, 16, v54
	v_lshl_or_b32 v43, v57, 16, v56
	v_lshl_or_b32 v44, v59, 16, v58
	v_lshl_or_b32 v45, v61, 16, v60
	s_nop 1
	v_mfma_f32_16x16x32_bf16 v[34:37], v[42:45], v[22:25], v[34:37]
	ds_read_u16 v54, v145 offset:59200
	ds_read_u16 v55, v145 offset:59464
	ds_read_u16 v56, v145 offset:59728
	ds_read_u16 v57, v145 offset:59992
	ds_read_u16 v58, v145 offset:63424
	ds_read_u16 v59, v145 offset:63688
	ds_read_u16 v60, v145 offset:63952
	s_waitcnt lgkmcnt(7)
	ds_read_u16 v61, v145 offset:64216
	v_lshl_or_b32 v62, v47, 16, v46
	v_lshl_or_b32 v63, v49, 16, v48
	v_lshl_or_b32 v64, v51, 16, v50
	v_lshl_or_b32 v65, v53, 16, v52
	s_nop 1
	v_mfma_f32_16x16x32_bf16 v[34:37], v[62:65], v[26:29], v[34:37]
	ds_read_u16 v46, v145 offset:96
	ds_read_u16 v47, v145 offset:360
	ds_read_u16 v48, v145 offset:624
	ds_read_u16 v49, v145 offset:888
	ds_read_u16 v50, v145 offset:4320
	ds_read_u16 v51, v145 offset:4584
	ds_read_u16 v52, v145 offset:4848
	s_waitcnt lgkmcnt(7)
	ds_read_u16 v53, v145 offset:5112
	v_lshl_or_b32 v42, v55, 16, v54
	v_lshl_or_b32 v43, v57, 16, v56
	v_lshl_or_b32 v44, v59, 16, v58
	v_lshl_or_b32 v45, v61, 16, v60
	s_nop 1
	v_mfma_f32_16x16x32_bf16 v[34:37], v[42:45], v[30:33], v[34:37]
	s_and_saveexec_b64 s[24:25], s[8:9]
	s_cbranch_execz .LBB0_131
	s_nop 5
	v_mov_b32_e32 v43, v36
	v_mov_b32_e32 v36, v35
	v_mov_b32_e32 v42, v34
	v_pk_mul_f32 v[34:35], v[40:41], v[36:37] op_sel_hi:[0,1]
	v_pk_mul_f32 v[42:43], v[40:41], v[42:43] op_sel_hi:[0,1]
	v_and_b32_sdwa v37, v35, v202 dst_sel:DWORD dst_unused:UNUSED_PAD src0_sel:WORD_1 src1_sel:DWORD
	v_and_b32_sdwa v41, v34, v202 dst_sel:DWORD dst_unused:UNUSED_PAD src0_sel:WORD_1 src1_sel:DWORD
	v_and_b32_sdwa v0, v43, v202 dst_sel:DWORD dst_unused:UNUSED_PAD src0_sel:WORD_1 src1_sel:DWORD
	v_and_b32_sdwa v36, v42, v202 dst_sel:DWORD dst_unused:UNUSED_PAD src0_sel:WORD_1 src1_sel:DWORD
	v_add3_u32 v35, v35, v37, s60
	v_add3_u32 v34, v34, v41, s60
	v_add3_u32 v36, v42, v36, s60
	v_add3_u32 v0, v43, v0, s60
	v_and_b32_e32 v35, 0xffff0000, v35
	v_and_b32_e32 v34, 0xffff0000, v34
	v_or_b32_sdwa v35, v35, v0 dst_sel:DWORD dst_unused:UNUSED_PAD src0_sel:DWORD src1_sel:WORD_1
	v_or_b32_sdwa v34, v34, v36 dst_sel:DWORD dst_unused:UNUSED_PAD src0_sel:DWORD src1_sel:WORD_1
	global_store_dwordx2 v[38:39], v[34:35], off offset:64
.LBB0_131:
	s_or_b64 exec, exec, s[24:25]
	ds_read_u16 v54, v145 offset:8544
	ds_read_u16 v55, v145 offset:8808
	ds_read_u16 v56, v145 offset:9072
	ds_read_u16 v57, v145 offset:9336
	ds_read_u16 v58, v145 offset:12768
	ds_read_u16 v59, v145 offset:13032
	ds_read_u16 v60, v145 offset:13296
	s_waitcnt lgkmcnt(7)
	ds_read_u16 v61, v145 offset:13560
	v_lshl_or_b32 v62, v47, 16, v46
	v_lshl_or_b32 v63, v49, 16, v48
	v_lshl_or_b32 v64, v51, 16, v50
	v_lshl_or_b32 v65, v53, 16, v52
	s_nop 1
	v_mfma_f32_16x16x32_bf16 v[34:37], v[62:65], v[2:5], 0
	ds_read_u16 v46, v145 offset:16992
	ds_read_u16 v47, v145 offset:17256
	ds_read_u16 v48, v145 offset:17520
	ds_read_u16 v49, v145 offset:17784
	ds_read_u16 v50, v145 offset:21216
	ds_read_u16 v51, v145 offset:21480
	ds_read_u16 v52, v145 offset:21744
	s_waitcnt lgkmcnt(7)
	ds_read_u16 v53, v145 offset:22008
	v_lshl_or_b32 v42, v55, 16, v54
	v_lshl_or_b32 v43, v57, 16, v56
	v_lshl_or_b32 v44, v59, 16, v58
	v_lshl_or_b32 v45, v61, 16, v60
	s_nop 1
	v_mfma_f32_16x16x32_bf16 v[34:37], v[42:45], v[6:9], v[34:37]
	ds_read_u16 v54, v145 offset:25440
	ds_read_u16 v55, v145 offset:25704
	ds_read_u16 v56, v145 offset:25968
	ds_read_u16 v57, v145 offset:26232
	ds_read_u16 v58, v145 offset:29664
	ds_read_u16 v59, v145 offset:29928
	ds_read_u16 v60, v145 offset:30192
	s_waitcnt lgkmcnt(7)
	ds_read_u16 v61, v145 offset:30456
	v_lshl_or_b32 v62, v47, 16, v46
	v_lshl_or_b32 v63, v49, 16, v48
	v_lshl_or_b32 v64, v51, 16, v50
	v_lshl_or_b32 v65, v53, 16, v52
	s_nop 1
	v_mfma_f32_16x16x32_bf16 v[34:37], v[62:65], v[10:13], v[34:37]
	ds_read_u16 v46, v145 offset:33888
	ds_read_u16 v47, v145 offset:34152
	ds_read_u16 v48, v145 offset:34416
	ds_read_u16 v49, v145 offset:34680
	ds_read_u16 v50, v145 offset:38112
	ds_read_u16 v51, v145 offset:38376
	ds_read_u16 v52, v145 offset:38640
	s_waitcnt lgkmcnt(7)
	ds_read_u16 v53, v145 offset:38904
	v_lshl_or_b32 v42, v55, 16, v54
	v_lshl_or_b32 v43, v57, 16, v56
	v_lshl_or_b32 v44, v59, 16, v58
	v_lshl_or_b32 v45, v61, 16, v60
	s_nop 1
	v_mfma_f32_16x16x32_bf16 v[34:37], v[42:45], v[14:17], v[34:37]
	ds_read_u16 v54, v145 offset:42336
	ds_read_u16 v55, v145 offset:42600
	ds_read_u16 v56, v145 offset:42864
	ds_read_u16 v57, v145 offset:43128
	ds_read_u16 v58, v145 offset:46560
	ds_read_u16 v59, v145 offset:46824
	ds_read_u16 v60, v145 offset:47088
	s_waitcnt lgkmcnt(7)
	ds_read_u16 v61, v145 offset:47352
	v_lshl_or_b32 v62, v47, 16, v46
	v_lshl_or_b32 v63, v49, 16, v48
	v_lshl_or_b32 v64, v51, 16, v50
	v_lshl_or_b32 v65, v53, 16, v52
	s_nop 1
	v_mfma_f32_16x16x32_bf16 v[34:37], v[62:65], v[18:21], v[34:37]
	ds_read_u16 v46, v145 offset:50784
	ds_read_u16 v47, v145 offset:51048
	ds_read_u16 v48, v145 offset:51312
	ds_read_u16 v49, v145 offset:51576
	ds_read_u16 v50, v145 offset:55008
	ds_read_u16 v51, v145 offset:55272
	ds_read_u16 v52, v145 offset:55536
	s_waitcnt lgkmcnt(7)
	ds_read_u16 v53, v145 offset:55800
	v_lshl_or_b32 v42, v55, 16, v54
	v_lshl_or_b32 v43, v57, 16, v56
	v_lshl_or_b32 v44, v59, 16, v58
	v_lshl_or_b32 v45, v61, 16, v60
	s_nop 1
	v_mfma_f32_16x16x32_bf16 v[34:37], v[42:45], v[22:25], v[34:37]
	ds_read_u16 v54, v145 offset:59232
	ds_read_u16 v55, v145 offset:59496
	ds_read_u16 v56, v145 offset:59760
	ds_read_u16 v57, v145 offset:60024
	ds_read_u16 v58, v145 offset:63456
	ds_read_u16 v59, v145 offset:63720
	ds_read_u16 v60, v145 offset:63984
	s_waitcnt lgkmcnt(7)
	ds_read_u16 v61, v145 offset:64248
	v_lshl_or_b32 v62, v47, 16, v46
	v_lshl_or_b32 v63, v49, 16, v48
	v_lshl_or_b32 v64, v51, 16, v50
	v_lshl_or_b32 v65, v53, 16, v52
	s_nop 1
	v_mfma_f32_16x16x32_bf16 v[34:37], v[62:65], v[26:29], v[34:37]
	ds_read_u16 v46, v145 offset:128
	ds_read_u16 v47, v145 offset:392
	ds_read_u16 v48, v145 offset:656
	ds_read_u16 v49, v145 offset:920
	ds_read_u16 v50, v145 offset:4352
	ds_read_u16 v51, v145 offset:4616
	ds_read_u16 v52, v145 offset:4880
	s_waitcnt lgkmcnt(7)
	ds_read_u16 v53, v145 offset:5144
	v_lshl_or_b32 v42, v55, 16, v54
	v_lshl_or_b32 v43, v57, 16, v56
	v_lshl_or_b32 v44, v59, 16, v58
	v_lshl_or_b32 v45, v61, 16, v60
	s_nop 1
	v_mfma_f32_16x16x32_bf16 v[34:37], v[42:45], v[30:33], v[34:37]
	s_and_saveexec_b64 s[24:25], s[8:9]
	s_cbranch_execz .LBB0_133
	s_nop 5
	v_mov_b32_e32 v43, v36
	v_mov_b32_e32 v36, v35
	v_mov_b32_e32 v42, v34
	v_pk_mul_f32 v[34:35], v[40:41], v[36:37] op_sel_hi:[0,1]
	v_pk_mul_f32 v[42:43], v[40:41], v[42:43] op_sel_hi:[0,1]
	v_and_b32_sdwa v37, v35, v202 dst_sel:DWORD dst_unused:UNUSED_PAD src0_sel:WORD_1 src1_sel:DWORD
	v_and_b32_sdwa v41, v34, v202 dst_sel:DWORD dst_unused:UNUSED_PAD src0_sel:WORD_1 src1_sel:DWORD
	v_and_b32_sdwa v0, v43, v202 dst_sel:DWORD dst_unused:UNUSED_PAD src0_sel:WORD_1 src1_sel:DWORD
	v_and_b32_sdwa v36, v42, v202 dst_sel:DWORD dst_unused:UNUSED_PAD src0_sel:WORD_1 src1_sel:DWORD
	v_add3_u32 v35, v35, v37, s60
	v_add3_u32 v34, v34, v41, s60
	v_add3_u32 v36, v42, v36, s60
	v_add3_u32 v0, v43, v0, s60
	v_and_b32_e32 v35, 0xffff0000, v35
	v_and_b32_e32 v34, 0xffff0000, v34
	v_or_b32_sdwa v35, v35, v0 dst_sel:DWORD dst_unused:UNUSED_PAD src0_sel:DWORD src1_sel:WORD_1
	v_or_b32_sdwa v34, v34, v36 dst_sel:DWORD dst_unused:UNUSED_PAD src0_sel:DWORD src1_sel:WORD_1
	global_store_dwordx2 v[38:39], v[34:35], off offset:96
.LBB0_133:
	s_or_b64 exec, exec, s[24:25]
	ds_read_u16 v54, v145 offset:8576
	ds_read_u16 v55, v145 offset:8840
	ds_read_u16 v56, v145 offset:9104
	ds_read_u16 v57, v145 offset:9368
	ds_read_u16 v58, v145 offset:12800
	ds_read_u16 v59, v145 offset:13064
	ds_read_u16 v60, v145 offset:13328
	s_waitcnt lgkmcnt(7)
	ds_read_u16 v61, v145 offset:13592
	v_lshl_or_b32 v62, v47, 16, v46
	v_lshl_or_b32 v63, v49, 16, v48
	v_lshl_or_b32 v64, v51, 16, v50
	v_lshl_or_b32 v65, v53, 16, v52
	s_nop 1
	v_mfma_f32_16x16x32_bf16 v[34:37], v[62:65], v[2:5], 0
	ds_read_u16 v46, v145 offset:17024
	ds_read_u16 v47, v145 offset:17288
	ds_read_u16 v48, v145 offset:17552
	ds_read_u16 v49, v145 offset:17816
	ds_read_u16 v50, v145 offset:21248
	ds_read_u16 v51, v145 offset:21512
	ds_read_u16 v52, v145 offset:21776
	s_waitcnt lgkmcnt(7)
	ds_read_u16 v53, v145 offset:22040
	v_lshl_or_b32 v42, v55, 16, v54
	v_lshl_or_b32 v43, v57, 16, v56
	v_lshl_or_b32 v44, v59, 16, v58
	v_lshl_or_b32 v45, v61, 16, v60
	s_nop 1
	v_mfma_f32_16x16x32_bf16 v[34:37], v[42:45], v[6:9], v[34:37]
	ds_read_u16 v54, v145 offset:25472
	ds_read_u16 v55, v145 offset:25736
	ds_read_u16 v56, v145 offset:26000
	ds_read_u16 v57, v145 offset:26264
	ds_read_u16 v58, v145 offset:29696
	ds_read_u16 v59, v145 offset:29960
	ds_read_u16 v60, v145 offset:30224
	s_waitcnt lgkmcnt(7)
	ds_read_u16 v61, v145 offset:30488
	v_lshl_or_b32 v62, v47, 16, v46
	v_lshl_or_b32 v63, v49, 16, v48
	v_lshl_or_b32 v64, v51, 16, v50
	v_lshl_or_b32 v65, v53, 16, v52
	s_nop 1
	v_mfma_f32_16x16x32_bf16 v[34:37], v[62:65], v[10:13], v[34:37]
	ds_read_u16 v46, v145 offset:33920
	ds_read_u16 v47, v145 offset:34184
	ds_read_u16 v48, v145 offset:34448
	ds_read_u16 v49, v145 offset:34712
	ds_read_u16 v50, v145 offset:38144
	ds_read_u16 v51, v145 offset:38408
	ds_read_u16 v52, v145 offset:38672
	s_waitcnt lgkmcnt(7)
	ds_read_u16 v53, v145 offset:38936
	v_lshl_or_b32 v42, v55, 16, v54
	v_lshl_or_b32 v43, v57, 16, v56
	v_lshl_or_b32 v44, v59, 16, v58
	v_lshl_or_b32 v45, v61, 16, v60
	s_nop 1
	v_mfma_f32_16x16x32_bf16 v[34:37], v[42:45], v[14:17], v[34:37]
	ds_read_u16 v54, v145 offset:42368
	ds_read_u16 v55, v145 offset:42632
	ds_read_u16 v56, v145 offset:42896
	ds_read_u16 v57, v145 offset:43160
	ds_read_u16 v58, v145 offset:46592
	ds_read_u16 v59, v145 offset:46856
	ds_read_u16 v60, v145 offset:47120
	s_waitcnt lgkmcnt(7)
	ds_read_u16 v61, v145 offset:47384
	v_lshl_or_b32 v62, v47, 16, v46
	v_lshl_or_b32 v63, v49, 16, v48
	v_lshl_or_b32 v64, v51, 16, v50
	v_lshl_or_b32 v65, v53, 16, v52
	s_nop 1
	v_mfma_f32_16x16x32_bf16 v[34:37], v[62:65], v[18:21], v[34:37]
	ds_read_u16 v46, v145 offset:50816
	ds_read_u16 v47, v145 offset:51080
	ds_read_u16 v48, v145 offset:51344
	ds_read_u16 v49, v145 offset:51608
	ds_read_u16 v50, v145 offset:55040
	ds_read_u16 v51, v145 offset:55304
	ds_read_u16 v52, v145 offset:55568
	s_waitcnt lgkmcnt(7)
	ds_read_u16 v53, v145 offset:55832
	v_lshl_or_b32 v42, v55, 16, v54
	v_lshl_or_b32 v43, v57, 16, v56
	v_lshl_or_b32 v44, v59, 16, v58
	v_lshl_or_b32 v45, v61, 16, v60
	s_nop 1
	v_mfma_f32_16x16x32_bf16 v[34:37], v[42:45], v[22:25], v[34:37]
	ds_read_u16 v54, v145 offset:59264
	ds_read_u16 v55, v145 offset:59528
	ds_read_u16 v56, v145 offset:59792
	ds_read_u16 v57, v145 offset:60056
	ds_read_u16 v58, v145 offset:63488
	ds_read_u16 v59, v145 offset:63752
	ds_read_u16 v60, v145 offset:64016
	s_waitcnt lgkmcnt(7)
	ds_read_u16 v61, v145 offset:64280
	v_lshl_or_b32 v62, v47, 16, v46
	v_lshl_or_b32 v63, v49, 16, v48
	v_lshl_or_b32 v64, v51, 16, v50
	v_lshl_or_b32 v65, v53, 16, v52
	s_nop 1
	v_mfma_f32_16x16x32_bf16 v[34:37], v[62:65], v[26:29], v[34:37]
	ds_read_u16 v46, v145 offset:160
	ds_read_u16 v47, v145 offset:424
	ds_read_u16 v48, v145 offset:688
	ds_read_u16 v49, v145 offset:952
	ds_read_u16 v50, v145 offset:4384
	ds_read_u16 v51, v145 offset:4648
	ds_read_u16 v52, v145 offset:4912
	s_waitcnt lgkmcnt(7)
	ds_read_u16 v53, v145 offset:5176
	v_lshl_or_b32 v42, v55, 16, v54
	v_lshl_or_b32 v43, v57, 16, v56
	v_lshl_or_b32 v44, v59, 16, v58
	v_lshl_or_b32 v45, v61, 16, v60
	s_nop 1
	v_mfma_f32_16x16x32_bf16 v[34:37], v[42:45], v[30:33], v[34:37]
	s_and_saveexec_b64 s[24:25], s[8:9]
	s_cbranch_execz .LBB0_135
	s_nop 5
	v_mov_b32_e32 v43, v36
	v_mov_b32_e32 v36, v35
	v_mov_b32_e32 v42, v34
	v_pk_mul_f32 v[34:35], v[40:41], v[36:37] op_sel_hi:[0,1]
	v_pk_mul_f32 v[42:43], v[40:41], v[42:43] op_sel_hi:[0,1]
	v_and_b32_sdwa v37, v35, v202 dst_sel:DWORD dst_unused:UNUSED_PAD src0_sel:WORD_1 src1_sel:DWORD
	v_and_b32_sdwa v41, v34, v202 dst_sel:DWORD dst_unused:UNUSED_PAD src0_sel:WORD_1 src1_sel:DWORD
	v_and_b32_sdwa v0, v43, v202 dst_sel:DWORD dst_unused:UNUSED_PAD src0_sel:WORD_1 src1_sel:DWORD
	v_and_b32_sdwa v36, v42, v202 dst_sel:DWORD dst_unused:UNUSED_PAD src0_sel:WORD_1 src1_sel:DWORD
	v_add3_u32 v35, v35, v37, s60
	v_add3_u32 v34, v34, v41, s60
	v_add3_u32 v36, v42, v36, s60
	v_add3_u32 v0, v43, v0, s60
	v_and_b32_e32 v35, 0xffff0000, v35
	v_and_b32_e32 v34, 0xffff0000, v34
	v_or_b32_sdwa v35, v35, v0 dst_sel:DWORD dst_unused:UNUSED_PAD src0_sel:DWORD src1_sel:WORD_1
	v_or_b32_sdwa v34, v34, v36 dst_sel:DWORD dst_unused:UNUSED_PAD src0_sel:DWORD src1_sel:WORD_1
	global_store_dwordx2 v[38:39], v[34:35], off offset:128
.LBB0_135:
	s_or_b64 exec, exec, s[24:25]
	ds_read_u16 v54, v145 offset:8608
	ds_read_u16 v55, v145 offset:8872
	ds_read_u16 v56, v145 offset:9136
	ds_read_u16 v57, v145 offset:9400
	ds_read_u16 v58, v145 offset:12832
	ds_read_u16 v59, v145 offset:13096
	ds_read_u16 v60, v145 offset:13360
	s_waitcnt lgkmcnt(7)
	ds_read_u16 v61, v145 offset:13624
	v_lshl_or_b32 v62, v47, 16, v46
	v_lshl_or_b32 v63, v49, 16, v48
	v_lshl_or_b32 v64, v51, 16, v50
	v_lshl_or_b32 v65, v53, 16, v52
	s_nop 1
	v_mfma_f32_16x16x32_bf16 v[34:37], v[62:65], v[2:5], 0
	ds_read_u16 v46, v145 offset:17056
	ds_read_u16 v47, v145 offset:17320
	ds_read_u16 v48, v145 offset:17584
	ds_read_u16 v49, v145 offset:17848
	ds_read_u16 v50, v145 offset:21280
	ds_read_u16 v51, v145 offset:21544
	ds_read_u16 v52, v145 offset:21808
	s_waitcnt lgkmcnt(7)
	ds_read_u16 v53, v145 offset:22072
	v_lshl_or_b32 v42, v55, 16, v54
	v_lshl_or_b32 v43, v57, 16, v56
	v_lshl_or_b32 v44, v59, 16, v58
	v_lshl_or_b32 v45, v61, 16, v60
	s_nop 1
	v_mfma_f32_16x16x32_bf16 v[34:37], v[42:45], v[6:9], v[34:37]
	ds_read_u16 v54, v145 offset:25504
	ds_read_u16 v55, v145 offset:25768
	ds_read_u16 v56, v145 offset:26032
	ds_read_u16 v57, v145 offset:26296
	ds_read_u16 v58, v145 offset:29728
	ds_read_u16 v59, v145 offset:29992
	ds_read_u16 v60, v145 offset:30256
	s_waitcnt lgkmcnt(7)
	ds_read_u16 v61, v145 offset:30520
	v_lshl_or_b32 v62, v47, 16, v46
	v_lshl_or_b32 v63, v49, 16, v48
	v_lshl_or_b32 v64, v51, 16, v50
	v_lshl_or_b32 v65, v53, 16, v52
	s_nop 1
	v_mfma_f32_16x16x32_bf16 v[34:37], v[62:65], v[10:13], v[34:37]
	ds_read_u16 v46, v145 offset:33952
	ds_read_u16 v47, v145 offset:34216
	ds_read_u16 v48, v145 offset:34480
	ds_read_u16 v49, v145 offset:34744
	ds_read_u16 v50, v145 offset:38176
	ds_read_u16 v51, v145 offset:38440
	ds_read_u16 v52, v145 offset:38704
	s_waitcnt lgkmcnt(7)
	ds_read_u16 v53, v145 offset:38968
	v_lshl_or_b32 v42, v55, 16, v54
	v_lshl_or_b32 v43, v57, 16, v56
	v_lshl_or_b32 v44, v59, 16, v58
	v_lshl_or_b32 v45, v61, 16, v60
	s_nop 1
	v_mfma_f32_16x16x32_bf16 v[34:37], v[42:45], v[14:17], v[34:37]
	ds_read_u16 v54, v145 offset:42400
	ds_read_u16 v55, v145 offset:42664
	ds_read_u16 v56, v145 offset:42928
	ds_read_u16 v57, v145 offset:43192
	ds_read_u16 v58, v145 offset:46624
	ds_read_u16 v59, v145 offset:46888
	ds_read_u16 v60, v145 offset:47152
	s_waitcnt lgkmcnt(7)
	ds_read_u16 v61, v145 offset:47416
	v_lshl_or_b32 v62, v47, 16, v46
	v_lshl_or_b32 v63, v49, 16, v48
	v_lshl_or_b32 v64, v51, 16, v50
	v_lshl_or_b32 v65, v53, 16, v52
	s_nop 1
	v_mfma_f32_16x16x32_bf16 v[34:37], v[62:65], v[18:21], v[34:37]
	ds_read_u16 v46, v145 offset:50848
	ds_read_u16 v47, v145 offset:51112
	ds_read_u16 v48, v145 offset:51376
	ds_read_u16 v49, v145 offset:51640
	ds_read_u16 v50, v145 offset:55072
	ds_read_u16 v51, v145 offset:55336
	ds_read_u16 v52, v145 offset:55600
	s_waitcnt lgkmcnt(7)
	ds_read_u16 v53, v145 offset:55864
	v_lshl_or_b32 v42, v55, 16, v54
	v_lshl_or_b32 v43, v57, 16, v56
	v_lshl_or_b32 v44, v59, 16, v58
	v_lshl_or_b32 v45, v61, 16, v60
	s_nop 1
	v_mfma_f32_16x16x32_bf16 v[34:37], v[42:45], v[22:25], v[34:37]
	ds_read_u16 v54, v145 offset:59296
	ds_read_u16 v55, v145 offset:59560
	ds_read_u16 v56, v145 offset:59824
	ds_read_u16 v57, v145 offset:60088
	ds_read_u16 v58, v145 offset:63520
	ds_read_u16 v59, v145 offset:63784
	ds_read_u16 v60, v145 offset:64048
	s_waitcnt lgkmcnt(7)
	ds_read_u16 v61, v145 offset:64312
	v_lshl_or_b32 v62, v47, 16, v46
	v_lshl_or_b32 v63, v49, 16, v48
	v_lshl_or_b32 v64, v51, 16, v50
	v_lshl_or_b32 v65, v53, 16, v52
	s_nop 1
	v_mfma_f32_16x16x32_bf16 v[34:37], v[62:65], v[26:29], v[34:37]
	ds_read_u16 v46, v145 offset:192
	ds_read_u16 v47, v145 offset:456
	ds_read_u16 v48, v145 offset:720
	ds_read_u16 v49, v145 offset:984
	ds_read_u16 v50, v145 offset:4416
	ds_read_u16 v51, v145 offset:4680
	ds_read_u16 v52, v145 offset:4944
	s_waitcnt lgkmcnt(7)
	ds_read_u16 v53, v145 offset:5208
	v_lshl_or_b32 v42, v55, 16, v54
	v_lshl_or_b32 v43, v57, 16, v56
	v_lshl_or_b32 v44, v59, 16, v58
	v_lshl_or_b32 v45, v61, 16, v60
	s_nop 1
	v_mfma_f32_16x16x32_bf16 v[34:37], v[42:45], v[30:33], v[34:37]
	s_and_saveexec_b64 s[24:25], s[8:9]
	s_cbranch_execz .LBB0_137
	s_nop 5
	v_mov_b32_e32 v43, v36
	v_mov_b32_e32 v36, v35
	v_mov_b32_e32 v42, v34
	v_pk_mul_f32 v[34:35], v[40:41], v[36:37] op_sel_hi:[0,1]
	v_pk_mul_f32 v[42:43], v[40:41], v[42:43] op_sel_hi:[0,1]
	v_and_b32_sdwa v37, v35, v202 dst_sel:DWORD dst_unused:UNUSED_PAD src0_sel:WORD_1 src1_sel:DWORD
	v_and_b32_sdwa v41, v34, v202 dst_sel:DWORD dst_unused:UNUSED_PAD src0_sel:WORD_1 src1_sel:DWORD
	v_and_b32_sdwa v0, v43, v202 dst_sel:DWORD dst_unused:UNUSED_PAD src0_sel:WORD_1 src1_sel:DWORD
	v_and_b32_sdwa v36, v42, v202 dst_sel:DWORD dst_unused:UNUSED_PAD src0_sel:WORD_1 src1_sel:DWORD
	v_add3_u32 v35, v35, v37, s60
	v_add3_u32 v34, v34, v41, s60
	v_add3_u32 v36, v42, v36, s60
	v_add3_u32 v0, v43, v0, s60
	v_and_b32_e32 v35, 0xffff0000, v35
	v_and_b32_e32 v34, 0xffff0000, v34
	v_or_b32_sdwa v35, v35, v0 dst_sel:DWORD dst_unused:UNUSED_PAD src0_sel:DWORD src1_sel:WORD_1
	v_or_b32_sdwa v34, v34, v36 dst_sel:DWORD dst_unused:UNUSED_PAD src0_sel:DWORD src1_sel:WORD_1
	global_store_dwordx2 v[38:39], v[34:35], off offset:160
.LBB0_137:
	s_or_b64 exec, exec, s[24:25]
	ds_read_u16 v54, v145 offset:8640
	ds_read_u16 v55, v145 offset:8904
	ds_read_u16 v56, v145 offset:9168
	ds_read_u16 v57, v145 offset:9432
	ds_read_u16 v58, v145 offset:12864
	ds_read_u16 v59, v145 offset:13128
	ds_read_u16 v60, v145 offset:13392
	s_waitcnt lgkmcnt(7)
	ds_read_u16 v61, v145 offset:13656
	v_lshl_or_b32 v62, v47, 16, v46
	v_lshl_or_b32 v63, v49, 16, v48
	v_lshl_or_b32 v64, v51, 16, v50
	v_lshl_or_b32 v65, v53, 16, v52
	s_nop 1
	v_mfma_f32_16x16x32_bf16 v[34:37], v[62:65], v[2:5], 0
	ds_read_u16 v46, v145 offset:17088
	ds_read_u16 v47, v145 offset:17352
	ds_read_u16 v48, v145 offset:17616
	ds_read_u16 v49, v145 offset:17880
	ds_read_u16 v50, v145 offset:21312
	ds_read_u16 v51, v145 offset:21576
	ds_read_u16 v52, v145 offset:21840
	s_waitcnt lgkmcnt(7)
	ds_read_u16 v53, v145 offset:22104
	v_lshl_or_b32 v42, v55, 16, v54
	v_lshl_or_b32 v43, v57, 16, v56
	v_lshl_or_b32 v44, v59, 16, v58
	v_lshl_or_b32 v45, v61, 16, v60
	s_nop 1
	v_mfma_f32_16x16x32_bf16 v[34:37], v[42:45], v[6:9], v[34:37]
	ds_read_u16 v54, v145 offset:25536
	ds_read_u16 v55, v145 offset:25800
	ds_read_u16 v56, v145 offset:26064
	ds_read_u16 v57, v145 offset:26328
	ds_read_u16 v58, v145 offset:29760
	ds_read_u16 v59, v145 offset:30024
	ds_read_u16 v60, v145 offset:30288
	s_waitcnt lgkmcnt(7)
	ds_read_u16 v61, v145 offset:30552
	v_lshl_or_b32 v62, v47, 16, v46
	v_lshl_or_b32 v63, v49, 16, v48
	v_lshl_or_b32 v64, v51, 16, v50
	v_lshl_or_b32 v65, v53, 16, v52
	s_nop 1
	v_mfma_f32_16x16x32_bf16 v[34:37], v[62:65], v[10:13], v[34:37]
	ds_read_u16 v46, v145 offset:33984
	ds_read_u16 v47, v145 offset:34248
	ds_read_u16 v48, v145 offset:34512
	ds_read_u16 v49, v145 offset:34776
	ds_read_u16 v50, v145 offset:38208
	ds_read_u16 v51, v145 offset:38472
	ds_read_u16 v52, v145 offset:38736
	s_waitcnt lgkmcnt(7)
	ds_read_u16 v53, v145 offset:39000
	v_lshl_or_b32 v42, v55, 16, v54
	v_lshl_or_b32 v43, v57, 16, v56
	v_lshl_or_b32 v44, v59, 16, v58
	v_lshl_or_b32 v45, v61, 16, v60
	s_nop 1
	v_mfma_f32_16x16x32_bf16 v[34:37], v[42:45], v[14:17], v[34:37]
	ds_read_u16 v54, v145 offset:42432
	ds_read_u16 v55, v145 offset:42696
	ds_read_u16 v56, v145 offset:42960
	ds_read_u16 v57, v145 offset:43224
	ds_read_u16 v58, v145 offset:46656
	ds_read_u16 v59, v145 offset:46920
	ds_read_u16 v60, v145 offset:47184
	s_waitcnt lgkmcnt(7)
	ds_read_u16 v61, v145 offset:47448
	v_lshl_or_b32 v62, v47, 16, v46
	v_lshl_or_b32 v63, v49, 16, v48
	v_lshl_or_b32 v64, v51, 16, v50
	v_lshl_or_b32 v65, v53, 16, v52
	s_nop 1
	v_mfma_f32_16x16x32_bf16 v[34:37], v[62:65], v[18:21], v[34:37]
	ds_read_u16 v46, v145 offset:50880
	ds_read_u16 v47, v145 offset:51144
	ds_read_u16 v48, v145 offset:51408
	ds_read_u16 v49, v145 offset:51672
	ds_read_u16 v50, v145 offset:55104
	ds_read_u16 v51, v145 offset:55368
	ds_read_u16 v52, v145 offset:55632
	s_waitcnt lgkmcnt(7)
	ds_read_u16 v53, v145 offset:55896
	v_lshl_or_b32 v42, v55, 16, v54
	v_lshl_or_b32 v43, v57, 16, v56
	v_lshl_or_b32 v44, v59, 16, v58
	v_lshl_or_b32 v45, v61, 16, v60
	s_nop 1
	v_mfma_f32_16x16x32_bf16 v[34:37], v[42:45], v[22:25], v[34:37]
	ds_read_u16 v54, v145 offset:59328
	ds_read_u16 v55, v145 offset:59592
	ds_read_u16 v56, v145 offset:59856
	ds_read_u16 v57, v145 offset:60120
	ds_read_u16 v58, v145 offset:63552
	ds_read_u16 v59, v145 offset:63816
	ds_read_u16 v60, v145 offset:64080
	s_waitcnt lgkmcnt(7)
	ds_read_u16 v61, v145 offset:64344
	v_lshl_or_b32 v62, v47, 16, v46
	v_lshl_or_b32 v63, v49, 16, v48
	v_lshl_or_b32 v64, v51, 16, v50
	v_lshl_or_b32 v65, v53, 16, v52
	s_nop 1
	v_mfma_f32_16x16x32_bf16 v[34:37], v[62:65], v[26:29], v[34:37]
	ds_read_u16 v46, v145 offset:224
	ds_read_u16 v47, v145 offset:488
	ds_read_u16 v48, v145 offset:752
	ds_read_u16 v49, v145 offset:1016
	ds_read_u16 v50, v145 offset:4448
	ds_read_u16 v51, v145 offset:4712
	ds_read_u16 v52, v145 offset:4976
	s_waitcnt lgkmcnt(7)
	ds_read_u16 v53, v145 offset:5240
	v_lshl_or_b32 v42, v55, 16, v54
	v_lshl_or_b32 v43, v57, 16, v56
	v_lshl_or_b32 v44, v59, 16, v58
	v_lshl_or_b32 v45, v61, 16, v60
	s_nop 1
	v_mfma_f32_16x16x32_bf16 v[34:37], v[42:45], v[30:33], v[34:37]
	s_and_saveexec_b64 s[24:25], s[8:9]
	s_cbranch_execz .LBB0_139
	s_nop 5
	v_mov_b32_e32 v43, v36
	v_mov_b32_e32 v36, v35
	v_mov_b32_e32 v42, v34
	v_pk_mul_f32 v[34:35], v[40:41], v[36:37] op_sel_hi:[0,1]
	v_pk_mul_f32 v[42:43], v[40:41], v[42:43] op_sel_hi:[0,1]
	v_and_b32_sdwa v37, v35, v202 dst_sel:DWORD dst_unused:UNUSED_PAD src0_sel:WORD_1 src1_sel:DWORD
	v_and_b32_sdwa v41, v34, v202 dst_sel:DWORD dst_unused:UNUSED_PAD src0_sel:WORD_1 src1_sel:DWORD
	v_and_b32_sdwa v0, v43, v202 dst_sel:DWORD dst_unused:UNUSED_PAD src0_sel:WORD_1 src1_sel:DWORD
	v_and_b32_sdwa v36, v42, v202 dst_sel:DWORD dst_unused:UNUSED_PAD src0_sel:WORD_1 src1_sel:DWORD
	v_add3_u32 v35, v35, v37, s60
	v_add3_u32 v34, v34, v41, s60
	v_add3_u32 v36, v42, v36, s60
	v_add3_u32 v0, v43, v0, s60
	v_and_b32_e32 v35, 0xffff0000, v35
	v_and_b32_e32 v34, 0xffff0000, v34
	v_or_b32_sdwa v35, v35, v0 dst_sel:DWORD dst_unused:UNUSED_PAD src0_sel:DWORD src1_sel:WORD_1
	v_or_b32_sdwa v34, v34, v36 dst_sel:DWORD dst_unused:UNUSED_PAD src0_sel:DWORD src1_sel:WORD_1
	global_store_dwordx2 v[38:39], v[34:35], off offset:192
.LBB0_139:
	s_or_b64 exec, exec, s[24:25]
	ds_read_u16 v54, v145 offset:8672
	ds_read_u16 v55, v145 offset:8936
	ds_read_u16 v56, v145 offset:9200
	ds_read_u16 v57, v145 offset:9464
	ds_read_u16 v58, v145 offset:12896
	ds_read_u16 v59, v145 offset:13160
	ds_read_u16 v60, v145 offset:13424
	s_waitcnt lgkmcnt(7)
	ds_read_u16 v61, v145 offset:13688
	v_lshl_or_b32 v62, v47, 16, v46
	v_lshl_or_b32 v63, v49, 16, v48
	v_lshl_or_b32 v64, v51, 16, v50
	v_lshl_or_b32 v65, v53, 16, v52
	s_nop 1
	v_mfma_f32_16x16x32_bf16 v[2:5], v[62:65], v[2:5], 0
	ds_read_u16 v46, v145 offset:17120
	ds_read_u16 v47, v145 offset:17384
	ds_read_u16 v48, v145 offset:17648
	ds_read_u16 v49, v145 offset:17912
	ds_read_u16 v50, v145 offset:21344
	ds_read_u16 v51, v145 offset:21608
	ds_read_u16 v52, v145 offset:21872
	s_waitcnt lgkmcnt(7)
	ds_read_u16 v53, v145 offset:22136
	v_lshl_or_b32 v42, v55, 16, v54
	v_lshl_or_b32 v43, v57, 16, v56
	v_lshl_or_b32 v44, v59, 16, v58
	v_lshl_or_b32 v45, v61, 16, v60
	s_nop 1
	v_mfma_f32_16x16x32_bf16 v[2:5], v[42:45], v[6:9], v[2:5]
	ds_read_u16 v54, v145 offset:25568
	ds_read_u16 v55, v145 offset:25832
	ds_read_u16 v56, v145 offset:26096
	ds_read_u16 v57, v145 offset:26360
	ds_read_u16 v58, v145 offset:29792
	ds_read_u16 v59, v145 offset:30056
	ds_read_u16 v60, v145 offset:30320
	s_waitcnt lgkmcnt(7)
	ds_read_u16 v61, v145 offset:30584
	v_lshl_or_b32 v62, v47, 16, v46
	v_lshl_or_b32 v63, v49, 16, v48
	v_lshl_or_b32 v64, v51, 16, v50
	v_lshl_or_b32 v65, v53, 16, v52
	s_nop 1
	v_mfma_f32_16x16x32_bf16 v[2:5], v[62:65], v[10:13], v[2:5]
	ds_read_u16 v46, v145 offset:34016
	ds_read_u16 v47, v145 offset:34280
	ds_read_u16 v48, v145 offset:34544
	ds_read_u16 v49, v145 offset:34808
	ds_read_u16 v50, v145 offset:38240
	ds_read_u16 v51, v145 offset:38504
	ds_read_u16 v52, v145 offset:38768
	s_waitcnt lgkmcnt(7)
	ds_read_u16 v53, v145 offset:39032
	v_lshl_or_b32 v42, v55, 16, v54
	v_lshl_or_b32 v43, v57, 16, v56
	v_lshl_or_b32 v44, v59, 16, v58
	v_lshl_or_b32 v45, v61, 16, v60
	s_nop 1
	v_mfma_f32_16x16x32_bf16 v[2:5], v[42:45], v[14:17], v[2:5]
	ds_read_u16 v54, v145 offset:42464
	ds_read_u16 v55, v145 offset:42728
	ds_read_u16 v56, v145 offset:42992
	ds_read_u16 v57, v145 offset:43256
	ds_read_u16 v58, v145 offset:46688
	ds_read_u16 v59, v145 offset:46952
	ds_read_u16 v60, v145 offset:47216
	s_waitcnt lgkmcnt(7)
	ds_read_u16 v61, v145 offset:47480
	v_lshl_or_b32 v62, v47, 16, v46
	v_lshl_or_b32 v63, v49, 16, v48
	v_lshl_or_b32 v64, v51, 16, v50
	v_lshl_or_b32 v65, v53, 16, v52
	s_nop 1
	v_mfma_f32_16x16x32_bf16 v[2:5], v[62:65], v[18:21], v[2:5]
	ds_read_u16 v46, v145 offset:50912
	ds_read_u16 v47, v145 offset:51176
	ds_read_u16 v48, v145 offset:51440
	ds_read_u16 v49, v145 offset:51704
	ds_read_u16 v50, v145 offset:55136
	ds_read_u16 v51, v145 offset:55400
	ds_read_u16 v52, v145 offset:55664
	s_waitcnt lgkmcnt(7)
	ds_read_u16 v53, v145 offset:55928
	v_lshl_or_b32 v42, v55, 16, v54
	v_lshl_or_b32 v43, v57, 16, v56
	v_lshl_or_b32 v44, v59, 16, v58
	v_lshl_or_b32 v45, v61, 16, v60
	s_nop 1
	v_mfma_f32_16x16x32_bf16 v[2:5], v[42:45], v[22:25], v[2:5]
	ds_read_u16 v54, v145 offset:59360
	ds_read_u16 v55, v145 offset:59624
	ds_read_u16 v56, v145 offset:59888
	ds_read_u16 v57, v145 offset:60152
	ds_read_u16 v58, v145 offset:63584
	ds_read_u16 v59, v145 offset:63848
	ds_read_u16 v60, v145 offset:64112
	s_waitcnt lgkmcnt(7)
	ds_read_u16 v61, v145 offset:64376
	v_lshl_or_b32 v62, v47, 16, v46
	v_lshl_or_b32 v63, v49, 16, v48
	v_lshl_or_b32 v64, v51, 16, v50
	v_lshl_or_b32 v65, v53, 16, v52
	s_nop 1
	v_mfma_f32_16x16x32_bf16 v[2:5], v[62:65], v[26:29], v[2:5]
	s_waitcnt lgkmcnt(0)
	v_lshl_or_b32 v42, v55, 16, v54
	v_lshl_or_b32 v43, v57, 16, v56
	v_lshl_or_b32 v44, v59, 16, v58
	v_lshl_or_b32 v45, v61, 16, v60
	s_nop 1
	v_mfma_f32_16x16x32_bf16 v[2:5], v[42:45], v[30:33], v[2:5]
	s_and_saveexec_b64 s[24:25], s[8:9]
	s_cbranch_execz .LBB0_86
	s_nop 5
	v_mov_b32_e32 v6, v2
	v_mov_b32_e32 v7, v4
	v_pk_mul_f32 v[6:7], v[40:41], v[6:7] op_sel_hi:[0,1]
	v_mov_b32_e32 v4, v3
	v_pk_mul_f32 v[2:3], v[40:41], v[4:5] op_sel_hi:[0,1]
	v_and_b32_sdwa v4, v6, v202 dst_sel:DWORD dst_unused:UNUSED_PAD src0_sel:WORD_1 src1_sel:DWORD
	v_add3_u32 v4, v6, v4, s60
	v_and_b32_sdwa v5, v3, v202 dst_sel:DWORD dst_unused:UNUSED_PAD src0_sel:WORD_1 src1_sel:DWORD
	v_and_b32_sdwa v6, v2, v202 dst_sel:DWORD dst_unused:UNUSED_PAD src0_sel:WORD_1 src1_sel:DWORD
	v_and_b32_sdwa v0, v7, v202 dst_sel:DWORD dst_unused:UNUSED_PAD src0_sel:WORD_1 src1_sel:DWORD
	v_add3_u32 v3, v3, v5, s60
	v_add3_u32 v2, v2, v6, s60
	v_add3_u32 v0, v7, v0, s60
	v_and_b32_e32 v3, 0xffff0000, v3
	v_and_b32_e32 v2, 0xffff0000, v2
	v_or_b32_sdwa v3, v3, v0 dst_sel:DWORD dst_unused:UNUSED_PAD src0_sel:DWORD src1_sel:WORD_1
	v_or_b32_sdwa v2, v2, v4 dst_sel:DWORD dst_unused:UNUSED_PAD src0_sel:DWORD src1_sel:WORD_1
	global_store_dwordx2 v[38:39], v[2:3], off offset:224
	s_branch .LBB0_86

.LBB0_1881:
	s_ashr_i32 s40, s19, 2
	s_cmpk_gt_i32 s40, 0x1fff
	s_cselect_b32 s51, 3, 0x7ff
	s_cselect_b32 s52, 1, 0
	s_and_b32 s51, s40, s51
	s_add_i32 s6, s40, -3
	v_readlane_b32 s48, v251, 16
	v_readlane_b32 s49, v251, 17
	s_mul_hi_i32 s7, s6, 0x3c00
	s_mulk_i32 s6, 0x3c00
	s_add_u32 s6, s48, s6
	s_addc_u32 s7, s49, s7
	s_add_u32 s6, s6, 0x1a00
	s_addc_u32 s7, s7, 0
	s_add_i32 s53, s40, 0xffffe000
	s_lshr_b32 s53, s53, 2
	s_mul_i32 s54, s53, 0x9000
	s_mul_hi_u32 s55, s53, 0x9000
	s_add_u32 s54, s0, s54
	s_addc_u32 s55, s1, s55
	s_add_i32 s26, s51, 0
	s_cmp_lt_u32 s26, 3
	s_cbranch_scc1 .Lgdp_t0_early
	global_load_dwordx2 v[2:3], v89, s[6:7]
	global_load_dwordx2 v[4:5], v90, s[6:7]
	global_load_dwordx2 v[6:7], v91, s[6:7]
	s_branch .Lgdp_t0_done
.Lgdp_t0_early:
	s_cmp_eq_u32 s52, 0
	s_cbranch_scc1 .Lgdp_t0_done
	s_mul_i32 s27, s26, 0x3000
	s_add_u32 s38, s54, s27
	s_addc_u32 s39, s55, 0
	global_load_dwordx4 v[92:95], v86, s[38:39]
	global_load_dwordx4 v[96:99], v87, s[38:39]
	global_load_dwordx4 v[100:103], v88, s[38:39]
.Lgdp_t0_done:
	s_add_u32 s6, s6, 0x3c00
	s_addc_u32 s7, s7, 0
	s_add_i32 s26, s51, 1
	s_cmp_lt_u32 s26, 3
	s_cbranch_scc1 .Lgdp_t1_early
	global_load_dwordx2 v[8:9], v89, s[6:7]
	global_load_dwordx2 v[10:11], v90, s[6:7]
	global_load_dwordx2 v[12:13], v91, s[6:7]
	s_branch .Lgdp_t1_done
.Lgdp_t1_early:
	s_cmp_eq_u32 s52, 0
	s_cbranch_scc1 .Lgdp_t1_done
	s_mul_i32 s27, s26, 0x3000
	s_add_u32 s38, s54, s27
	s_addc_u32 s39, s55, 0
	global_load_dwordx4 v[104:107], v86, s[38:39]
	global_load_dwordx4 v[108:111], v87, s[38:39]
	global_load_dwordx4 v[112:115], v88, s[38:39]
.Lgdp_t1_done:
	s_add_u32 s6, s6, 0x3c00
	s_addc_u32 s7, s7, 0
	s_add_i32 s26, s51, 2
	s_cmp_lt_u32 s26, 3
	s_cbranch_scc1 .Lgdp_t2_early
	global_load_dwordx2 v[14:15], v89, s[6:7]
	global_load_dwordx2 v[16:17], v90, s[6:7]
	global_load_dwordx2 v[18:19], v91, s[6:7]
	s_branch .Lgdp_t2_done
.Lgdp_t2_early:
	s_cmp_eq_u32 s52, 0
	s_cbranch_scc1 .Lgdp_t2_done
	s_mul_i32 s27, s26, 0x3000
	s_add_u32 s38, s54, s27
	s_addc_u32 s39, s55, 0
	global_load_dwordx4 v[116:119], v86, s[38:39]
	global_load_dwordx4 v[120:123], v87, s[38:39]
	global_load_dwordx4 v[124:127], v88, s[38:39]
.Lgdp_t2_done:
	s_add_u32 s6, s6, 0x3c00
	s_addc_u32 s7, s7, 0
	s_add_i32 s26, s51, 3
	s_cmp_lt_u32 s26, 3
	s_cbranch_scc1 .Lgdp_t3_early
	global_load_dwordx2 v[20:21], v89, s[6:7]
	global_load_dwordx2 v[22:23], v90, s[6:7]
	global_load_dwordx2 v[24:25], v91, s[6:7]
	s_branch .Lgdp_t3_done
.Lgdp_t3_early:
	s_cmp_eq_u32 s52, 0
	s_cbranch_scc1 .Lgdp_t3_done
	s_mul_i32 s27, s26, 0x3000
	s_add_u32 s38, s54, s27
	s_addc_u32 s39, s55, 0
	global_load_dwordx4 v[128:131], v86, s[38:39]
	global_load_dwordx4 v[132:135], v87, s[38:39]
	global_load_dwordx4 v[194:197], v88, s[38:39]
.Lgdp_t3_done:
	global_load_ushort v26, v190, s[6:7]
	global_load_ushort v27, v190, s[6:7] offset:16
	s_lshl_b32 s44, s40, 12
	v_add_u32_e32 v56, s44, v86
	s_waitcnt vmcnt(0)
	s_add_i32 s26, s51, 0
	s_cmp_lt_u32 s26, 3
	s_cbranch_scc1 .Lgdp_c0_early
	v_lshlrev_b32_e32 v92, 16, v2
	v_and_b32_e32 v93, v191, v2
	v_lshlrev_b32_e32 v94, 16, v3
	v_and_b32_e32 v95, v191, v3
	v_lshlrev_b32_e32 v96, 16, v4
	v_and_b32_e32 v97, v191, v4
	v_lshlrev_b32_e32 v98, 16, v5
	v_and_b32_e32 v99, v191, v5
	v_lshlrev_b32_e32 v100, 16, v6
	v_and_b32_e32 v101, v191, v6
	v_lshlrev_b32_e32 v102, 16, v7
	v_and_b32_e32 v103, v191, v7
	s_branch .Lgdp_c0_done
.Lgdp_c0_early:
	s_cmp_eq_u32 s52, 0
	s_cbranch_scc0 .Lgdp_c0_done
	v_mov_b32_e32 v92, 0
	v_mov_b32_e32 v93, 0
	v_mov_b32_e32 v94, 0
	v_mov_b32_e32 v95, 0
	v_mov_b32_e32 v96, 0
	v_mov_b32_e32 v97, 0
	v_mov_b32_e32 v98, 0
	v_mov_b32_e32 v99, 0
	v_mov_b32_e32 v100, 0
	v_mov_b32_e32 v101, 0
	v_mov_b32_e32 v102, 0
	v_mov_b32_e32 v103, 0
.Lgdp_c0_done:
	s_add_i32 s26, s51, 1
	s_cmp_lt_u32 s26, 3
	s_cbranch_scc1 .Lgdp_c1_early
	v_lshlrev_b32_e32 v104, 16, v8
	v_and_b32_e32 v105, v191, v8
	v_lshlrev_b32_e32 v106, 16, v9
	v_and_b32_e32 v107, v191, v9
	v_lshlrev_b32_e32 v108, 16, v10
	v_and_b32_e32 v109, v191, v10
	v_lshlrev_b32_e32 v110, 16, v11
	v_and_b32_e32 v111, v191, v11
	v_lshlrev_b32_e32 v112, 16, v12
	v_and_b32_e32 v113, v191, v12
	v_lshlrev_b32_e32 v114, 16, v13
	v_and_b32_e32 v115, v191, v13
	s_branch .Lgdp_c1_done
.Lgdp_c1_early:
	s_cmp_eq_u32 s52, 0
	s_cbranch_scc0 .Lgdp_c1_done
	v_mov_b32_e32 v104, 0
	v_mov_b32_e32 v105, 0
	v_mov_b32_e32 v106, 0
	v_mov_b32_e32 v107, 0
	v_mov_b32_e32 v108, 0
	v_mov_b32_e32 v109, 0
	v_mov_b32_e32 v110, 0
	v_mov_b32_e32 v111, 0
	v_mov_b32_e32 v112, 0
	v_mov_b32_e32 v113, 0
	v_mov_b32_e32 v114, 0
	v_mov_b32_e32 v115, 0
.Lgdp_c1_done:
	s_add_i32 s26, s51, 2
	s_cmp_lt_u32 s26, 3
	s_cbranch_scc1 .Lgdp_c2_early
	v_lshlrev_b32_e32 v116, 16, v14
	v_and_b32_e32 v117, v191, v14
	v_lshlrev_b32_e32 v118, 16, v15
	v_and_b32_e32 v119, v191, v15
	v_lshlrev_b32_e32 v120, 16, v16
	v_and_b32_e32 v121, v191, v16
	v_lshlrev_b32_e32 v122, 16, v17
	v_and_b32_e32 v123, v191, v17
	v_lshlrev_b32_e32 v124, 16, v18
	v_and_b32_e32 v125, v191, v18
	v_lshlrev_b32_e32 v126, 16, v19
	v_and_b32_e32 v127, v191, v19
	s_branch .Lgdp_c2_done
.Lgdp_c2_early:
	s_cmp_eq_u32 s52, 0
	s_cbranch_scc0 .Lgdp_c2_done
	v_mov_b32_e32 v116, 0
	v_mov_b32_e32 v117, 0
	v_mov_b32_e32 v118, 0
	v_mov_b32_e32 v119, 0
	v_mov_b32_e32 v120, 0
	v_mov_b32_e32 v121, 0
	v_mov_b32_e32 v122, 0
	v_mov_b32_e32 v123, 0
	v_mov_b32_e32 v124, 0
	v_mov_b32_e32 v125, 0
	v_mov_b32_e32 v126, 0
	v_mov_b32_e32 v127, 0
.Lgdp_c2_done:
	s_add_i32 s26, s51, 3
	s_cmp_lt_u32 s26, 3
	s_cbranch_scc1 .Lgdp_c3_early
	v_lshlrev_b32_e32 v128, 16, v20
	v_and_b32_e32 v129, v191, v20
	v_lshlrev_b32_e32 v130, 16, v21
	v_and_b32_e32 v131, v191, v21
	v_lshlrev_b32_e32 v132, 16, v22
	v_and_b32_e32 v133, v191, v22
	v_lshlrev_b32_e32 v134, 16, v23
	v_and_b32_e32 v135, v191, v23
	v_lshlrev_b32_e32 v194, 16, v24
	v_and_b32_e32 v195, v191, v24
	v_lshlrev_b32_e32 v196, 16, v25
	v_and_b32_e32 v197, v191, v25
	s_branch .Lgdp_c3_done
.Lgdp_c3_early:
	s_cmp_eq_u32 s52, 0
	s_cbranch_scc0 .Lgdp_c3_done
	v_mov_b32_e32 v128, 0
	v_mov_b32_e32 v129, 0
	v_mov_b32_e32 v130, 0
	v_mov_b32_e32 v131, 0
	v_mov_b32_e32 v132, 0
	v_mov_b32_e32 v133, 0
	v_mov_b32_e32 v134, 0
	v_mov_b32_e32 v135, 0
	v_mov_b32_e32 v194, 0
	v_mov_b32_e32 v195, 0
	v_mov_b32_e32 v196, 0
	v_mov_b32_e32 v197, 0
.Lgdp_c3_done:
	v_mul_f32_e32 v28, v92, v140
	v_mul_f32_e32 v29, v93, v141
	v_mul_f32_e32 v30, v94, v142
	v_mul_f32_e32 v31, v95, v143
	v_fmac_f32_e32 v28, v104, v152
	v_fmac_f32_e32 v29, v105, v153
	v_fmac_f32_e32 v30, v106, v154
	v_fmac_f32_e32 v31, v107, v155
	v_fmac_f32_e32 v28, v116, v164
	v_fmac_f32_e32 v29, v117, v165
	v_fmac_f32_e32 v30, v118, v166
	v_fmac_f32_e32 v31, v119, v167
	v_fmac_f32_e32 v28, v128, v176
	v_fmac_f32_e32 v29, v129, v177
	v_fmac_f32_e32 v30, v130, v178
	v_fmac_f32_e32 v31, v131, v179
	v_mul_f32_e32 v32, v96, v144
	v_mul_f32_e32 v33, v97, v145
	v_mul_f32_e32 v34, v98, v146
	v_mul_f32_e32 v35, v99, v147
	v_fmac_f32_e32 v32, v108, v156
	v_fmac_f32_e32 v33, v109, v157
	v_fmac_f32_e32 v34, v110, v158
	v_fmac_f32_e32 v35, v111, v159
	v_fmac_f32_e32 v32, v120, v168
	v_fmac_f32_e32 v33, v121, v169
	v_fmac_f32_e32 v34, v122, v170
	v_fmac_f32_e32 v35, v123, v171
	v_fmac_f32_e32 v32, v132, v180
	v_fmac_f32_e32 v33, v133, v181
	v_fmac_f32_e32 v34, v134, v182
	v_fmac_f32_e32 v35, v135, v183
	v_mul_f32_e32 v36, v100, v148
	v_mul_f32_e32 v37, v101, v149
	v_mul_f32_e32 v38, v102, v150
	v_mul_f32_e32 v39, v103, v151
	v_fmac_f32_e32 v36, v112, v160
	v_fmac_f32_e32 v37, v113, v161
	v_fmac_f32_e32 v38, v114, v162
	v_fmac_f32_e32 v39, v115, v163
	v_fmac_f32_e32 v36, v124, v172
	v_fmac_f32_e32 v37, v125, v173
	v_fmac_f32_e32 v38, v126, v174
	v_fmac_f32_e32 v39, v127, v175
	v_fmac_f32_e32 v36, v194, v184
	v_fmac_f32_e32 v37, v195, v185
	v_fmac_f32_e32 v38, v196, v186
	v_fmac_f32_e32 v39, v197, v187
	v_mul_f32_e32 v44, s81, v28
	v_mul_f32_e32 v45, s81, v29
	v_mul_f32_e32 v46, s81, v30
	v_mul_f32_e32 v47, s81, v31
	v_mul_f32_e32 v48, s81, v32
	v_mul_f32_e32 v49, s81, v33
	v_mul_f32_e32 v50, s81, v34
	v_mul_f32_e32 v51, s81, v35
	v_mul_f32_e32 v52, s81, v36
	v_mul_f32_e32 v53, s81, v37
	v_mul_f32_e32 v54, s81, v38
	v_mul_f32_e32 v55, s81, v39
	v_exp_f32_e32 v44, v44
	v_exp_f32_e32 v45, v45
	v_exp_f32_e32 v46, v46
	v_exp_f32_e32 v47, v47
	v_exp_f32_e32 v48, v48
	v_exp_f32_e32 v49, v49
	v_exp_f32_e32 v50, v50
	v_exp_f32_e32 v51, v51
	v_exp_f32_e32 v52, v52
	v_exp_f32_e32 v53, v53
	v_exp_f32_e32 v54, v54
	v_exp_f32_e32 v55, v55
	v_add_f32_e32 v44, 1.0, v44
	v_add_f32_e32 v45, 1.0, v45
	v_add_f32_e32 v46, 1.0, v46
	v_add_f32_e32 v47, 1.0, v47
	v_add_f32_e32 v48, 1.0, v48
	v_add_f32_e32 v49, 1.0, v49
	v_add_f32_e32 v50, 1.0, v50
	v_add_f32_e32 v51, 1.0, v51
	v_add_f32_e32 v52, 1.0, v52
	v_add_f32_e32 v53, 1.0, v53
	v_add_f32_e32 v54, 1.0, v54
	v_add_f32_e32 v55, 1.0, v55
	v_rcp_f32_e32 v44, v44
	v_rcp_f32_e32 v45, v45
	v_rcp_f32_e32 v46, v46
	v_rcp_f32_e32 v47, v47
	v_rcp_f32_e32 v48, v48
	v_rcp_f32_e32 v49, v49
	v_rcp_f32_e32 v50, v50
	v_rcp_f32_e32 v51, v51
	v_rcp_f32_e32 v52, v52
	v_rcp_f32_e32 v53, v53
	v_rcp_f32_e32 v54, v54
	v_rcp_f32_e32 v55, v55
	v_mul_f32_e32 v28, v28, v44
	v_mul_f32_e32 v29, v29, v45
	v_mul_f32_e32 v30, v30, v46
	v_mul_f32_e32 v31, v31, v47
	v_mul_f32_e32 v32, v32, v48
	v_mul_f32_e32 v33, v33, v49
	v_mul_f32_e32 v34, v34, v50
	v_mul_f32_e32 v35, v35, v51
	v_mul_f32_e32 v36, v36, v52
	v_mul_f32_e32 v37, v37, v53
	v_mul_f32_e32 v38, v38, v54
	v_mul_f32_e32 v39, v39, v55
	v_mul_f32_e32 v44, v28, v28
	v_mul_f32_e32 v45, v32, v32
	v_mul_f32_e32 v46, v29, v29
	v_mul_f32_e32 v47, v33, v33
	v_fmac_f32_e32 v44, v30, v30
	v_fmac_f32_e32 v45, v34, v34
	v_fmac_f32_e32 v46, v31, v31
	v_fmac_f32_e32 v47, v35, v35
	v_add_f32_e32 v44, v44, v46
	v_add_f32_e32 v45, v45, v47
	s_nop 0
	v_add_f32_dpp v44, v44, v44 quad_perm:[1,0,3,2] row_mask:0xf bank_mask:0xf bound_ctrl:1
	v_add_f32_dpp v45, v45, v45 quad_perm:[1,0,3,2] row_mask:0xf bank_mask:0xf bound_ctrl:1
	s_nop 0
	v_add_f32_dpp v44, v44, v44 quad_perm:[2,3,0,1] row_mask:0xf bank_mask:0xf bound_ctrl:1
	v_add_f32_dpp v45, v45, v45 quad_perm:[2,3,0,1] row_mask:0xf bank_mask:0xf bound_ctrl:1
	s_nop 0
	v_add_f32_dpp v44, v44, v44 row_half_mirror row_mask:0xf bank_mask:0xf bound_ctrl:1
	v_add_f32_dpp v45, v45, v45 row_half_mirror row_mask:0xf bank_mask:0xf bound_ctrl:1
	s_nop 0
	v_add_f32_dpp v44, v44, v44 row_ror:8 row_mask:0xf bank_mask:0xf bound_ctrl:1
	v_add_f32_dpp v45, v45, v45 row_ror:8 row_mask:0xf bank_mask:0xf bound_ctrl:1
	s_nop 0
	ds_bpermute_b32 v46, v73, v44
	ds_bpermute_b32 v47, v73, v45
	s_add_u32 s26, s4, s44
	s_addc_u32 s27, s5, 0
	s_waitcnt lgkmcnt(0)
	v_add_f32_e32 v44, v44, v46
	v_add_f32_e32 v45, v45, v47
	v_add_f32_e32 v44, 0x2b8cbccc, v44
	v_add_f32_e32 v45, 0x2b8cbccc, v45
	v_rsq_f32_e32 v44, v44
	v_rsq_f32_e32 v45, v45
	s_nop 0
	v_mul_f32_e32 v44, 0x3db504f3, v44
	v_mul_f32_e32 v28, v28, v44
	v_mul_f32_e32 v29, v29, v44
	v_mul_f32_e32 v30, v30, v44
	v_mul_f32_e32 v31, v31, v44
	v_mul_f32_e32 v32, v32, v45
	v_mul_f32_e32 v33, v33, v45
	v_mul_f32_e32 v34, v34, v45
	v_mul_f32_e32 v35, v35, v45
	global_store_dwordx4 v56, v[28:31], s[22:23]
	global_store_dwordx4 v56, v[32:35], s[24:25]
	global_store_dwordx4 v56, v[36:39], s[28:29]
	s_and_saveexec_b64 s[38:39], s[2:3]
	v_lshlrev_b32_e32 v44, 16, v26
	v_lshlrev_b32_e32 v45, 16, v27
	v_mul_f32_e32 v44, s81, v44
	v_add_f32_e32 v45, v189, v45
	v_exp_f32_e32 v44, v44
	v_mul_f32_e64 v46, |v45|, s81
	v_exp_f32_e32 v46, v46
	v_add_f32_e32 v44, 1.0, v44
	v_rcp_f32_e32 v44, v44
	v_max_f32_e32 v45, 0, v45
	v_add_f32_e32 v46, 1.0, v46
	global_store_dword v192, v44, s[26:27]
	v_cmp_gt_f32_e32 vcc, s82, v46
	s_nop 1
	v_cndmask_b32_e64 v47, 0, 32, vcc
	v_ldexp_f32 v46, v46, v47
	v_log_f32_e32 v46, v46
	s_nop 0
	v_mul_f32_e32 v47, 0x3f317217, v46
	v_fma_f32 v47, v46, s83, -v47
	v_fmac_f32_e32 v47, 0x3377d1cf, v46
	v_fmac_f32_e32 v47, 0x3f317217, v46
	v_cmp_lt_f32_e64 s[6:7], |v46|, s84
	s_nop 1
	v_cndmask_b32_e64 v46, v46, v47, s[6:7]
	v_cndmask_b32_e32 v47, 0, v218, vcc
	v_sub_f32_e32 v46, v46, v47
	v_add_f32_e32 v45, v45, v46
	v_mul_f32_e32 v45, v45, v188
	v_mul_f32_e32 v45, s81, v45
	v_exp_f32_e32 v45, v45
	s_nop 0
	global_store_dword v192, v45, s[26:27] offset:4
	s_or_b64 exec, exec, s[38:39]
	s_add_i32 s19, s19, s50
	s_add_i32 s18, s18, s80
	s_cmp_gt_i32 s19, 0x87ff
	s_cbranch_scc0 .LBB0_1881
	s_branch .LBB0_1931
